# all phase-output global stores made write-through (sc1) so the grid-barrier release fence has little to write back
# baseline (speedup 1.0000x reference)
.LBB0_23:
	s_mul_hi_i32 s0, s42, 0x66666667
	s_lshr_b32 s1, s0, 31
	s_ashr_i32 s0, s0, 10
	s_add_i32 s0, s0, s1
	s_mul_i32 s1, s0, 0xfffff600
	s_add_i32 s43, s42, s1
	s_ashr_i32 s1, s0, 31
	s_cmpk_gt_i32 s43, 0x7ff
	s_mov_b64 s[4:5], -1
	s_cbranch_scc0 .LBB0_25
	s_lshl_b64 s[4:5], s[0:1], 22
	s_waitcnt lgkmcnt(0)
	s_add_u32 s2, s66, s4
	s_addc_u32 s47, s67, s5
	s_lshl_b64 s[4:5], s[0:1], 21
	v_readlane_b32 s44, v252, 18
	s_add_u32 s44, s44, s4
	v_readlane_b32 s4, v252, 19
	s_addc_u32 s5, s4, s5
	s_mul_i32 s4, s0, 0xffffec00
	s_add_i32 s4, s7, s4
	s_and_b32 s45, s4, 0x1ffc0
	s_and_b32 s4, s3, 0x3e0
	s_lshl_b32 s46, s4, 2
	s_add_u32 s46, s2, s46
	v_or_b32_e32 v3, s45, v4
	s_addc_u32 s47, s47, 0
	v_lshl_add_u64 v[18:19], s[46:47], 0, v[0:1]
	v_lshlrev_b32_e32 v20, 12, v3
	v_mov_b32_e32 v21, v1
	v_lshl_add_u64 v[18:19], v[18:19], 0, v[20:21]
	s_movk_i32 s2, 0x2000
	v_add_co_u32_e32 v20, vcc, s2, v18
	s_movk_i32 s2, 0x4000
	s_nop 0
	v_addc_co_u32_e32 v21, vcc, 0, v19, vcc
	v_add_co_u32_e32 v22, vcc, s2, v18
	s_movk_i32 s2, 0x6000
	s_nop 0
	v_addc_co_u32_e32 v23, vcc, 0, v19, vcc
	v_add_co_u32_e32 v24, vcc, s2, v18
	s_mov_b32 s2, 0x8000
	s_nop 0
	v_addc_co_u32_e32 v25, vcc, 0, v19, vcc
	v_add_co_u32_e32 v26, vcc, s2, v18
	s_mov_b32 s2, 0xa000
	s_nop 0
	v_addc_co_u32_e32 v27, vcc, 0, v19, vcc
	v_add_co_u32_e32 v32, vcc, s2, v18
	s_mov_b32 s2, 0xc000
	s_nop 0
	v_addc_co_u32_e32 v33, vcc, 0, v19, vcc
	v_add_co_u32_e32 v34, vcc, s2, v18
	s_lshl_b32 s2, s45, 1
	s_nop 0
	v_addc_co_u32_e32 v35, vcc, 0, v19, vcc
	v_add_co_u32_e32 v36, vcc, s11, v18
	s_add_u32 s44, s44, s2
	s_nop 0
	v_addc_co_u32_e32 v37, vcc, 0, v19, vcc
	global_load_dword v3, v[18:19], off
	global_load_dword v29, v[20:21], off
	global_load_dword v31, v[22:23], off
	global_load_dword v40, v[24:25], off
	global_load_dword v41, v[26:27], off
	global_load_dword v42, v[32:33], off
	global_load_dword v43, v[34:35], off
	global_load_dword v44, v[36:37], off
	v_add_co_u32_e32 v20, vcc, s12, v18
	s_addc_u32 s45, s5, 0
	s_nop 0
	v_addc_co_u32_e32 v21, vcc, 0, v19, vcc
	v_add_co_u32_e32 v22, vcc, s13, v18
	s_nop 1
	v_addc_co_u32_e32 v23, vcc, 0, v19, vcc
	v_add_co_u32_e32 v24, vcc, s14, v18
	s_nop 1
	v_addc_co_u32_e32 v25, vcc, 0, v19, vcc
	v_add_co_u32_e32 v26, vcc, s15, v18
	s_nop 1
	v_addc_co_u32_e32 v27, vcc, 0, v19, vcc
	v_add_co_u32_e32 v32, vcc, s16, v18
	s_nop 1
	v_addc_co_u32_e32 v33, vcc, 0, v19, vcc
	v_add_co_u32_e32 v34, vcc, s17, v18
	s_nop 1
	v_addc_co_u32_e32 v35, vcc, 0, v19, vcc
	v_add_co_u32_e32 v36, vcc, s19, v18
	s_nop 1
	v_addc_co_u32_e32 v37, vcc, 0, v19, vcc
	v_add_co_u32_e32 v38, vcc, s20, v18
	s_nop 1
	v_addc_co_u32_e32 v39, vcc, 0, v19, vcc
	global_load_dword v45, v[20:21], off
	global_load_dword v46, v[22:23], off
	global_load_dword v47, v[24:25], off
	global_load_dword v48, v[26:27], off
	global_load_dword v49, v[32:33], off
	global_load_dword v50, v[34:35], off
	global_load_dword v51, v[36:37], off
	global_load_dword v52, v[38:39], off
	v_add_co_u32_e32 v20, vcc, s21, v18
	s_nop 1
	v_addc_co_u32_e32 v21, vcc, 0, v19, vcc
	v_add_co_u32_e32 v22, vcc, s22, v18
	s_nop 1
	v_addc_co_u32_e32 v23, vcc, 0, v19, vcc
	v_add_co_u32_e32 v24, vcc, s23, v18
	s_nop 1
	v_addc_co_u32_e32 v25, vcc, 0, v19, vcc
	v_add_co_u32_e32 v26, vcc, s24, v18
	s_nop 1
	v_addc_co_u32_e32 v27, vcc, 0, v19, vcc
	v_add_co_u32_e32 v32, vcc, s25, v18
	s_nop 1
	v_addc_co_u32_e32 v33, vcc, 0, v19, vcc
	v_add_co_u32_e32 v34, vcc, s26, v18
	s_nop 1
	v_addc_co_u32_e32 v35, vcc, 0, v19, vcc
	v_add_co_u32_e32 v36, vcc, s27, v18
	s_nop 1
	v_addc_co_u32_e32 v37, vcc, 0, v19, vcc
	v_add_co_u32_e32 v38, vcc, s28, v18
	s_nop 1
	v_addc_co_u32_e32 v39, vcc, 0, v19, vcc
	global_load_dword v53, v[20:21], off
	global_load_dword v54, v[22:23], off
	global_load_dword v55, v[24:25], off
	global_load_dword v56, v[26:27], off
	global_load_dword v57, v[32:33], off
	global_load_dword v58, v[34:35], off
	global_load_dword v59, v[36:37], off
	s_nop 0
	global_load_dword v38, v[38:39], off
	v_add_co_u32_e32 v20, vcc, s29, v18
	s_nop 1
	v_addc_co_u32_e32 v21, vcc, 0, v19, vcc
	v_add_co_u32_e32 v22, vcc, s30, v18
	s_nop 1
	v_addc_co_u32_e32 v23, vcc, 0, v19, vcc
	v_add_co_u32_e32 v24, vcc, s31, v18
	s_nop 1
	v_addc_co_u32_e32 v25, vcc, 0, v19, vcc
	v_add_co_u32_e32 v26, vcc, s33, v18
	s_nop 1
	v_addc_co_u32_e32 v27, vcc, 0, v19, vcc
	v_add_co_u32_e32 v32, vcc, s34, v18
	s_nop 1
	v_addc_co_u32_e32 v33, vcc, 0, v19, vcc
	v_add_co_u32_e32 v34, vcc, s35, v18
	s_nop 1
	v_addc_co_u32_e32 v35, vcc, 0, v19, vcc
	v_add_co_u32_e32 v36, vcc, s38, v18
	s_nop 1
	v_addc_co_u32_e32 v37, vcc, 0, v19, vcc
	v_add_co_u32_e32 v18, vcc, s39, v18
	s_nop 1
	v_addc_co_u32_e32 v19, vcc, 0, v19, vcc
	global_load_dword v20, v[20:21], off
	s_nop 0
	global_load_dword v21, v[22:23], off
	s_nop 0
	global_load_dword v22, v[24:25], off
	global_load_dword v23, v[26:27], off
	s_nop 0
	global_load_dword v24, v[32:33], off
	global_load_dword v25, v[34:35], off
	global_load_dword v26, v[36:37], off
	s_nop 0
	global_load_dword v18, v[18:19], off
	s_waitcnt vmcnt(30)
	ds_write2_b32 v10, v3, v29 offset1:66
	s_waitcnt vmcnt(28)
	ds_write2_b32 v10, v31, v40 offset0:132 offset1:198
	s_waitcnt vmcnt(26)
	ds_write2_b32 v11, v41, v42 offset0:8 offset1:74
	s_waitcnt vmcnt(24)
	ds_write2_b32 v11, v43, v44 offset0:140 offset1:206
	s_waitcnt vmcnt(22)
	ds_write2_b32 v12, v45, v46 offset0:16 offset1:82
	s_waitcnt vmcnt(20)
	ds_write2_b32 v12, v47, v48 offset0:148 offset1:214
	s_waitcnt vmcnt(18)
	ds_write2_b32 v13, v49, v50 offset0:24 offset1:90
	s_waitcnt vmcnt(16)
	ds_write2_b32 v13, v51, v52 offset0:156 offset1:222
	s_waitcnt vmcnt(14)
	ds_write2_b32 v14, v53, v54 offset0:32 offset1:98
	s_waitcnt vmcnt(12)
	ds_write2_b32 v14, v55, v56 offset0:164 offset1:230
	s_waitcnt vmcnt(10)
	ds_write2_b32 v15, v57, v58 offset0:40 offset1:106
	s_waitcnt vmcnt(8)
	ds_write2_b32 v15, v59, v38 offset0:172 offset1:238
	s_waitcnt vmcnt(6)
	ds_write2_b32 v16, v20, v21 offset0:48 offset1:114
	s_waitcnt vmcnt(4)
	ds_write2_b32 v16, v22, v23 offset0:180 offset1:246
	s_waitcnt vmcnt(2)
	ds_write2_b32 v17, v24, v25 offset0:56 offset1:122
	s_waitcnt vmcnt(0)
	ds_write2_b32 v17, v26, v18 offset0:188 offset1:254
	s_waitcnt lgkmcnt(0)
	ds_read2_b32 v[22:23], v6 offset1:8
	ds_read2_b32 v[26:27], v6 offset0:33 offset1:41
	ds_read2_b32 v[32:33], v6 offset0:66 offset1:74
	v_mov_b32_e32 v3, v1
	ds_read2_b32 v[34:35], v6 offset0:99 offset1:107
	v_lshl_add_u64 v[24:25], s[44:45], 0, v[2:3]
	s_waitcnt lgkmcnt(3)
	v_bfe_u32 v3, v22, 16, 1
	v_add3_u32 v3, v22, v3, s40
	s_waitcnt lgkmcnt(2)
	v_bfe_u32 v18, v26, 16, 1
	ds_read2_b32 v[36:37], v6 offset0:132 offset1:140
	v_lshrrev_b32_e32 v3, 16, v3
	v_add3_u32 v18, v26, v18, s40
	ds_read2_b32 v[38:39], v6 offset0:165 offset1:173
	v_and_or_b32 v18, v18, s41, v3
	s_waitcnt lgkmcnt(3)
	v_bfe_u32 v3, v32, 16, 1
	v_add3_u32 v3, v32, v3, s40
	s_waitcnt lgkmcnt(2)
	v_bfe_u32 v19, v34, 16, 1
	ds_read2_b32 v[40:41], v6 offset0:198 offset1:206
	v_lshrrev_b32_e32 v3, 16, v3
	v_add3_u32 v19, v34, v19, s40
	ds_read2_b32 v[42:43], v6 offset0:231 offset1:239
	v_and_or_b32 v19, v19, s41, v3
	s_waitcnt lgkmcnt(3)
	v_bfe_u32 v3, v36, 16, 1
	v_add3_u32 v3, v36, v3, s40
	s_waitcnt lgkmcnt(2)
	v_bfe_u32 v20, v38, 16, 1
	v_lshrrev_b32_e32 v3, 16, v3
	v_add3_u32 v20, v38, v20, s40
	v_and_or_b32 v20, v20, s41, v3
	s_waitcnt lgkmcnt(1)
	v_bfe_u32 v3, v40, 16, 1
	v_add3_u32 v3, v40, v3, s40
	s_waitcnt lgkmcnt(0)
	v_bfe_u32 v21, v42, 16, 1
	v_lshrrev_b32_e32 v3, 16, v3
	v_add3_u32 v21, v42, v21, s40
	v_and_or_b32 v21, v21, s41, v3
	v_or_b32_e32 v3, s4, v5
	v_lshlrev_b32_e32 v44, 11, v3
	v_mov_b32_e32 v45, v1
	v_lshl_add_u64 v[44:45], v[24:25], 0, v[44:45]
	v_bfe_u32 v3, v23, 16, 1
	global_store_dwordx4 v[44:45], v[18:21], off sc1
	v_add3_u32 v3, v23, v3, s40
	v_lshrrev_b32_e32 v3, 16, v3
	v_bfe_u32 v18, v27, 16, 1
	v_add3_u32 v18, v27, v18, s40
	v_and_or_b32 v18, v18, s41, v3
	v_bfe_u32 v3, v33, 16, 1
	v_add3_u32 v3, v33, v3, s40
	v_bfe_u32 v19, v35, 16, 1
	v_lshrrev_b32_e32 v3, 16, v3
	v_add3_u32 v19, v35, v19, s40
	v_and_or_b32 v19, v19, s41, v3
	v_bfe_u32 v3, v37, 16, 1
	v_add3_u32 v3, v37, v3, s40
	v_bfe_u32 v20, v39, 16, 1
	v_lshrrev_b32_e32 v3, 16, v3
	v_add3_u32 v20, v39, v20, s40
	v_and_or_b32 v20, v20, s41, v3
	v_bfe_u32 v3, v41, 16, 1
	v_add3_u32 v3, v41, v3, s40
	v_bfe_u32 v21, v43, 16, 1
	v_lshrrev_b32_e32 v3, 16, v3
	v_add3_u32 v21, v43, v21, s40
	v_and_or_b32 v21, v21, s41, v3
	v_or_b32_e32 v3, s4, v7
	v_lshlrev_b32_e32 v22, 11, v3
	v_mov_b32_e32 v23, v1
	ds_read2_b32 v[26:27], v6 offset0:16 offset1:24
	v_lshl_add_u64 v[22:23], v[24:25], 0, v[22:23]
	global_store_dwordx4 v[22:23], v[18:21], off sc1
	ds_read2_b32 v[22:23], v6 offset0:49 offset1:57
	ds_read2_b32 v[32:33], v6 offset0:82 offset1:90
	ds_read2_b32 v[34:35], v6 offset0:115 offset1:123
	s_waitcnt lgkmcnt(3)
	v_bfe_u32 v3, v26, 16, 1
	v_add3_u32 v3, v26, v3, s40
	s_waitcnt lgkmcnt(2)
	v_bfe_u32 v18, v22, 16, 1
	ds_read2_b32 v[36:37], v6 offset0:148 offset1:156
	v_lshrrev_b32_e32 v3, 16, v3
	v_add3_u32 v18, v22, v18, s40
	ds_read2_b32 v[38:39], v6 offset0:181 offset1:189
	v_and_or_b32 v18, v18, s41, v3
	s_waitcnt lgkmcnt(3)
	v_bfe_u32 v3, v32, 16, 1
	v_add3_u32 v3, v32, v3, s40
	s_waitcnt lgkmcnt(2)
	v_bfe_u32 v19, v34, 16, 1
	ds_read2_b32 v[40:41], v6 offset0:214 offset1:222
	v_lshrrev_b32_e32 v3, 16, v3
	v_add3_u32 v19, v34, v19, s40
	ds_read2_b32 v[42:43], v6 offset0:247 offset1:255
	v_and_or_b32 v19, v19, s41, v3
	s_waitcnt lgkmcnt(3)
	v_bfe_u32 v3, v36, 16, 1
	v_add3_u32 v3, v36, v3, s40
	s_waitcnt lgkmcnt(2)
	v_bfe_u32 v20, v38, 16, 1
	v_lshrrev_b32_e32 v3, 16, v3
	v_add3_u32 v20, v38, v20, s40
	v_and_or_b32 v20, v20, s41, v3
	s_waitcnt lgkmcnt(1)
	v_bfe_u32 v3, v40, 16, 1
	v_add3_u32 v3, v40, v3, s40
	s_waitcnt lgkmcnt(0)
	v_bfe_u32 v21, v42, 16, 1
	v_lshrrev_b32_e32 v3, 16, v3
	v_add3_u32 v21, v42, v21, s40
	v_and_or_b32 v21, v21, s41, v3
	v_or_b32_e32 v3, s4, v8
	v_lshlrev_b32_e32 v44, 11, v3
	v_mov_b32_e32 v45, v1
	v_lshl_add_u64 v[44:45], v[24:25], 0, v[44:45]
	v_bfe_u32 v3, v27, 16, 1
	global_store_dwordx4 v[44:45], v[18:21], off sc1
	v_add3_u32 v3, v27, v3, s40
	v_lshrrev_b32_e32 v3, 16, v3
	v_bfe_u32 v18, v23, 16, 1
	v_add3_u32 v18, v23, v18, s40
	v_and_or_b32 v18, v18, s41, v3
	v_bfe_u32 v3, v33, 16, 1
	v_add3_u32 v3, v33, v3, s40
	v_bfe_u32 v19, v35, 16, 1
	v_lshrrev_b32_e32 v3, 16, v3
	v_add3_u32 v19, v35, v19, s40
	v_and_or_b32 v19, v19, s41, v3
	v_bfe_u32 v3, v37, 16, 1
	v_add3_u32 v3, v37, v3, s40
	v_bfe_u32 v20, v39, 16, 1
	v_lshrrev_b32_e32 v3, 16, v3
	v_add3_u32 v20, v39, v20, s40
	v_and_or_b32 v20, v20, s41, v3
	v_bfe_u32 v3, v41, 16, 1
	v_add3_u32 v3, v41, v3, s40
	v_bfe_u32 v21, v43, 16, 1
	v_lshrrev_b32_e32 v3, 16, v3
	v_add3_u32 v21, v43, v21, s40
	v_and_or_b32 v21, v21, s41, v3
	v_or_b32_e32 v3, s4, v9
	v_lshlrev_b32_e32 v22, 11, v3
	v_mov_b32_e32 v23, v1
	v_lshl_add_u64 v[22:23], v[24:25], 0, v[22:23]
	global_store_dwordx4 v[22:23], v[18:21], off sc1
	s_waitcnt lgkmcnt(0)
	s_mov_b64 s[4:5], 0
.LBB0_25:
	s_andn2_b64 vcc, exec, s[4:5]
	s_cbranch_vccnz .LBB0_22
	s_lshl_b64 s[4:5], s[0:1], 24
	s_waitcnt lgkmcnt(0)
	s_add_u32 s2, s64, s4
	s_addc_u32 s5, s65, s5
	s_lshl_b64 s[0:1], s[0:1], 23
	v_readlane_b32 s4, v252, 16
	s_add_u32 s45, s4, s0
	v_readlane_b32 s0, v252, 17
	s_addc_u32 s44, s0, s1
	s_bfe_u32 s0, s43, 0x70018
	s_add_i32 s0, s43, s0
	s_sext_i32_i16 s1, s0
	s_and_b32 s0, s0, 0xff80
	s_sub_i32 s0, s43, s0
	s_sext_i32_i16 s0, s0
	s_ashr_i32 s1, s1, 7
	s_lshl_b32 s0, s0, 5
	s_lshl_b32 s4, s1, 6
	s_ashr_i32 s1, s0, 31
	v_or_b32_e32 v18, s4, v4
	s_lshl_b64 s[46:47], s[0:1], 2
	s_add_u32 s46, s2, s46
	v_or_b32_e32 v24, 2, v18
	v_or_b32_e32 v26, 4, v18
	v_or_b32_e32 v32, 6, v18
	v_or_b32_e32 v34, 8, v18
	v_or_b32_e32 v36, 10, v18
	v_or_b32_e32 v38, 12, v18
	v_or_b32_e32 v40, 14, v18
	s_addc_u32 s47, s5, s47
	v_ashrrev_i32_e32 v19, 31, v18
	v_ashrrev_i32_e32 v25, 31, v24
	v_ashrrev_i32_e32 v27, 31, v26
	v_ashrrev_i32_e32 v33, 31, v32
	v_ashrrev_i32_e32 v35, 31, v34
	v_ashrrev_i32_e32 v37, 31, v36
	v_ashrrev_i32_e32 v39, 31, v38
	v_ashrrev_i32_e32 v41, 31, v40
	v_lshl_add_u64 v[20:21], s[46:47], 0, v[0:1]
	v_lshlrev_b64 v[22:23], 14, v[18:19]
	v_lshlrev_b64 v[24:25], 14, v[24:25]
	v_lshlrev_b64 v[26:27], 14, v[26:27]
	v_lshlrev_b64 v[32:33], 14, v[32:33]
	v_lshlrev_b64 v[34:35], 14, v[34:35]
	v_lshlrev_b64 v[36:37], 14, v[36:37]
	v_lshlrev_b64 v[38:39], 14, v[38:39]
	v_lshlrev_b64 v[40:41], 14, v[40:41]
	v_lshl_add_u64 v[22:23], v[20:21], 0, v[22:23]
	v_lshl_add_u64 v[24:25], v[20:21], 0, v[24:25]
	v_lshl_add_u64 v[26:27], v[20:21], 0, v[26:27]
	v_lshl_add_u64 v[32:33], v[20:21], 0, v[32:33]
	v_lshl_add_u64 v[34:35], v[20:21], 0, v[34:35]
	v_lshl_add_u64 v[36:37], v[20:21], 0, v[36:37]
	v_lshl_add_u64 v[38:39], v[20:21], 0, v[38:39]
	v_lshl_add_u64 v[40:41], v[20:21], 0, v[40:41]
	global_load_dword v3, v[22:23], off
	global_load_dword v29, v[24:25], off
	global_load_dword v31, v[26:27], off
	global_load_dword v42, v[32:33], off
	global_load_dword v43, v[34:35], off
	global_load_dword v44, v[36:37], off
	global_load_dword v45, v[38:39], off
	global_load_dword v46, v[40:41], off
	v_or_b32_e32 v22, 16, v18
	v_or_b32_e32 v24, 18, v18
	v_or_b32_e32 v26, 20, v18
	v_or_b32_e32 v32, 22, v18
	v_or_b32_e32 v34, 24, v18
	v_or_b32_e32 v36, 26, v18
	v_or_b32_e32 v38, 28, v18
	v_or_b32_e32 v40, 30, v18
	v_ashrrev_i32_e32 v23, 31, v22
	v_ashrrev_i32_e32 v25, 31, v24
	v_ashrrev_i32_e32 v27, 31, v26
	v_ashrrev_i32_e32 v33, 31, v32
	v_ashrrev_i32_e32 v35, 31, v34
	v_ashrrev_i32_e32 v37, 31, v36
	v_ashrrev_i32_e32 v39, 31, v38
	v_ashrrev_i32_e32 v41, 31, v40
	v_lshlrev_b64 v[22:23], 14, v[22:23]
	v_lshlrev_b64 v[24:25], 14, v[24:25]
	v_lshlrev_b64 v[26:27], 14, v[26:27]
	v_lshlrev_b64 v[32:33], 14, v[32:33]
	v_lshlrev_b64 v[34:35], 14, v[34:35]
	v_lshlrev_b64 v[36:37], 14, v[36:37]
	v_lshlrev_b64 v[38:39], 14, v[38:39]
	v_lshlrev_b64 v[40:41], 14, v[40:41]
	v_lshl_add_u64 v[22:23], v[20:21], 0, v[22:23]
	v_lshl_add_u64 v[24:25], v[20:21], 0, v[24:25]
	v_lshl_add_u64 v[26:27], v[20:21], 0, v[26:27]
	v_lshl_add_u64 v[32:33], v[20:21], 0, v[32:33]
	v_lshl_add_u64 v[34:35], v[20:21], 0, v[34:35]
	v_lshl_add_u64 v[36:37], v[20:21], 0, v[36:37]
	v_lshl_add_u64 v[38:39], v[20:21], 0, v[38:39]
	v_lshl_add_u64 v[40:41], v[20:21], 0, v[40:41]
	global_load_dword v47, v[22:23], off
	global_load_dword v48, v[24:25], off
	global_load_dword v49, v[26:27], off
	global_load_dword v50, v[32:33], off
	global_load_dword v51, v[34:35], off
	global_load_dword v52, v[36:37], off
	global_load_dword v53, v[38:39], off
	global_load_dword v54, v[40:41], off
	v_or_b32_e32 v22, 32, v18
	v_or_b32_e32 v24, 34, v18
	v_or_b32_e32 v26, 36, v18
	v_or_b32_e32 v32, 38, v18
	v_or_b32_e32 v34, 40, v18
	v_or_b32_e32 v36, 42, v18
	v_or_b32_e32 v38, 44, v18
	v_or_b32_e32 v40, 46, v18
	v_ashrrev_i32_e32 v23, 31, v22
	v_ashrrev_i32_e32 v25, 31, v24
	v_ashrrev_i32_e32 v27, 31, v26
	v_ashrrev_i32_e32 v33, 31, v32
	v_ashrrev_i32_e32 v35, 31, v34
	v_ashrrev_i32_e32 v37, 31, v36
	v_ashrrev_i32_e32 v39, 31, v38
	v_ashrrev_i32_e32 v41, 31, v40
	v_lshlrev_b64 v[22:23], 14, v[22:23]
	v_lshlrev_b64 v[24:25], 14, v[24:25]
	v_lshlrev_b64 v[26:27], 14, v[26:27]
	v_lshlrev_b64 v[32:33], 14, v[32:33]
	v_lshlrev_b64 v[34:35], 14, v[34:35]
	v_lshlrev_b64 v[36:37], 14, v[36:37]
	v_lshlrev_b64 v[38:39], 14, v[38:39]
	v_lshlrev_b64 v[40:41], 14, v[40:41]
	v_lshl_add_u64 v[22:23], v[20:21], 0, v[22:23]
	v_lshl_add_u64 v[24:25], v[20:21], 0, v[24:25]
	v_lshl_add_u64 v[26:27], v[20:21], 0, v[26:27]
	v_lshl_add_u64 v[32:33], v[20:21], 0, v[32:33]
	v_lshl_add_u64 v[34:35], v[20:21], 0, v[34:35]
	v_lshl_add_u64 v[36:37], v[20:21], 0, v[36:37]
	v_lshl_add_u64 v[38:39], v[20:21], 0, v[38:39]
	v_lshl_add_u64 v[40:41], v[20:21], 0, v[40:41]
	global_load_dword v55, v[22:23], off
	global_load_dword v56, v[24:25], off
	global_load_dword v57, v[26:27], off
	global_load_dword v58, v[32:33], off
	global_load_dword v59, v[34:35], off
	global_load_dword v60, v[36:37], off
	global_load_dword v61, v[38:39], off
	s_nop 0
	global_load_dword v40, v[40:41], off
	v_or_b32_e32 v22, 48, v18
	v_or_b32_e32 v24, 50, v18
	v_or_b32_e32 v26, 52, v18
	v_or_b32_e32 v32, 54, v18
	v_or_b32_e32 v34, 56, v18
	v_or_b32_e32 v36, 58, v18
	v_or_b32_e32 v38, 60, v18
	v_or_b32_e32 v18, 62, v18
	v_ashrrev_i32_e32 v23, 31, v22
	v_ashrrev_i32_e32 v25, 31, v24
	v_ashrrev_i32_e32 v27, 31, v26
	v_ashrrev_i32_e32 v19, 31, v18
	v_lshlrev_b64 v[22:23], 14, v[22:23]
	v_lshlrev_b64 v[24:25], 14, v[24:25]
	v_lshlrev_b64 v[26:27], 14, v[26:27]
	v_ashrrev_i32_e32 v33, 31, v32
	v_ashrrev_i32_e32 v35, 31, v34
	v_ashrrev_i32_e32 v37, 31, v36
	v_ashrrev_i32_e32 v39, 31, v38
	v_lshlrev_b64 v[18:19], 14, v[18:19]
	v_lshl_add_u64 v[22:23], v[20:21], 0, v[22:23]
	v_lshl_add_u64 v[24:25], v[20:21], 0, v[24:25]
	v_lshl_add_u64 v[26:27], v[20:21], 0, v[26:27]
	v_lshlrev_b64 v[32:33], 14, v[32:33]
	v_lshlrev_b64 v[34:35], 14, v[34:35]
	v_lshlrev_b64 v[36:37], 14, v[36:37]
	v_lshlrev_b64 v[38:39], 14, v[38:39]
	v_lshl_add_u64 v[18:19], v[20:21], 0, v[18:19]
	v_lshl_add_u64 v[32:33], v[20:21], 0, v[32:33]
	v_lshl_add_u64 v[34:35], v[20:21], 0, v[34:35]
	v_lshl_add_u64 v[36:37], v[20:21], 0, v[36:37]
	v_lshl_add_u64 v[38:39], v[20:21], 0, v[38:39]
	global_load_dword v20, v[22:23], off
	global_load_dword v21, v[24:25], off
	s_nop 0
	global_load_dword v22, v[26:27], off
	global_load_dword v23, v[32:33], off
	global_load_dword v24, v[34:35], off
	global_load_dword v25, v[36:37], off
	s_nop 0
	global_load_dword v26, v[38:39], off
	s_nop 0
	global_load_dword v18, v[18:19], off
	s_waitcnt vmcnt(30)
	ds_write2_b32 v10, v3, v29 offset1:66
	s_waitcnt vmcnt(28)
	ds_write2_b32 v10, v31, v42 offset0:132 offset1:198
	s_waitcnt vmcnt(26)
	ds_write2_b32 v11, v43, v44 offset0:8 offset1:74
	s_waitcnt vmcnt(24)
	ds_write2_b32 v11, v45, v46 offset0:140 offset1:206
	s_waitcnt vmcnt(22)
	ds_write2_b32 v12, v47, v48 offset0:16 offset1:82
	s_waitcnt vmcnt(20)
	ds_write2_b32 v12, v49, v50 offset0:148 offset1:214
	s_waitcnt vmcnt(18)
	ds_write2_b32 v13, v51, v52 offset0:24 offset1:90
	s_waitcnt vmcnt(16)
	ds_write2_b32 v13, v53, v54 offset0:156 offset1:222
	s_waitcnt vmcnt(14)
	ds_write2_b32 v14, v55, v56 offset0:32 offset1:98
	s_waitcnt vmcnt(12)
	ds_write2_b32 v14, v57, v58 offset0:164 offset1:230
	s_waitcnt vmcnt(10)
	ds_write2_b32 v15, v59, v60 offset0:40 offset1:106
	s_waitcnt vmcnt(8)
	ds_write2_b32 v15, v61, v40 offset0:172 offset1:238
	s_waitcnt vmcnt(6)
	ds_write2_b32 v16, v20, v21 offset0:48 offset1:114
	s_waitcnt vmcnt(4)
	ds_write2_b32 v16, v22, v23 offset0:180 offset1:246
	s_waitcnt vmcnt(2)
	ds_write2_b32 v17, v24, v25 offset0:56 offset1:122
	s_waitcnt vmcnt(0)
	ds_write2_b32 v17, v26, v18 offset0:188 offset1:254
	s_waitcnt lgkmcnt(0)
	ds_read2_b32 v[22:23], v6 offset1:8
	s_ashr_i32 s5, s4, 31
	ds_read2_b32 v[26:27], v6 offset0:33 offset1:41
	s_lshl_b64 s[4:5], s[4:5], 1
	s_add_u32 s4, s45, s4
	ds_read2_b32 v[32:33], v6 offset0:66 offset1:74
	s_addc_u32 s5, s44, s5
	v_mov_b32_e32 v3, v1
	ds_read2_b32 v[34:35], v6 offset0:99 offset1:107
	v_lshl_add_u64 v[24:25], s[4:5], 0, v[2:3]
	s_waitcnt lgkmcnt(3)
	v_bfe_u32 v3, v22, 16, 1
	v_add3_u32 v3, v22, v3, s40
	s_waitcnt lgkmcnt(2)
	v_bfe_u32 v18, v26, 16, 1
	ds_read2_b32 v[36:37], v6 offset0:132 offset1:140
	v_lshrrev_b32_e32 v3, 16, v3
	v_add3_u32 v18, v26, v18, s40
	ds_read2_b32 v[38:39], v6 offset0:165 offset1:173
	v_and_or_b32 v18, v18, s41, v3
	s_waitcnt lgkmcnt(3)
	v_bfe_u32 v3, v32, 16, 1
	v_add3_u32 v3, v32, v3, s40
	s_waitcnt lgkmcnt(2)
	v_bfe_u32 v19, v34, 16, 1
	ds_read2_b32 v[40:41], v6 offset0:198 offset1:206
	v_lshrrev_b32_e32 v3, 16, v3
	v_add3_u32 v19, v34, v19, s40
	ds_read2_b32 v[42:43], v6 offset0:231 offset1:239
	v_and_or_b32 v19, v19, s41, v3
	s_waitcnt lgkmcnt(3)
	v_bfe_u32 v3, v36, 16, 1
	v_add3_u32 v3, v36, v3, s40
	s_waitcnt lgkmcnt(2)
	v_bfe_u32 v20, v38, 16, 1
	v_lshrrev_b32_e32 v3, 16, v3
	v_add3_u32 v20, v38, v20, s40
	v_and_or_b32 v20, v20, s41, v3
	s_waitcnt lgkmcnt(1)
	v_bfe_u32 v3, v40, 16, 1
	v_or_b32_e32 v44, s0, v5
	v_add3_u32 v3, v40, v3, s40
	s_waitcnt lgkmcnt(0)
	v_bfe_u32 v21, v42, 16, 1
	v_ashrrev_i32_e32 v45, 31, v44
	v_lshrrev_b32_e32 v3, 16, v3
	v_add3_u32 v21, v42, v21, s40
	v_lshlrev_b64 v[44:45], 11, v[44:45]
	v_and_or_b32 v21, v21, s41, v3
	v_lshl_add_u64 v[44:45], v[24:25], 0, v[44:45]
	v_bfe_u32 v3, v23, 16, 1
	global_store_dwordx4 v[44:45], v[18:21], off sc1
	v_add3_u32 v3, v23, v3, s40
	v_lshrrev_b32_e32 v3, 16, v3
	v_bfe_u32 v18, v27, 16, 1
	v_add3_u32 v18, v27, v18, s40
	v_and_or_b32 v18, v18, s41, v3
	v_bfe_u32 v3, v33, 16, 1
	v_add3_u32 v3, v33, v3, s40
	v_bfe_u32 v19, v35, 16, 1
	v_lshrrev_b32_e32 v3, 16, v3
	v_add3_u32 v19, v35, v19, s40
	v_and_or_b32 v19, v19, s41, v3
	v_bfe_u32 v3, v37, 16, 1
	v_add3_u32 v3, v37, v3, s40
	v_bfe_u32 v20, v39, 16, 1
	v_lshrrev_b32_e32 v3, 16, v3
	v_add3_u32 v20, v39, v20, s40
	v_and_or_b32 v20, v20, s41, v3
	v_bfe_u32 v3, v41, 16, 1
	v_or_b32_e32 v22, s0, v7
	v_add3_u32 v3, v41, v3, s40
	v_bfe_u32 v21, v43, 16, 1
	v_ashrrev_i32_e32 v23, 31, v22
	v_lshrrev_b32_e32 v3, 16, v3
	v_add3_u32 v21, v43, v21, s40
	v_lshlrev_b64 v[22:23], 11, v[22:23]
	v_and_or_b32 v21, v21, s41, v3
	ds_read2_b32 v[26:27], v6 offset0:16 offset1:24
	v_lshl_add_u64 v[22:23], v[24:25], 0, v[22:23]
	global_store_dwordx4 v[22:23], v[18:21], off sc1
	ds_read2_b32 v[22:23], v6 offset0:49 offset1:57
	ds_read2_b32 v[32:33], v6 offset0:82 offset1:90
	ds_read2_b32 v[34:35], v6 offset0:115 offset1:123
	s_waitcnt lgkmcnt(3)
	v_bfe_u32 v3, v26, 16, 1
	v_add3_u32 v3, v26, v3, s40
	s_waitcnt lgkmcnt(2)
	v_bfe_u32 v18, v22, 16, 1
	ds_read2_b32 v[36:37], v6 offset0:148 offset1:156
	v_lshrrev_b32_e32 v3, 16, v3
	v_add3_u32 v18, v22, v18, s40
	ds_read2_b32 v[38:39], v6 offset0:181 offset1:189
	v_and_or_b32 v18, v18, s41, v3
	s_waitcnt lgkmcnt(3)
	v_bfe_u32 v3, v32, 16, 1
	v_add3_u32 v3, v32, v3, s40
	s_waitcnt lgkmcnt(2)
	v_bfe_u32 v19, v34, 16, 1
	ds_read2_b32 v[40:41], v6 offset0:214 offset1:222
	v_lshrrev_b32_e32 v3, 16, v3
	v_add3_u32 v19, v34, v19, s40
	ds_read2_b32 v[42:43], v6 offset0:247 offset1:255
	v_and_or_b32 v19, v19, s41, v3
	s_waitcnt lgkmcnt(3)
	v_bfe_u32 v3, v36, 16, 1
	v_add3_u32 v3, v36, v3, s40
	s_waitcnt lgkmcnt(2)
	v_bfe_u32 v20, v38, 16, 1
	v_lshrrev_b32_e32 v3, 16, v3
	v_add3_u32 v20, v38, v20, s40
	v_and_or_b32 v20, v20, s41, v3
	s_waitcnt lgkmcnt(1)
	v_bfe_u32 v3, v40, 16, 1
	v_or_b32_e32 v44, s0, v8
	v_add3_u32 v3, v40, v3, s40
	s_waitcnt lgkmcnt(0)
	v_bfe_u32 v21, v42, 16, 1
	v_ashrrev_i32_e32 v45, 31, v44
	v_lshrrev_b32_e32 v3, 16, v3
	v_add3_u32 v21, v42, v21, s40
	v_lshlrev_b64 v[44:45], 11, v[44:45]
	v_and_or_b32 v21, v21, s41, v3
	v_lshl_add_u64 v[44:45], v[24:25], 0, v[44:45]
	v_bfe_u32 v3, v27, 16, 1
	global_store_dwordx4 v[44:45], v[18:21], off sc1
	v_add3_u32 v3, v27, v3, s40
	v_lshrrev_b32_e32 v3, 16, v3
	v_bfe_u32 v18, v23, 16, 1
	v_add3_u32 v18, v23, v18, s40
	v_and_or_b32 v18, v18, s41, v3
	v_bfe_u32 v3, v33, 16, 1
	v_add3_u32 v3, v33, v3, s40
	v_bfe_u32 v19, v35, 16, 1
	v_lshrrev_b32_e32 v3, 16, v3
	v_add3_u32 v19, v35, v19, s40
	v_and_or_b32 v19, v19, s41, v3
	v_bfe_u32 v3, v37, 16, 1
	v_add3_u32 v3, v37, v3, s40
	v_bfe_u32 v20, v39, 16, 1
	v_lshrrev_b32_e32 v3, 16, v3
	v_add3_u32 v20, v39, v20, s40
	v_and_or_b32 v20, v20, s41, v3
	v_bfe_u32 v3, v41, 16, 1
	v_or_b32_e32 v22, s0, v9
	v_add3_u32 v3, v41, v3, s40
	v_bfe_u32 v21, v43, 16, 1
	v_ashrrev_i32_e32 v23, 31, v22
	v_lshrrev_b32_e32 v3, 16, v3
	v_add3_u32 v21, v43, v21, s40
	v_lshlrev_b64 v[22:23], 11, v[22:23]
	v_and_or_b32 v21, v21, s41, v3
	v_lshl_add_u64 v[22:23], v[24:25], 0, v[22:23]
	global_store_dwordx4 v[22:23], v[18:21], off sc1
	s_waitcnt lgkmcnt(0)
	s_branch .LBB0_22

.LBB0_34:
	s_or_b64 exec, exec, s[4:5]
	v_ashrrev_i32_e32 v1, 31, v0
	v_readlane_b32 s2, v252, 12
	v_lshlrev_b64 v[0:1], 2, v[0:1]
	v_readlane_b32 s3, v252, 13
	v_cvt_f32_f64_e32 v6, v[4:5]
	v_cvt_f32_f64_e32 v2, v[2:3]
	v_lshl_add_u64 v[4:5], s[2:3], 0, v[0:1]
	v_readlane_b32 s2, v252, 14
	v_readlane_b32 s3, v252, 15
	global_store_dword v[4:5], v6, off sc1
	s_nop 0
	v_lshl_add_u64 v[0:1], s[2:3], 0, v[0:1]
	global_store_dword v[0:1], v2, off sc1

.LBB0_54:
	global_load_dword v5, v[0:1], off
	v_ashrrev_i32_e32 v6, 6, v4
	v_add_u32_e32 v7, 0x200, v4
	v_lshl_add_u32 v12, v6, 8, v31
	v_cmp_lt_i32_e64 s[0:1], 63, v4
	v_add_u32_e32 v14, s12, v6
	v_mov_b32_e32 v4, v7
	ds_read2st64_b32 v[6:7], v12 offset0:144 offset1:153
	ds_read2st64_b32 v[8:9], v12 offset0:162 offset1:171
	ds_read2st64_b32 v[10:11], v12 offset0:180 offset1:189
	ds_read2st64_b32 v[12:13], v12 offset0:198 offset1:207
	s_or_b64 s[6:7], s[0:1], s[6:7]
	v_mad_i64_i32 v[14:15], s[0:1], v14, s10, v[2:3]
	s_waitcnt vmcnt(0) lgkmcnt(3)
	v_add_f32_e32 v5, v5, v6
	v_add_f32_e32 v5, v5, v7
	s_waitcnt lgkmcnt(2)
	v_add_f32_e32 v5, v5, v8
	v_add_f32_e32 v5, v5, v9
	s_waitcnt lgkmcnt(1)
	v_add_f32_e32 v5, v5, v10
	v_add_f32_e32 v5, v5, v11
	s_waitcnt lgkmcnt(0)
	v_add_f32_e32 v5, v5, v12
	v_add_f32_e32 v5, v5, v13
	global_store_dword v[14:15], v5, off sc1
	s_andn2_b64 exec, exec, s[6:7]
	s_cbranch_execnz .LBB0_54
	s_branch .LBB0_49

.LBB0_131:
	s_and_b64 s[10:11], s[10:11], exec
	v_readlane_b32 s10, v252, 32
	v_ashrrev_i32_e32 v181, 31, v180
	v_readlane_b32 s11, v252, 33
	s_cselect_b32 s1, s52, s78
	s_cselect_b32 s12, s53, s79
	s_cselect_b32 s13, s56, s33
	s_cselect_b32 s16, s57, s73
	s_and_b64 s[10:11], s[10:11], exec
	v_lshlrev_b64 v[194:195], 12, v[180:181]
	s_cselect_b32 s39, s16, s12
	s_cselect_b32 s38, s13, s1
	v_lshl_or_b32 v194, v188, 2, v194
	v_lshl_add_u64 v[208:209], s[38:39], 0, v[194:195]
	global_load_dwordx4 v[222:225], v[208:209], off
	global_load_dwordx4 v[226:229], v[208:209], off offset:64
	global_load_dwordx4 v[230:233], v[208:209], off offset:512
	global_load_dwordx4 v[234:237], v[208:209], off offset:576
	v_readlane_b32 s10, v252, 35
	s_waitcnt vmcnt(3)
	v_pk_add_f32 v[132:133], v[132:133], 1.0 op_sel_hi:[1,0]
	v_pk_add_f32 v[130:131], v[130:131], 1.0 op_sel_hi:[1,0]
	v_readlane_b32 s11, v252, 36
	s_and_b64 vcc, exec, s[36:37]
	v_sub_f32_e32 v223, v223, v186
	v_sub_f32_e32 v222, v222, v186
	v_sub_f32_e32 v225, v225, v186
	v_sub_f32_e32 v224, v224, v186
	v_pk_mul_f32 v[224:225], v[184:185], v[224:225] op_sel_hi:[0,1]
	v_pk_mul_f32 v[222:223], v[184:185], v[222:223] op_sel_hi:[0,1]
	v_pk_fma_f32 v[222:223], v[152:153], v[222:223], v[156:157]
	v_pk_fma_f32 v[224:225], v[150:151], v[224:225], v[154:155]
	v_lshl_add_u64 v[194:195], s[10:11], 0, v[194:195]
	v_pk_fma_f32 v[128:129], v[128:129], v[132:133], v[224:225]
	v_pk_fma_f32 v[126:127], v[126:127], v[130:131], v[222:223]
	global_store_dwordx4 v[194:195], v[126:129], off sc1
	s_nop 0
	s_nop 0
	v_pk_add_f32 v[126:127], v[136:137], 1.0 op_sel_hi:[1,0]
	v_pk_add_f32 v[128:129], v[134:135], 1.0 op_sel_hi:[1,0]
	s_waitcnt vmcnt(3)
	v_sub_f32_e32 v135, v227, v186
	v_sub_f32_e32 v134, v226, v186
	v_sub_f32_e32 v137, v229, v186
	v_sub_f32_e32 v136, v228, v186
	v_pk_mul_f32 v[136:137], v[184:185], v[136:137] op_sel_hi:[0,1]
	v_pk_mul_f32 v[134:135], v[184:185], v[134:135] op_sel_hi:[0,1]
	v_pk_fma_f32 v[134:135], v[146:147], v[134:135], v[148:149]
	v_pk_fma_f32 v[136:137], v[158:159], v[136:137], v[164:165]
	v_pk_fma_f32 v[122:123], v[122:123], v[128:129], v[134:135]
	v_pk_fma_f32 v[124:125], v[124:125], v[126:127], v[136:137]
	global_store_dwordx4 v[194:195], v[122:125], off offset:64 sc1
	s_nop 0
	s_waitcnt vmcnt(3)
	v_sub_f32_e32 v231, v231, v186
	v_sub_f32_e32 v230, v230, v186
	v_sub_f32_e32 v233, v233, v186
	v_sub_f32_e32 v232, v232, v186
	v_pk_mul_f32 v[232:233], v[184:185], v[232:233] op_sel_hi:[0,1]
	v_pk_mul_f32 v[230:231], v[184:185], v[230:231] op_sel_hi:[0,1]
	v_pk_add_f32 v[122:123], v[140:141], 1.0 op_sel_hi:[1,0]
	v_pk_add_f32 v[124:125], v[138:139], 1.0 op_sel_hi:[1,0]
	v_pk_fma_f32 v[230:231], v[168:169], v[230:231], v[172:173]
	v_pk_fma_f32 v[232:233], v[166:167], v[232:233], v[170:171]
	v_pk_fma_f32 v[118:119], v[118:119], v[124:125], v[230:231]
	v_pk_fma_f32 v[120:121], v[120:121], v[122:123], v[232:233]
	global_store_dwordx4 v[194:195], v[118:121], off offset:512 sc1
	s_nop 0
	s_waitcnt vmcnt(3)
	v_sub_f32_e32 v235, v235, v186
	v_sub_f32_e32 v234, v234, v186
	v_sub_f32_e32 v237, v237, v186
	v_sub_f32_e32 v236, v236, v186
	v_pk_mul_f32 v[236:237], v[184:185], v[236:237] op_sel_hi:[0,1]
	v_pk_mul_f32 v[234:235], v[184:185], v[234:235] op_sel_hi:[0,1]
	v_pk_add_f32 v[118:119], v[144:145], 1.0 op_sel_hi:[1,0]
	v_pk_add_f32 v[120:121], v[142:143], 1.0 op_sel_hi:[1,0]
	v_pk_fma_f32 v[234:235], v[160:161], v[234:235], v[162:163]
	v_pk_fma_f32 v[236:237], v[174:175], v[236:237], v[176:177]
	v_pk_fma_f32 v[114:115], v[114:115], v[120:121], v[234:235]
	v_pk_fma_f32 v[116:117], v[116:117], v[118:119], v[236:237]
	global_store_dwordx4 v[194:195], v[114:117], off offset:576 sc1
	s_cbranch_vccnz .LBB0_133
	s_nop 0
	v_or_b32_e32 v114, 16, v178
	v_ashrrev_i32_e32 v115, 31, v114
	v_lshl_add_u64 v[114:115], v[114:115], 3, s[8:9]
	global_load_dwordx2 v[182:183], v[114:115], off
	s_waitcnt vmcnt(0)
	v_mov_b32_e32 v0, v183
.LBB0_133:
	s_nop 0
	v_or_b32_e32 v114, 16, v180
	v_ashrrev_i32_e32 v115, 31, v114
	v_lshlrev_b64 v[134:135], 12, v[114:115]
	v_lshl_or_b32 v134, v188, 2, v134
	v_lshl_add_u64 v[136:137], s[38:39], 0, v[134:135]
	global_load_dwordx4 v[222:225], v[136:137], off
	global_load_dwordx4 v[226:229], v[136:137], off offset:64
	global_load_dwordx4 v[230:233], v[136:137], off offset:512
	global_load_dwordx4 v[234:237], v[136:137], off offset:576
	v_readlane_b32 s10, v252, 35
	v_readlane_b32 s11, v252, 36
	s_and_b64 vcc, exec, s[36:37]
	s_waitcnt vmcnt(3)
	v_sub_f32_e32 v223, v223, v182
	v_sub_f32_e32 v222, v222, v182
	v_sub_f32_e32 v225, v225, v182
	v_sub_f32_e32 v224, v224, v182
	v_pk_mul_f32 v[224:225], v[0:1], v[224:225] op_sel_hi:[0,1]
	v_pk_mul_f32 v[222:223], v[0:1], v[222:223] op_sel_hi:[0,1]
	v_pk_fma_f32 v[222:223], v[152:153], v[222:223], v[156:157]
	v_pk_fma_f32 v[224:225], v[150:151], v[224:225], v[154:155]
	v_lshl_add_u64 v[134:135], s[10:11], 0, v[134:135]
	v_pk_fma_f32 v[112:113], v[112:113], v[132:133], v[224:225]
	v_pk_fma_f32 v[110:111], v[110:111], v[130:131], v[222:223]
	global_store_dwordx4 v[134:135], v[110:113], off sc1
	s_nop 0
	s_waitcnt vmcnt(3)
	v_sub_f32_e32 v227, v227, v182
	v_sub_f32_e32 v226, v226, v182
	v_sub_f32_e32 v229, v229, v182
	v_sub_f32_e32 v228, v228, v182
	v_pk_mul_f32 v[228:229], v[0:1], v[228:229] op_sel_hi:[0,1]
	v_pk_mul_f32 v[226:227], v[0:1], v[226:227] op_sel_hi:[0,1]
	v_pk_fma_f32 v[226:227], v[146:147], v[226:227], v[148:149]
	v_pk_fma_f32 v[228:229], v[158:159], v[228:229], v[164:165]
	v_pk_fma_f32 v[106:107], v[106:107], v[128:129], v[226:227]
	v_pk_fma_f32 v[108:109], v[108:109], v[126:127], v[228:229]
	global_store_dwordx4 v[134:135], v[106:109], off offset:64 sc1
	s_nop 0
	s_waitcnt vmcnt(3)
	v_sub_f32_e32 v231, v231, v182
	v_sub_f32_e32 v230, v230, v182
	v_sub_f32_e32 v233, v233, v182
	v_sub_f32_e32 v232, v232, v182
	v_pk_mul_f32 v[232:233], v[0:1], v[232:233] op_sel_hi:[0,1]
	v_pk_mul_f32 v[230:231], v[0:1], v[230:231] op_sel_hi:[0,1]
	v_pk_fma_f32 v[230:231], v[168:169], v[230:231], v[172:173]
	v_pk_fma_f32 v[232:233], v[166:167], v[232:233], v[170:171]
	v_pk_fma_f32 v[102:103], v[102:103], v[124:125], v[230:231]
	v_pk_fma_f32 v[104:105], v[104:105], v[122:123], v[232:233]
	global_store_dwordx4 v[134:135], v[102:105], off offset:512 sc1
	s_nop 0
	s_waitcnt vmcnt(3)
	v_sub_f32_e32 v237, v237, v182
	v_sub_f32_e32 v235, v235, v182
	v_sub_f32_e32 v234, v234, v182
	v_sub_f32_e32 v236, v236, v182
	v_pk_mul_f32 v[236:237], v[0:1], v[236:237] op_sel_hi:[0,1]
	v_pk_mul_f32 v[234:235], v[0:1], v[234:235] op_sel_hi:[0,1]
	v_pk_fma_f32 v[234:235], v[160:161], v[234:235], v[162:163]
	v_pk_fma_f32 v[236:237], v[174:175], v[236:237], v[176:177]
	v_pk_fma_f32 v[98:99], v[98:99], v[120:121], v[234:235]
	v_pk_fma_f32 v[100:101], v[100:101], v[118:119], v[236:237]
	global_store_dwordx4 v[134:135], v[98:101], off offset:576 sc1
	v_mov_b32_e32 v102, 1.0
	v_mov_b32_e32 v0, 1.0
	v_mov_b32_e32 v98, 0
	v_mov_b32_e32 v100, 0
	s_cbranch_vccnz .LBB0_135
	v_or_b32_e32 v100, 32, v178
	v_ashrrev_i32_e32 v101, 31, v100
	v_lshl_add_u64 v[100:101], v[100:101], 3, s[8:9]
	global_load_dwordx2 v[100:101], v[100:101], off
	s_waitcnt vmcnt(0)
	v_mov_b32_e32 v0, v101
.LBB0_135:
	v_or_b32_e32 v104, 32, v180
	v_ashrrev_i32_e32 v105, 31, v104
	v_lshlrev_b64 v[108:109], 12, v[104:105]
	v_lshl_or_b32 v108, v188, 2, v108
	v_lshl_add_u64 v[110:111], s[38:39], 0, v[108:109]
	global_load_dwordx4 v[222:225], v[110:111], off
	global_load_dwordx4 v[226:229], v[110:111], off offset:64
	global_load_dwordx4 v[230:233], v[110:111], off offset:512
	global_load_dwordx4 v[234:237], v[110:111], off offset:576
	v_readlane_b32 s10, v252, 35
	v_readlane_b32 s11, v252, 36
	s_and_b64 vcc, exec, s[36:37]
	s_waitcnt vmcnt(3)
	v_sub_f32_e32 v223, v223, v100
	v_sub_f32_e32 v222, v222, v100
	v_sub_f32_e32 v225, v225, v100
	v_sub_f32_e32 v224, v224, v100
	v_pk_mul_f32 v[224:225], v[0:1], v[224:225] op_sel_hi:[0,1]
	v_pk_mul_f32 v[222:223], v[0:1], v[222:223] op_sel_hi:[0,1]
	v_pk_fma_f32 v[222:223], v[152:153], v[222:223], v[156:157]
	v_pk_fma_f32 v[224:225], v[150:151], v[224:225], v[154:155]
	v_lshl_add_u64 v[108:109], s[10:11], 0, v[108:109]
	v_pk_fma_f32 v[96:97], v[96:97], v[132:133], v[224:225]
	v_pk_fma_f32 v[94:95], v[94:95], v[130:131], v[222:223]
	global_store_dwordx4 v[108:109], v[94:97], off sc1
	s_nop 0
	s_waitcnt vmcnt(3)
	v_sub_f32_e32 v227, v227, v100
	v_sub_f32_e32 v226, v226, v100
	v_sub_f32_e32 v229, v229, v100
	v_sub_f32_e32 v228, v228, v100
	v_pk_mul_f32 v[228:229], v[0:1], v[228:229] op_sel_hi:[0,1]
	v_pk_mul_f32 v[226:227], v[0:1], v[226:227] op_sel_hi:[0,1]
	v_pk_fma_f32 v[226:227], v[146:147], v[226:227], v[148:149]
	v_pk_fma_f32 v[228:229], v[158:159], v[228:229], v[164:165]
	v_pk_fma_f32 v[90:91], v[90:91], v[128:129], v[226:227]
	v_pk_fma_f32 v[92:93], v[92:93], v[126:127], v[228:229]
	global_store_dwordx4 v[108:109], v[90:93], off offset:64 sc1
	s_nop 0
	s_waitcnt vmcnt(3)
	v_sub_f32_e32 v231, v231, v100
	v_sub_f32_e32 v230, v230, v100
	v_sub_f32_e32 v233, v233, v100
	v_sub_f32_e32 v232, v232, v100
	v_pk_mul_f32 v[232:233], v[0:1], v[232:233] op_sel_hi:[0,1]
	v_pk_mul_f32 v[230:231], v[0:1], v[230:231] op_sel_hi:[0,1]
	v_pk_fma_f32 v[230:231], v[168:169], v[230:231], v[172:173]
	v_pk_fma_f32 v[232:233], v[166:167], v[232:233], v[170:171]
	v_pk_fma_f32 v[86:87], v[86:87], v[124:125], v[230:231]
	v_pk_fma_f32 v[88:89], v[88:89], v[122:123], v[232:233]
	global_store_dwordx4 v[108:109], v[86:89], off offset:512 sc1
	s_nop 0
	s_waitcnt vmcnt(3)
	v_sub_f32_e32 v235, v235, v100
	v_sub_f32_e32 v234, v234, v100
	v_sub_f32_e32 v237, v237, v100
	v_sub_f32_e32 v236, v236, v100
	v_pk_mul_f32 v[236:237], v[0:1], v[236:237] op_sel_hi:[0,1]
	v_pk_mul_f32 v[234:235], v[0:1], v[234:235] op_sel_hi:[0,1]
	v_pk_fma_f32 v[234:235], v[160:161], v[234:235], v[162:163]
	v_pk_fma_f32 v[236:237], v[174:175], v[236:237], v[176:177]
	v_pk_fma_f32 v[82:83], v[82:83], v[120:121], v[234:235]
	v_pk_fma_f32 v[84:85], v[84:85], v[118:119], v[236:237]
	global_store_dwordx4 v[108:109], v[82:85], off offset:576 sc1
	s_cbranch_vccnz .LBB0_137
	s_nop 0
	v_or_b32_e32 v82, 48, v178
	v_ashrrev_i32_e32 v83, 31, v82
	v_lshl_add_u64 v[82:83], v[82:83], 3, s[8:9]
	global_load_dwordx2 v[98:99], v[82:83], off
	s_waitcnt vmcnt(0)
	v_mov_b32_e32 v102, v99
.LBB0_137:
	s_nop 0
	v_or_b32_e32 v82, 48, v180
	v_ashrrev_i32_e32 v83, 31, v82
	v_lshlrev_b64 v[86:87], 12, v[82:83]
	v_lshl_or_b32 v86, v188, 2, v86
	v_lshl_add_u64 v[88:89], s[38:39], 0, v[86:87]
	global_load_dwordx4 v[222:225], v[88:89], off
	global_load_dwordx4 v[226:229], v[88:89], off offset:64
	global_load_dwordx4 v[230:233], v[88:89], off offset:512
	global_load_dwordx4 v[234:237], v[88:89], off offset:576
	v_readlane_b32 s10, v252, 35
	v_readlane_b32 s11, v252, 36
	v_mov_b32_e32 v0, 1.0
	s_and_b64 vcc, exec, s[36:37]
	v_lshl_add_u64 v[86:87], s[10:11], 0, v[86:87]
	s_waitcnt vmcnt(3)
	v_sub_f32_e32 v223, v223, v98
	v_sub_f32_e32 v222, v222, v98
	v_sub_f32_e32 v225, v225, v98
	v_sub_f32_e32 v224, v224, v98
	v_pk_mul_f32 v[224:225], v[102:103], v[224:225] op_sel_hi:[0,1]
	v_pk_mul_f32 v[222:223], v[102:103], v[222:223] op_sel_hi:[0,1]
	v_pk_fma_f32 v[222:223], v[152:153], v[222:223], v[156:157]
	v_pk_fma_f32 v[224:225], v[150:151], v[224:225], v[154:155]
	v_pk_fma_f32 v[78:79], v[78:79], v[130:131], v[222:223]
	v_pk_fma_f32 v[80:81], v[80:81], v[132:133], v[224:225]
	global_store_dwordx4 v[86:87], v[78:81], off sc1
	s_nop 0
	s_waitcnt vmcnt(3)
	v_sub_f32_e32 v227, v227, v98
	v_sub_f32_e32 v226, v226, v98
	v_sub_f32_e32 v229, v229, v98
	v_sub_f32_e32 v228, v228, v98
	v_pk_mul_f32 v[228:229], v[102:103], v[228:229] op_sel_hi:[0,1]
	v_pk_mul_f32 v[226:227], v[102:103], v[226:227] op_sel_hi:[0,1]
	v_pk_fma_f32 v[226:227], v[146:147], v[226:227], v[148:149]
	v_pk_fma_f32 v[228:229], v[158:159], v[228:229], v[164:165]
	v_pk_fma_f32 v[74:75], v[74:75], v[128:129], v[226:227]
	v_pk_fma_f32 v[76:77], v[76:77], v[126:127], v[228:229]
	global_store_dwordx4 v[86:87], v[74:77], off offset:64 sc1
	s_nop 0
	s_waitcnt vmcnt(3)
	v_sub_f32_e32 v231, v231, v98
	v_sub_f32_e32 v230, v230, v98
	v_sub_f32_e32 v233, v233, v98
	v_sub_f32_e32 v232, v232, v98
	v_pk_mul_f32 v[232:233], v[102:103], v[232:233] op_sel_hi:[0,1]
	v_pk_mul_f32 v[230:231], v[102:103], v[230:231] op_sel_hi:[0,1]
	v_pk_fma_f32 v[230:231], v[168:169], v[230:231], v[172:173]
	v_pk_fma_f32 v[232:233], v[166:167], v[232:233], v[170:171]
	v_pk_fma_f32 v[70:71], v[70:71], v[124:125], v[230:231]
	v_pk_fma_f32 v[72:73], v[72:73], v[122:123], v[232:233]
	global_store_dwordx4 v[86:87], v[70:73], off offset:512 sc1
	s_nop 0
	s_waitcnt vmcnt(3)
	v_sub_f32_e32 v235, v235, v98
	v_sub_f32_e32 v234, v234, v98
	v_sub_f32_e32 v237, v237, v98
	v_sub_f32_e32 v236, v236, v98
	v_pk_mul_f32 v[236:237], v[102:103], v[236:237] op_sel_hi:[0,1]
	v_pk_mul_f32 v[234:235], v[102:103], v[234:235] op_sel_hi:[0,1]
	v_pk_fma_f32 v[234:235], v[160:161], v[234:235], v[162:163]
	v_pk_fma_f32 v[236:237], v[174:175], v[236:237], v[176:177]
	v_pk_fma_f32 v[66:67], v[66:67], v[120:121], v[234:235]
	v_pk_fma_f32 v[68:69], v[68:69], v[118:119], v[236:237]
	global_store_dwordx4 v[86:87], v[66:69], off offset:576 sc1
	v_mov_b32_e32 v72, 0
	v_mov_b32_e32 v70, 1.0
	v_mov_b32_e32 v66, 0
	s_cbranch_vccnz .LBB0_139
	v_lshl_add_u64 v[68:69], v[178:179], 3, s[8:9]
	global_load_dwordx2 v[72:73], v[68:69], off offset:1024
	s_waitcnt vmcnt(0)
	v_mov_b32_e32 v70, v73
.LBB0_139:
	v_lshlrev_b64 v[68:69], 12, v[180:181]
	v_lshl_or_b32 v68, v188, 2, v68
	s_mov_b64 s[10:11], 0x80000
	v_lshl_add_u64 v[78:79], v[68:69], 0, s[10:11]
	v_lshl_add_u64 v[80:81], s[38:39], 0, v[78:79]
	global_load_dwordx4 v[222:225], v[80:81], off
	global_load_dwordx4 v[226:229], v[80:81], off offset:64
	global_load_dwordx4 v[230:233], v[80:81], off offset:512
	global_load_dwordx4 v[234:237], v[80:81], off offset:576
	v_readlane_b32 s10, v252, 35
	v_readlane_b32 s11, v252, 36
	s_and_b64 vcc, exec, s[36:37]
	s_waitcnt vmcnt(3)
	v_sub_f32_e32 v223, v223, v72
	v_sub_f32_e32 v222, v222, v72
	v_sub_f32_e32 v225, v225, v72
	v_sub_f32_e32 v224, v224, v72
	v_pk_mul_f32 v[224:225], v[70:71], v[224:225] op_sel_hi:[0,1]
	v_pk_mul_f32 v[222:223], v[70:71], v[222:223] op_sel_hi:[0,1]
	v_pk_fma_f32 v[222:223], v[152:153], v[222:223], v[156:157]
	v_pk_fma_f32 v[224:225], v[150:151], v[224:225], v[154:155]
	v_lshl_add_u64 v[78:79], s[10:11], 0, v[78:79]
	v_pk_fma_f32 v[64:65], v[64:65], v[132:133], v[224:225]
	v_pk_fma_f32 v[62:63], v[62:63], v[130:131], v[222:223]
	global_store_dwordx4 v[78:79], v[62:65], off sc1
	s_nop 0
	s_waitcnt vmcnt(3)
	v_sub_f32_e32 v227, v227, v72
	v_sub_f32_e32 v226, v226, v72
	v_sub_f32_e32 v229, v229, v72
	v_sub_f32_e32 v228, v228, v72
	v_pk_mul_f32 v[228:229], v[70:71], v[228:229] op_sel_hi:[0,1]
	v_pk_mul_f32 v[226:227], v[70:71], v[226:227] op_sel_hi:[0,1]
	v_pk_fma_f32 v[226:227], v[146:147], v[226:227], v[148:149]
	v_pk_fma_f32 v[228:229], v[158:159], v[228:229], v[164:165]
	v_pk_fma_f32 v[58:59], v[58:59], v[128:129], v[226:227]
	v_pk_fma_f32 v[60:61], v[60:61], v[126:127], v[228:229]
	global_store_dwordx4 v[78:79], v[58:61], off offset:64 sc1
	s_nop 0
	s_waitcnt vmcnt(3)
	v_sub_f32_e32 v231, v231, v72
	v_sub_f32_e32 v230, v230, v72
	v_sub_f32_e32 v233, v233, v72
	v_sub_f32_e32 v232, v232, v72
	v_pk_mul_f32 v[232:233], v[70:71], v[232:233] op_sel_hi:[0,1]
	v_pk_mul_f32 v[230:231], v[70:71], v[230:231] op_sel_hi:[0,1]
	v_pk_fma_f32 v[230:231], v[168:169], v[230:231], v[172:173]
	v_pk_fma_f32 v[232:233], v[166:167], v[232:233], v[170:171]
	v_pk_fma_f32 v[54:55], v[54:55], v[124:125], v[230:231]
	v_pk_fma_f32 v[56:57], v[56:57], v[122:123], v[232:233]
	global_store_dwordx4 v[78:79], v[54:57], off offset:512 sc1
	s_nop 0
	s_waitcnt vmcnt(3)
	v_sub_f32_e32 v235, v235, v72
	v_sub_f32_e32 v234, v234, v72
	v_sub_f32_e32 v237, v237, v72
	v_sub_f32_e32 v236, v236, v72
	v_pk_mul_f32 v[236:237], v[70:71], v[236:237] op_sel_hi:[0,1]
	v_pk_mul_f32 v[234:235], v[70:71], v[234:235] op_sel_hi:[0,1]
	v_pk_fma_f32 v[234:235], v[160:161], v[234:235], v[162:163]
	v_pk_fma_f32 v[236:237], v[174:175], v[236:237], v[176:177]
	v_pk_fma_f32 v[50:51], v[50:51], v[120:121], v[234:235]
	v_pk_fma_f32 v[52:53], v[52:53], v[118:119], v[236:237]
	global_store_dwordx4 v[78:79], v[50:53], off offset:576 sc1
	s_cbranch_vccnz .LBB0_141
	s_nop 0
	v_lshl_add_u64 v[50:51], v[178:179], 3, s[8:9]
	global_load_dwordx2 v[66:67], v[50:51], off offset:1152
	s_waitcnt vmcnt(0)
	v_mov_b32_e32 v0, v67
.LBB0_141:
	s_mov_b64 s[10:11], 0x90000
	v_lshl_add_u64 v[54:55], v[68:69], 0, s[10:11]
	v_lshl_add_u64 v[56:57], s[38:39], 0, v[54:55]
	global_load_dwordx4 v[222:225], v[56:57], off
	global_load_dwordx4 v[226:229], v[56:57], off offset:64
	global_load_dwordx4 v[230:233], v[56:57], off offset:512
	global_load_dwordx4 v[234:237], v[56:57], off offset:576
	v_readlane_b32 s10, v252, 35
	v_readlane_b32 s11, v252, 36
	s_and_b64 vcc, exec, s[36:37]
	s_waitcnt vmcnt(3)
	v_sub_f32_e32 v223, v223, v66
	v_sub_f32_e32 v222, v222, v66
	v_sub_f32_e32 v225, v225, v66
	v_sub_f32_e32 v224, v224, v66
	v_pk_mul_f32 v[224:225], v[0:1], v[224:225] op_sel_hi:[0,1]
	v_pk_mul_f32 v[222:223], v[0:1], v[222:223] op_sel_hi:[0,1]
	v_pk_fma_f32 v[222:223], v[152:153], v[222:223], v[156:157]
	v_pk_fma_f32 v[224:225], v[150:151], v[224:225], v[154:155]
	v_lshl_add_u64 v[54:55], s[10:11], 0, v[54:55]
	v_pk_fma_f32 v[48:49], v[48:49], v[132:133], v[224:225]
	v_pk_fma_f32 v[46:47], v[46:47], v[130:131], v[222:223]
	global_store_dwordx4 v[54:55], v[46:49], off sc1
	s_nop 0
	s_waitcnt vmcnt(3)
	v_sub_f32_e32 v227, v227, v66
	v_sub_f32_e32 v226, v226, v66
	v_sub_f32_e32 v229, v229, v66
	v_sub_f32_e32 v228, v228, v66
	v_pk_mul_f32 v[228:229], v[0:1], v[228:229] op_sel_hi:[0,1]
	v_pk_mul_f32 v[226:227], v[0:1], v[226:227] op_sel_hi:[0,1]
	v_pk_fma_f32 v[226:227], v[146:147], v[226:227], v[148:149]
	v_pk_fma_f32 v[228:229], v[158:159], v[228:229], v[164:165]
	v_pk_fma_f32 v[42:43], v[42:43], v[128:129], v[226:227]
	v_pk_fma_f32 v[44:45], v[44:45], v[126:127], v[228:229]
	global_store_dwordx4 v[54:55], v[42:45], off offset:64 sc1
	s_nop 0
	s_waitcnt vmcnt(3)
	v_sub_f32_e32 v231, v231, v66
	v_sub_f32_e32 v230, v230, v66
	v_sub_f32_e32 v233, v233, v66
	v_sub_f32_e32 v232, v232, v66
	v_pk_mul_f32 v[232:233], v[0:1], v[232:233] op_sel_hi:[0,1]
	v_pk_mul_f32 v[230:231], v[0:1], v[230:231] op_sel_hi:[0,1]
	v_pk_fma_f32 v[230:231], v[168:169], v[230:231], v[172:173]
	v_pk_fma_f32 v[232:233], v[166:167], v[232:233], v[170:171]
	v_pk_fma_f32 v[38:39], v[38:39], v[124:125], v[230:231]
	v_pk_fma_f32 v[40:41], v[40:41], v[122:123], v[232:233]
	global_store_dwordx4 v[54:55], v[38:41], off offset:512 sc1
	s_nop 0
	s_waitcnt vmcnt(3)
	v_sub_f32_e32 v237, v237, v66
	v_sub_f32_e32 v235, v235, v66
	v_sub_f32_e32 v234, v234, v66
	v_sub_f32_e32 v236, v236, v66
	v_pk_mul_f32 v[236:237], v[0:1], v[236:237] op_sel_hi:[0,1]
	v_pk_mul_f32 v[234:235], v[0:1], v[234:235] op_sel_hi:[0,1]
	v_pk_fma_f32 v[234:235], v[160:161], v[234:235], v[162:163]
	v_pk_fma_f32 v[236:237], v[174:175], v[236:237], v[176:177]
	v_pk_fma_f32 v[34:35], v[34:35], v[120:121], v[234:235]
	v_pk_fma_f32 v[36:37], v[36:37], v[118:119], v[236:237]
	global_store_dwordx4 v[54:55], v[34:37], off offset:576 sc1
	v_mov_b32_e32 v38, 1.0
	v_mov_b32_e32 v40, 0
	v_mov_b32_e32 v34, 0
	v_mov_b32_e32 v0, 1.0
	s_cbranch_vccnz .LBB0_143
	v_lshl_add_u64 v[36:37], v[178:179], 3, s[8:9]
	global_load_dwordx2 v[40:41], v[36:37], off offset:1280
	s_waitcnt vmcnt(0)
	v_mov_b32_e32 v0, v41
.LBB0_143:
	v_lshlrev_b64 v[36:37], 12, v[180:181]
	v_lshl_or_b32 v36, v188, 2, v36
	s_mov_b64 s[10:11], 0xa0000
	v_lshl_add_u64 v[46:47], v[36:37], 0, s[10:11]
	v_lshl_add_u64 v[48:49], s[38:39], 0, v[46:47]
	global_load_dwordx4 v[222:225], v[48:49], off
	global_load_dwordx4 v[226:229], v[48:49], off offset:64
	global_load_dwordx4 v[230:233], v[48:49], off offset:512
	global_load_dwordx4 v[234:237], v[48:49], off offset:576
	v_readlane_b32 s10, v252, 35
	v_readlane_b32 s11, v252, 36
	s_and_b64 vcc, exec, s[36:37]
	s_waitcnt vmcnt(3)
	v_sub_f32_e32 v223, v223, v40
	v_sub_f32_e32 v222, v222, v40
	v_sub_f32_e32 v225, v225, v40
	v_sub_f32_e32 v224, v224, v40
	v_pk_mul_f32 v[224:225], v[0:1], v[224:225] op_sel_hi:[0,1]
	v_pk_mul_f32 v[222:223], v[0:1], v[222:223] op_sel_hi:[0,1]
	v_pk_fma_f32 v[222:223], v[152:153], v[222:223], v[156:157]
	v_pk_fma_f32 v[224:225], v[150:151], v[224:225], v[154:155]
	v_lshl_add_u64 v[46:47], s[10:11], 0, v[46:47]
	v_pk_fma_f32 v[32:33], v[32:33], v[132:133], v[224:225]
	v_pk_fma_f32 v[30:31], v[30:31], v[130:131], v[222:223]
	global_store_dwordx4 v[46:47], v[30:33], off sc1
	s_nop 0
	s_waitcnt vmcnt(3)
	v_sub_f32_e32 v227, v227, v40
	v_sub_f32_e32 v226, v226, v40
	v_sub_f32_e32 v229, v229, v40
	v_sub_f32_e32 v228, v228, v40
	v_pk_mul_f32 v[228:229], v[0:1], v[228:229] op_sel_hi:[0,1]
	v_pk_mul_f32 v[226:227], v[0:1], v[226:227] op_sel_hi:[0,1]
	v_pk_fma_f32 v[226:227], v[146:147], v[226:227], v[148:149]
	v_pk_fma_f32 v[228:229], v[158:159], v[228:229], v[164:165]
	v_pk_fma_f32 v[26:27], v[26:27], v[128:129], v[226:227]
	v_pk_fma_f32 v[28:29], v[28:29], v[126:127], v[228:229]
	global_store_dwordx4 v[46:47], v[26:29], off offset:64 sc1
	s_nop 0
	s_waitcnt vmcnt(3)
	v_sub_f32_e32 v231, v231, v40
	v_sub_f32_e32 v230, v230, v40
	v_sub_f32_e32 v233, v233, v40
	v_sub_f32_e32 v232, v232, v40
	v_pk_mul_f32 v[232:233], v[0:1], v[232:233] op_sel_hi:[0,1]
	v_pk_mul_f32 v[230:231], v[0:1], v[230:231] op_sel_hi:[0,1]
	v_pk_fma_f32 v[230:231], v[168:169], v[230:231], v[172:173]
	v_pk_fma_f32 v[232:233], v[166:167], v[232:233], v[170:171]
	v_pk_fma_f32 v[22:23], v[22:23], v[124:125], v[230:231]
	v_pk_fma_f32 v[24:25], v[24:25], v[122:123], v[232:233]
	global_store_dwordx4 v[46:47], v[22:25], off offset:512 sc1
	s_nop 0
	s_waitcnt vmcnt(3)
	v_sub_f32_e32 v235, v235, v40
	v_sub_f32_e32 v234, v234, v40
	v_sub_f32_e32 v237, v237, v40
	v_sub_f32_e32 v236, v236, v40
	v_pk_mul_f32 v[236:237], v[0:1], v[236:237] op_sel_hi:[0,1]
	v_pk_mul_f32 v[234:235], v[0:1], v[234:235] op_sel_hi:[0,1]
	v_pk_fma_f32 v[234:235], v[160:161], v[234:235], v[162:163]
	v_pk_fma_f32 v[236:237], v[174:175], v[236:237], v[176:177]
	v_pk_fma_f32 v[18:19], v[18:19], v[120:121], v[234:235]
	v_pk_fma_f32 v[20:21], v[20:21], v[118:119], v[236:237]
	global_store_dwordx4 v[46:47], v[18:21], off offset:576 sc1
	s_cbranch_vccnz .LBB0_145
	s_nop 0
	v_lshl_add_u64 v[18:19], v[178:179], 3, s[8:9]
	global_load_dwordx2 v[34:35], v[18:19], off offset:1408
	s_waitcnt vmcnt(0)
	v_mov_b32_e32 v38, v35
.LBB0_145:
	s_mov_b64 s[8:9], 0xb0000
	v_lshl_add_u64 v[22:23], v[36:37], 0, s[8:9]
	v_lshl_add_u64 v[24:25], s[38:39], 0, v[22:23]
	global_load_dwordx4 v[222:225], v[24:25], off
	global_load_dwordx4 v[226:229], v[24:25], off offset:64
	global_load_dwordx4 v[230:233], v[24:25], off offset:512
	global_load_dwordx4 v[234:237], v[24:25], off offset:576
	v_readlane_b32 s8, v252, 35
	v_readlane_b32 s9, v252, 36
	v_cmp_eq_u32_e32 vcc, 0, v185
	s_waitcnt vmcnt(3)
	v_sub_f32_e32 v223, v223, v34
	v_sub_f32_e32 v222, v222, v34
	v_sub_f32_e32 v225, v225, v34
	v_sub_f32_e32 v224, v224, v34
	v_pk_mul_f32 v[224:225], v[38:39], v[224:225] op_sel_hi:[0,1]
	v_pk_mul_f32 v[222:223], v[38:39], v[222:223] op_sel_hi:[0,1]
	v_pk_fma_f32 v[222:223], v[152:153], v[222:223], v[156:157]
	v_pk_fma_f32 v[224:225], v[150:151], v[224:225], v[154:155]
	v_lshl_add_u64 v[22:23], s[8:9], 0, v[22:23]
	v_pk_fma_f32 v[16:17], v[16:17], v[132:133], v[224:225]
	v_pk_fma_f32 v[14:15], v[14:15], v[130:131], v[222:223]
	global_store_dwordx4 v[22:23], v[14:17], off sc1
	s_nop 0
	s_waitcnt vmcnt(3)
	v_sub_f32_e32 v227, v227, v34
	v_sub_f32_e32 v226, v226, v34
	v_sub_f32_e32 v229, v229, v34
	v_sub_f32_e32 v228, v228, v34
	v_pk_mul_f32 v[228:229], v[38:39], v[228:229] op_sel_hi:[0,1]
	v_pk_mul_f32 v[226:227], v[38:39], v[226:227] op_sel_hi:[0,1]
	v_pk_fma_f32 v[226:227], v[146:147], v[226:227], v[148:149]
	v_pk_fma_f32 v[228:229], v[158:159], v[228:229], v[164:165]
	v_pk_fma_f32 v[10:11], v[10:11], v[128:129], v[226:227]
	v_pk_fma_f32 v[12:13], v[12:13], v[126:127], v[228:229]
	global_store_dwordx4 v[22:23], v[10:13], off offset:64 sc1
	s_nop 0
	s_waitcnt vmcnt(3)
	v_sub_f32_e32 v231, v231, v34
	v_sub_f32_e32 v230, v230, v34
	v_sub_f32_e32 v233, v233, v34
	v_sub_f32_e32 v232, v232, v34
	v_pk_mul_f32 v[232:233], v[38:39], v[232:233] op_sel_hi:[0,1]
	v_pk_mul_f32 v[230:231], v[38:39], v[230:231] op_sel_hi:[0,1]
	v_pk_fma_f32 v[230:231], v[168:169], v[230:231], v[172:173]
	v_pk_fma_f32 v[232:233], v[166:167], v[232:233], v[170:171]
	v_pk_fma_f32 v[6:7], v[6:7], v[124:125], v[230:231]
	v_pk_fma_f32 v[8:9], v[8:9], v[122:123], v[232:233]
	global_store_dwordx4 v[22:23], v[6:9], off offset:512 sc1
	s_nop 0
	s_waitcnt vmcnt(3)
	v_sub_f32_e32 v235, v235, v34
	v_sub_f32_e32 v234, v234, v34
	v_sub_f32_e32 v237, v237, v34
	v_sub_f32_e32 v236, v236, v34
	v_pk_mul_f32 v[236:237], v[38:39], v[236:237] op_sel_hi:[0,1]
	v_pk_mul_f32 v[234:235], v[38:39], v[234:235] op_sel_hi:[0,1]
	v_pk_fma_f32 v[234:235], v[160:161], v[234:235], v[162:163]
	v_pk_fma_f32 v[236:237], v[174:175], v[236:237], v[176:177]
	v_pk_fma_f32 v[2:3], v[2:3], v[120:121], v[234:235]
	v_pk_fma_f32 v[4:5], v[4:5], v[118:119], v[236:237]
	global_store_dwordx4 v[22:23], v[2:5], off offset:576 sc1
	s_waitcnt vmcnt(0)
	s_barrier
	s_waitcnt vmcnt(0)
	s_barrier
	s_and_saveexec_b64 s[8:9], vcc
	v_readlane_b32 s16, v252, 41
	v_readlane_b32 s36, v254, 52
	v_readlane_b32 s17, v252, 42
	v_readlane_b32 s37, v254, 53
	s_cbranch_execz .LBB0_157
	s_mov_b64 s[10:11], exec
	buffer_wbl2 sc1
	s_waitcnt vmcnt(0)
	s_waitcnt vmcnt(0)
	v_mbcnt_lo_u32_b32 v0, s10, 0
	v_mbcnt_hi_u32_b32 v0, s11, v0
	v_cmp_eq_u32_e32 vcc, 0, v0
	s_and_saveexec_b64 s[12:13], vcc
	s_cbranch_execz .LBB0_148
	s_bcnt1_i32_b64 s1, s[10:11]
	v_mov_b32_e32 v0, s1
	global_atomic_add v1, v0, s[16:17]

.LBB0_161:
	s_min_i32 s0, s8, 0x8000
	s_ashr_i32 s0, s0, 12
	s_mulk_i32 s0, 0xc00
	s_ashr_i32 s1, s0, 31
	s_lshl_b64 s[0:1], s[0:1], 2
	s_add_u32 s0, s19, s0
	s_addc_u32 s1, s28, s1
	s_add_u32 s16, s0, 0x1000
	s_addc_u32 s17, s1, 0
	global_load_dwordx4 v[120:123], v0, s[0:1]
	global_load_dwordx4 v[124:127], v0, s[0:1] offset:1024
	global_load_dwordx4 v[128:131], v0, s[0:1] offset:2048
	global_load_dwordx4 v[132:135], v0, s[0:1] offset:3072
	global_load_dwordx4 v[136:139], v0, s[16:17]
	global_load_dwordx4 v[140:143], v0, s[16:17] offset:1024
	global_load_dwordx4 v[144:147], v0, s[16:17] offset:2048
	global_load_dwordx4 v[148:151], v0, s[16:17] offset:3072
	s_ashr_i32 s9, s8, 31
	s_lshl_b64 s[8:9], s[8:9], 11
	v_lshl_add_u64 v[26:27], v[72:73], 0, s[8:9]
	s_waitcnt vmcnt(0)
	v_pk_add_f32 v[138:139], v[138:139], 1.0 op_sel_hi:[1,0]
	v_pk_add_f32 v[136:137], v[136:137], 1.0 op_sel_hi:[1,0]
	v_pk_fma_f32 v[16:17], v[16:17], v[138:139], v[122:123]
	v_pk_fma_f32 v[14:15], v[14:15], v[136:137], v[120:121]
	s_nop 0
	v_cvt_pk_bf16_f32 v14, v14, v15
	v_cvt_pk_bf16_f32 v15, v16, v17
	global_store_dwordx2 v[26:27], v[14:15], off sc1
	v_pk_add_f32 v[142:143], v[142:143], 1.0 op_sel_hi:[1,0]
	v_pk_add_f32 v[140:141], v[140:141], 1.0 op_sel_hi:[1,0]
	v_pk_fma_f32 v[12:13], v[12:13], v[142:143], v[126:127]
	v_pk_fma_f32 v[10:11], v[10:11], v[140:141], v[124:125]
	s_nop 0
	v_cvt_pk_bf16_f32 v10, v10, v11
	v_cvt_pk_bf16_f32 v11, v12, v13
	global_store_dwordx2 v[26:27], v[10:11], off offset:512 sc1
	v_pk_add_f32 v[146:147], v[146:147], 1.0 op_sel_hi:[1,0]
	v_pk_add_f32 v[144:145], v[144:145], 1.0 op_sel_hi:[1,0]
	v_pk_fma_f32 v[4:5], v[4:5], v[146:147], v[130:131]
	v_pk_fma_f32 v[2:3], v[2:3], v[144:145], v[128:129]
	s_nop 0
	v_cvt_pk_bf16_f32 v2, v2, v3
	v_cvt_pk_bf16_f32 v3, v4, v5
	global_store_dwordx2 v[26:27], v[2:3], off offset:1024 sc1
	v_pk_add_f32 v[150:151], v[150:151], 1.0 op_sel_hi:[1,0]
	v_pk_add_f32 v[148:149], v[148:149], 1.0 op_sel_hi:[1,0]
	v_pk_fma_f32 v[8:9], v[8:9], v[150:151], v[134:135]
	v_pk_fma_f32 v[6:7], v[6:7], v[148:149], v[132:133]
	s_nop 0
	v_cvt_pk_bf16_f32 v6, v6, v7
	v_cvt_pk_bf16_f32 v7, v8, v9
	global_store_dwordx2 v[26:27], v[6:7], off offset:1536 sc1

.LBB0_163:
	s_add_i32 s0, s46, 0xffff8000
	s_cmpk_gt_i32 s46, 0x7fff
	s_cselect_b32 s0, s0, s46
	s_cselect_b32 s1, s56, s52
	s_cselect_b32 s10, s57, s53
	s_cselect_b32 s11, s33, s78
	s_cselect_b32 s16, s73, s79
	s_and_b64 s[8:9], s[6:7], exec
	s_cselect_b32 s8, s10, s16
	s_cselect_b32 s9, s1, s11
	s_ashr_i32 s1, s0, 31
	s_lshl_b64 s[0:1], s[0:1], 12
	s_add_u32 s0, s9, s0
	s_addc_u32 s1, s8, s1
	s_add_i32 s49, s12, s46
	s_cmp_lt_i32 s49, s13
	v_lshlrev_b32_e32 v0, 4, v66
	s_cselect_b64 s[10:11], -1, 0
	global_load_dwordx4 v[62:65], v0, s[0:1]
	global_load_dwordx4 v[58:61], v0, s[0:1] offset:1024
	global_load_dwordx4 v[54:57], v0, s[0:1] offset:2048
	global_load_dwordx4 v[50:53], v0, s[0:1] offset:3072
	s_and_b64 s[0:1], s[10:11], exec
	s_cselect_b32 s8, s49, s46
	s_cmpk_gt_i32 s8, 0x7fff
	s_cselect_b64 s[0:1], -1, 0
	s_add_i32 s9, s8, 0xffff8000
	s_and_b64 s[0:1], s[0:1], exec
	s_cselect_b32 s0, s9, s8
	s_cselect_b32 s1, s56, s52
	s_cselect_b32 s16, s57, s53
	s_cselect_b32 s17, s33, s78
	s_cselect_b32 s20, s73, s79
	s_and_b64 s[8:9], s[6:7], exec
	s_cselect_b32 s8, s16, s20
	s_cselect_b32 s9, s1, s17
	s_ashr_i32 s1, s0, 31
	s_lshl_b64 s[0:1], s[0:1], 12
	s_add_u32 s0, s9, s0
	s_addc_u32 s1, s8, s1
	s_add_i32 s16, s12, s49
	s_cmp_lt_i32 s16, s13
	s_cselect_b64 s[50:51], -1, 0
	global_load_dwordx4 v[46:49], v0, s[0:1]
	global_load_dwordx4 v[42:45], v0, s[0:1] offset:1024
	global_load_dwordx4 v[38:41], v0, s[0:1] offset:2048
	global_load_dwordx4 v[34:37], v0, s[0:1] offset:3072
	s_and_b64 s[0:1], s[50:51], exec
	s_cselect_b32 s8, s16, s46
	s_cmpk_gt_i32 s8, 0x7fff
	s_cselect_b64 s[0:1], -1, 0
	s_add_i32 s9, s8, 0xffff8000
	s_and_b64 s[0:1], s[0:1], exec
	s_cselect_b32 s0, s9, s8
	s_cselect_b32 s1, s56, s52
	s_cselect_b32 s17, s57, s53
	s_cselect_b32 s20, s33, s78
	s_cselect_b32 s22, s73, s79
	s_and_b64 s[8:9], s[6:7], exec
	s_cselect_b32 s8, s17, s22
	s_cselect_b32 s9, s1, s20
	s_ashr_i32 s1, s0, 31
	s_lshl_b64 s[0:1], s[0:1], 12
	s_add_u32 s0, s9, s0
	s_addc_u32 s1, s8, s1
	s_add_i32 s47, s12, s16
	s_cmp_lt_i32 s47, s13
	s_cselect_b64 s[8:9], -1, 0
	global_load_dwordx4 v[30:33], v0, s[0:1]
	global_load_dwordx4 v[26:29], v0, s[0:1] offset:1024
	global_load_dwordx4 v[18:21], v0, s[0:1] offset:2048
	global_load_dwordx4 v[22:25], v0, s[0:1] offset:3072
	s_and_b64 s[0:1], s[8:9], exec
	s_cselect_b32 s16, s47, s46
	s_cmpk_gt_i32 s16, 0x7fff
	s_cselect_b64 s[0:1], -1, 0
	s_add_i32 s17, s16, 0xffff8000
	s_and_b64 s[0:1], s[0:1], exec
	s_cselect_b32 s0, s17, s16
	s_cselect_b32 s1, s56, s52
	s_cselect_b32 s16, s57, s53
	s_cselect_b32 s17, s33, s78
	s_cselect_b32 s20, s73, s79
	s_and_b64 s[38:39], s[6:7], exec
	s_cselect_b32 s16, s16, s20
	s_cselect_b32 s17, s1, s17
	s_ashr_i32 s1, s0, 31
	s_lshl_b64 s[0:1], s[0:1], 12
	s_add_u32 s0, s17, s0
	s_addc_u32 s1, s16, s1
	global_load_dwordx4 v[14:17], v0, s[0:1]
	global_load_dwordx4 v[10:13], v0, s[0:1] offset:1024
	global_load_dwordx4 v[2:5], v0, s[0:1] offset:2048
	global_load_dwordx4 v[6:9], v0, s[0:1] offset:3072
	v_cndmask_b32_e64 v67, 0, 1, s[40:41]
	v_cmp_ne_u32_e64 s[38:39], 1, v67
	s_andn2_b64 vcc, exec, s[40:41]
	s_cbranch_vccnz .LBB0_167
	s_waitcnt vmcnt(0)
	v_mov_b32_e32 v78, v63
	v_mov_b32_e32 v79, v64
	v_mov_b32_e32 v80, v62
	v_mov_b32_e32 v81, v65
	v_pk_add_f32 v[78:79], v[78:79], v[80:81]
	s_waitcnt vmcnt(14)
	v_mov_b32_e32 v80, v59
	v_mov_b32_e32 v81, v60
	v_mov_b32_e32 v82, v58
	v_mov_b32_e32 v83, v61
	v_pk_add_f32 v[80:81], v[80:81], v[82:83]
	v_add_f32_e32 v67, v78, v79
	v_pk_add_f32 v[80:81], v[80:81], v[80:81] op_sel:[0,1] op_sel_hi:[1,0]
	v_add_f32_e32 v78, 0, v67
	s_waitcnt vmcnt(13)
	v_add_f32_e32 v82, v54, v55
	v_add_f32_e32 v84, v56, v57
	s_waitcnt vmcnt(12)
	v_mov_b32_e32 v79, v50
	v_mov_b32_e32 v81, v51
	v_mov_b32_e32 v83, v52
	v_mov_b32_e32 v85, v53
	v_pk_add_f32 v[78:79], v[78:79], v[80:81]
	v_pk_add_f32 v[80:81], v[82:83], v[84:85]
	s_nop 0
	v_pk_add_f32 v[78:79], v[78:79], v[80:81]
	s_nop 0
	v_add_f32_e32 v67, v78, v79
	s_nop 1
	v_add_f32_dpp v67, v67, v67 quad_perm:[1,0,3,2] row_mask:0xf bank_mask:0xf
	s_nop 1
	v_add_f32_dpp v67, v67, v67 quad_perm:[2,3,0,1] row_mask:0xf bank_mask:0xf
	s_nop 1
	v_add_f32_dpp v67, v67, v67 row_half_mirror row_mask:0xf bank_mask:0xf
	s_nop 1
	v_add_f32_dpp v67, v67, v67 row_mirror row_mask:0xf bank_mask:0xf
	s_nop 1
	v_add_f32_dpp v67, v67, v67 row_bcast:15 row_mask:0xa bank_mask:0xf
	s_nop 1
	v_add_f32_dpp v67, v67, v67 row_bcast:31 row_mask:0xc bank_mask:0xf
	s_nop 1
	v_readlane_b32 vcc_lo, v67, 63
	s_nop 1
	v_mov_b32_e32 v67, vcc_lo
	v_fmamk_f32 v65, v67, 0xba800000, v65
	v_fmamk_f32 v63, v67, 0xba800000, v63
	v_fmamk_f32 v64, v67, 0xba800000, v64
	v_fmac_f32_e32 v62, 0xba800000, v67
	v_mul_f32_e32 v84, v63, v63
	v_mul_f32_e32 v85, v65, v65
	v_fmac_f32_e32 v84, v62, v62
	v_fmac_f32_e32 v85, v64, v64
	v_fmamk_f32 v61, v67, 0xba800000, v61
	v_fmamk_f32 v59, v67, 0xba800000, v59
	v_add_f32_e32 v84, v84, v85
	v_fmamk_f32 v60, v67, 0xba800000, v60
	v_fmac_f32_e32 v58, 0xba800000, v67
	v_mul_f32_e32 v85, v59, v59
	v_mul_f32_e32 v86, v61, v61
	v_fmac_f32_e32 v85, v58, v58
	v_fmac_f32_e32 v86, v60, v60
	v_add_f32_e32 v85, v85, v86
	v_fmamk_f32 v57, v67, 0xba800000, v57
	v_fmamk_f32 v55, v67, 0xba800000, v55
	v_add_f32_e32 v84, v84, v85
	v_fmamk_f32 v56, v67, 0xba800000, v56
	v_fmac_f32_e32 v54, 0xba800000, v67
	v_mul_f32_e32 v85, v55, v55
	v_mul_f32_e32 v86, v57, v57
	v_fmac_f32_e32 v85, v54, v54
	v_fmac_f32_e32 v86, v56, v56
	v_add_f32_e32 v85, v85, v86
	v_fmamk_f32 v53, v67, 0xba800000, v53
	v_fmamk_f32 v51, v67, 0xba800000, v51
	v_add_f32_e32 v84, v84, v85
	v_fmamk_f32 v52, v67, 0xba800000, v52
	v_fmac_f32_e32 v50, 0xba800000, v67
	v_mul_f32_e32 v85, v51, v51
	v_mul_f32_e32 v86, v53, v53
	v_fmac_f32_e32 v85, v50, v50
	v_fmac_f32_e32 v86, v52, v52
	v_add_f32_e32 v85, v85, v86
	v_add_f32_e32 v84, v84, v85
	v_mov_b32_e32 v78, v84
	s_nop 1
	v_add_f32_dpp v78, v78, v78 quad_perm:[1,0,3,2] row_mask:0xf bank_mask:0xf
	s_nop 1
	v_add_f32_dpp v78, v78, v78 quad_perm:[2,3,0,1] row_mask:0xf bank_mask:0xf
	s_nop 1
	v_add_f32_dpp v78, v78, v78 row_half_mirror row_mask:0xf bank_mask:0xf
	s_nop 1
	v_add_f32_dpp v78, v78, v78 row_mirror row_mask:0xf bank_mask:0xf
	s_nop 1
	v_add_f32_dpp v78, v78, v78 row_bcast:15 row_mask:0xa bank_mask:0xf
	s_nop 1
	v_add_f32_dpp v78, v78, v78 row_bcast:31 row_mask:0xc bank_mask:0xf
	s_nop 1
	v_readlane_b32 vcc_lo, v78, 63
	s_nop 1
	v_mov_b32_e32 v78, vcc_lo
	v_fmamk_f32 v78, v78, 0x3a800000, v213
	v_mul_f32_e32 v79, 0x4f800000, v78
	v_cmp_gt_f32_e32 vcc, s61, v78
	s_nop 1
	v_cndmask_b32_e32 v78, v78, v79, vcc
	v_sqrt_f32_e32 v79, v78
	s_nop 0
	v_add_u32_e32 v80, -1, v79
	v_fma_f32 v81, -v80, v79, v78
	v_cmp_ge_f32_e64 s[0:1], 0, v81
	v_add_u32_e32 v81, 1, v79
	s_nop 0
	v_cndmask_b32_e64 v80, v79, v80, s[0:1]
	v_fma_f32 v79, -v81, v79, v78
	v_cmp_lt_f32_e64 s[0:1], 0, v79
	s_nop 1
	v_cndmask_b32_e64 v79, v80, v81, s[0:1]
	v_mul_f32_e32 v80, 0x37800000, v79
	v_cndmask_b32_e32 v79, v79, v80, vcc
	v_cmp_class_f32_e32 vcc, v78, v214
	s_nop 1
	v_cndmask_b32_e32 v78, v79, v78, vcc
	v_div_scale_f32 v79, s[0:1], v78, v78, 1.0
	v_rcp_f32_e32 v80, v79
	s_nop 0
	v_fma_f32 v81, -v79, v80, 1.0
	v_fmac_f32_e32 v80, v81, v80
	v_div_scale_f32 v81, vcc, 1.0, v78, 1.0
	v_mul_f32_e32 v82, v81, v80
	v_fma_f32 v83, -v79, v82, v81
	v_fmac_f32_e32 v82, v83, v80
	v_fma_f32 v79, -v79, v82, v81
	v_div_fmas_f32 v79, v79, v80, v82
	v_div_fixup_f32 v78, v79, v78, 1.0
	s_and_saveexec_b64 s[0:1], s[36:37]
	s_cbranch_execz .LBB0_166
	s_add_u32 s62, s90, s29
	v_mul_f32_e32 v80, 0x3a800000, v67
	s_addc_u32 s63, s91, s30
	v_mov_b32_e32 v81, v78
	global_store_dwordx2 v1, v[80:81], s[62:63] sc1

.LBB0_167:
	s_min_i32 s0, s46, 0x8000
	s_ashr_i32 s0, s0, 12
	s_mulk_i32 s0, 0xc00
	s_ashr_i32 s1, s0, 31
	s_lshl_b64 s[0:1], s[0:1], 2
	s_add_u32 s0, s19, s0
	s_addc_u32 s1, s28, s1
	s_add_u32 s16, s0, 0x1000
	s_addc_u32 s17, s1, 0
	global_load_dwordx4 v[120:123], v0, s[0:1]
	global_load_dwordx4 v[124:127], v0, s[0:1] offset:1024
	global_load_dwordx4 v[128:131], v0, s[0:1] offset:2048
	global_load_dwordx4 v[132:135], v0, s[0:1] offset:3072
	global_load_dwordx4 v[136:139], v0, s[16:17]
	global_load_dwordx4 v[140:143], v0, s[16:17] offset:1024
	global_load_dwordx4 v[144:147], v0, s[16:17] offset:2048
	global_load_dwordx4 v[148:151], v0, s[16:17] offset:3072
	v_lshl_add_u64 v[88:89], s[90:91], 0, v[74:75]
	v_add_co_u32_e32 v88, vcc, s70, v88
	v_addc_co_u32_e32 v89, vcc, 0, v89, vcc
	s_waitcnt vmcnt(0)
	v_pk_add_f32 v[138:139], v[138:139], 1.0 op_sel_hi:[1,0]
	v_pk_add_f32 v[136:137], v[136:137], 1.0 op_sel_hi:[1,0]
	v_pk_fma_f32 v[64:65], v[64:65], v[138:139], v[122:123]
	v_pk_fma_f32 v[62:63], v[62:63], v[136:137], v[120:121]
	s_nop 0
	v_cvt_pk_bf16_f32 v62, v62, v63
	v_cvt_pk_bf16_f32 v63, v64, v65
	global_store_dwordx2 v[88:89], v[62:63], off sc1
	v_pk_add_f32 v[142:143], v[142:143], 1.0 op_sel_hi:[1,0]
	v_pk_add_f32 v[140:141], v[140:141], 1.0 op_sel_hi:[1,0]
	v_pk_fma_f32 v[60:61], v[60:61], v[142:143], v[126:127]
	v_pk_fma_f32 v[58:59], v[58:59], v[140:141], v[124:125]
	s_nop 0
	v_cvt_pk_bf16_f32 v58, v58, v59
	v_cvt_pk_bf16_f32 v59, v60, v61
	global_store_dwordx2 v[88:89], v[58:59], off offset:512 sc1
	v_pk_add_f32 v[146:147], v[146:147], 1.0 op_sel_hi:[1,0]
	v_pk_add_f32 v[144:145], v[144:145], 1.0 op_sel_hi:[1,0]
	v_pk_fma_f32 v[56:57], v[56:57], v[146:147], v[130:131]
	v_pk_fma_f32 v[54:55], v[54:55], v[144:145], v[128:129]
	s_nop 0
	v_cvt_pk_bf16_f32 v54, v54, v55
	v_cvt_pk_bf16_f32 v55, v56, v57
	global_store_dwordx2 v[88:89], v[54:55], off offset:1024 sc1
	v_pk_add_f32 v[150:151], v[150:151], 1.0 op_sel_hi:[1,0]
	v_pk_add_f32 v[148:149], v[148:149], 1.0 op_sel_hi:[1,0]
	v_pk_fma_f32 v[52:53], v[52:53], v[150:151], v[134:135]
	v_pk_fma_f32 v[50:51], v[50:51], v[148:149], v[132:133]
	s_nop 0
	v_cvt_pk_bf16_f32 v50, v50, v51
	v_cvt_pk_bf16_f32 v51, v52, v53
	global_store_dwordx2 v[88:89], v[50:51], off offset:1536 sc1
	s_andn2_b64 vcc, exec, s[10:11]
	s_cbranch_vccnz .LBB0_162
	s_and_b64 vcc, exec, s[38:39]
	s_cbranch_vccnz .LBB0_172
	v_mov_b32_e32 v50, v47
	v_mov_b32_e32 v51, v48
	v_mov_b32_e32 v52, v46
	v_mov_b32_e32 v53, v49
	v_pk_add_f32 v[50:51], v[50:51], v[52:53]
	v_mov_b32_e32 v52, v43
	v_mov_b32_e32 v53, v44
	v_mov_b32_e32 v54, v42
	v_mov_b32_e32 v55, v45
	v_pk_add_f32 v[52:53], v[52:53], v[54:55]
	v_add_f32_e32 v50, v50, v51
	v_pk_add_f32 v[52:53], v[52:53], v[52:53] op_sel:[0,1] op_sel_hi:[1,0]
	v_add_f32_e32 v50, 0, v50
	v_add_f32_e32 v54, v38, v39
	v_add_f32_e32 v56, v40, v41
	v_mov_b32_e32 v51, v34
	v_mov_b32_e32 v53, v35
	v_mov_b32_e32 v55, v36
	v_mov_b32_e32 v57, v37
	v_pk_add_f32 v[50:51], v[50:51], v[52:53]
	v_pk_add_f32 v[52:53], v[54:55], v[56:57]
	s_nop 0
	v_pk_add_f32 v[50:51], v[50:51], v[52:53]
	v_add_f32_e32 v50, v50, v51
	v_mov_b32_e32 v51, v50
	s_nop 1
	v_add_f32_dpp v51, v51, v51 quad_perm:[1,0,3,2] row_mask:0xf bank_mask:0xf
	s_nop 1
	v_add_f32_dpp v51, v51, v51 quad_perm:[2,3,0,1] row_mask:0xf bank_mask:0xf
	s_nop 1
	v_add_f32_dpp v51, v51, v51 row_half_mirror row_mask:0xf bank_mask:0xf
	s_nop 1
	v_add_f32_dpp v51, v51, v51 row_mirror row_mask:0xf bank_mask:0xf
	s_nop 1
	v_add_f32_dpp v51, v51, v51 row_bcast:15 row_mask:0xa bank_mask:0xf
	s_nop 1
	v_add_f32_dpp v51, v51, v51 row_bcast:31 row_mask:0xc bank_mask:0xf
	s_nop 1
	v_readlane_b32 vcc_lo, v51, 63
	s_nop 1
	v_mov_b32_e32 v51, vcc_lo
	v_fmamk_f32 v49, v51, 0xba800000, v49
	v_fmamk_f32 v47, v51, 0xba800000, v47
	v_fmamk_f32 v48, v51, 0xba800000, v48
	v_fmac_f32_e32 v46, 0xba800000, v51
	v_mul_f32_e32 v50, v47, v47
	v_mul_f32_e32 v58, v49, v49
	v_fmac_f32_e32 v50, v46, v46
	v_fmac_f32_e32 v58, v48, v48
	v_fmamk_f32 v45, v51, 0xba800000, v45
	v_fmamk_f32 v43, v51, 0xba800000, v43
	v_add_f32_e32 v50, v50, v58
	v_fmamk_f32 v44, v51, 0xba800000, v44
	v_fmac_f32_e32 v42, 0xba800000, v51
	v_mul_f32_e32 v58, v43, v43
	v_mul_f32_e32 v59, v45, v45
	v_fmac_f32_e32 v58, v42, v42
	v_fmac_f32_e32 v59, v44, v44
	v_add_f32_e32 v58, v58, v59
	v_fmamk_f32 v41, v51, 0xba800000, v41
	v_fmamk_f32 v39, v51, 0xba800000, v39
	v_add_f32_e32 v50, v50, v58
	v_fmamk_f32 v40, v51, 0xba800000, v40
	v_fmac_f32_e32 v38, 0xba800000, v51
	v_mul_f32_e32 v58, v39, v39
	v_mul_f32_e32 v59, v41, v41
	v_fmac_f32_e32 v58, v38, v38
	v_fmac_f32_e32 v59, v40, v40
	v_add_f32_e32 v58, v58, v59
	v_fmamk_f32 v37, v51, 0xba800000, v37
	v_fmamk_f32 v35, v51, 0xba800000, v35
	v_add_f32_e32 v50, v50, v58
	v_fmamk_f32 v36, v51, 0xba800000, v36
	v_fmac_f32_e32 v34, 0xba800000, v51
	v_mul_f32_e32 v58, v35, v35
	v_mul_f32_e32 v59, v37, v37
	v_fmac_f32_e32 v58, v34, v34
	v_fmac_f32_e32 v59, v36, v36
	v_add_f32_e32 v58, v58, v59
	v_add_f32_e32 v50, v50, v58
	s_nop 1
	v_add_f32_dpp v50, v50, v50 quad_perm:[1,0,3,2] row_mask:0xf bank_mask:0xf
	s_nop 1
	v_add_f32_dpp v50, v50, v50 quad_perm:[2,3,0,1] row_mask:0xf bank_mask:0xf
	s_nop 1
	v_add_f32_dpp v50, v50, v50 row_half_mirror row_mask:0xf bank_mask:0xf
	s_nop 1
	v_add_f32_dpp v50, v50, v50 row_mirror row_mask:0xf bank_mask:0xf
	s_nop 1
	v_add_f32_dpp v50, v50, v50 row_bcast:15 row_mask:0xa bank_mask:0xf
	s_nop 1
	v_add_f32_dpp v50, v50, v50 row_bcast:31 row_mask:0xc bank_mask:0xf
	s_nop 1
	v_readlane_b32 vcc_lo, v50, 63
	s_nop 1
	v_mov_b32_e32 v50, vcc_lo
	v_fmamk_f32 v50, v50, 0x3a800000, v213
	v_mul_f32_e32 v52, 0x4f800000, v50
	v_cmp_gt_f32_e32 vcc, s61, v50
	s_nop 1
	v_cndmask_b32_e32 v50, v50, v52, vcc
	v_sqrt_f32_e32 v52, v50
	s_nop 0
	v_add_u32_e32 v53, -1, v52
	v_fma_f32 v54, -v53, v52, v50
	v_cmp_ge_f32_e64 s[0:1], 0, v54
	v_add_u32_e32 v54, 1, v52
	s_nop 0
	v_cndmask_b32_e64 v53, v52, v53, s[0:1]
	v_fma_f32 v52, -v54, v52, v50
	v_cmp_lt_f32_e64 s[0:1], 0, v52
	s_nop 1
	v_cndmask_b32_e64 v52, v53, v54, s[0:1]
	v_mul_f32_e32 v53, 0x37800000, v52
	v_cndmask_b32_e32 v52, v52, v53, vcc
	v_cmp_class_f32_e32 vcc, v50, v214
	s_nop 1
	v_cndmask_b32_e32 v50, v52, v50, vcc
	v_div_scale_f32 v52, s[0:1], v50, v50, 1.0
	v_rcp_f32_e32 v53, v52
	s_nop 0
	v_fma_f32 v54, -v52, v53, 1.0
	v_fmac_f32_e32 v53, v54, v53
	v_div_scale_f32 v54, vcc, 1.0, v50, 1.0
	v_mul_f32_e32 v55, v54, v53
	v_fma_f32 v56, -v52, v55, v54
	v_fmac_f32_e32 v55, v56, v53
	v_fma_f32 v52, -v52, v55, v54
	v_div_fmas_f32 v52, v52, v53, v55
	v_div_fixup_f32 v50, v52, v50, 1.0
	s_and_saveexec_b64 s[0:1], s[36:37]
	s_cbranch_execz .LBB0_171
	s_add_u32 s10, s90, s34
	v_mul_f32_e32 v52, 0x3a800000, v51
	s_addc_u32 s11, s91, s35
	v_mov_b32_e32 v53, v50
	global_store_dwordx2 v1, v[52:53], s[10:11] sc1

.LBB0_172:
	s_min_i32 s0, s49, 0x8000
	s_ashr_i32 s0, s0, 12
	s_mulk_i32 s0, 0xc00
	s_ashr_i32 s1, s0, 31
	s_lshl_b64 s[0:1], s[0:1], 2
	s_add_u32 s0, s19, s0
	s_addc_u32 s1, s28, s1
	s_add_u32 s16, s0, 0x1000
	s_addc_u32 s17, s1, 0
	global_load_dwordx4 v[120:123], v0, s[0:1]
	global_load_dwordx4 v[124:127], v0, s[0:1] offset:1024
	global_load_dwordx4 v[128:131], v0, s[0:1] offset:2048
	global_load_dwordx4 v[132:135], v0, s[0:1] offset:3072
	global_load_dwordx4 v[136:139], v0, s[16:17]
	global_load_dwordx4 v[140:143], v0, s[16:17] offset:1024
	global_load_dwordx4 v[144:147], v0, s[16:17] offset:2048
	global_load_dwordx4 v[148:151], v0, s[16:17] offset:3072
	v_lshl_add_u64 v[60:61], s[90:91], 0, v[76:77]
	v_add_co_u32_e32 v60, vcc, s70, v60
	v_addc_co_u32_e32 v61, vcc, 0, v61, vcc
	s_waitcnt vmcnt(0)
	v_pk_add_f32 v[138:139], v[138:139], 1.0 op_sel_hi:[1,0]
	v_pk_add_f32 v[136:137], v[136:137], 1.0 op_sel_hi:[1,0]
	v_pk_fma_f32 v[48:49], v[48:49], v[138:139], v[122:123]
	v_pk_fma_f32 v[46:47], v[46:47], v[136:137], v[120:121]
	s_nop 0
	v_cvt_pk_bf16_f32 v46, v46, v47
	v_cvt_pk_bf16_f32 v47, v48, v49
	global_store_dwordx2 v[60:61], v[46:47], off sc1
	v_pk_add_f32 v[142:143], v[142:143], 1.0 op_sel_hi:[1,0]
	v_pk_add_f32 v[140:141], v[140:141], 1.0 op_sel_hi:[1,0]
	v_pk_fma_f32 v[44:45], v[44:45], v[142:143], v[126:127]
	v_pk_fma_f32 v[42:43], v[42:43], v[140:141], v[124:125]
	s_nop 0
	v_cvt_pk_bf16_f32 v42, v42, v43
	v_cvt_pk_bf16_f32 v43, v44, v45
	global_store_dwordx2 v[60:61], v[42:43], off offset:512 sc1
	v_pk_add_f32 v[146:147], v[146:147], 1.0 op_sel_hi:[1,0]
	v_pk_add_f32 v[144:145], v[144:145], 1.0 op_sel_hi:[1,0]
	v_pk_fma_f32 v[40:41], v[40:41], v[146:147], v[130:131]
	v_pk_fma_f32 v[38:39], v[38:39], v[144:145], v[128:129]
	s_nop 0
	v_cvt_pk_bf16_f32 v38, v38, v39
	v_cvt_pk_bf16_f32 v39, v40, v41
	global_store_dwordx2 v[60:61], v[38:39], off offset:1024 sc1
	v_pk_add_f32 v[150:151], v[150:151], 1.0 op_sel_hi:[1,0]
	v_pk_add_f32 v[148:149], v[148:149], 1.0 op_sel_hi:[1,0]
	v_pk_fma_f32 v[36:37], v[36:37], v[150:151], v[134:135]
	v_pk_fma_f32 v[34:35], v[34:35], v[148:149], v[132:133]
	s_nop 0
	v_cvt_pk_bf16_f32 v34, v34, v35
	v_cvt_pk_bf16_f32 v35, v36, v37
	global_store_dwordx2 v[60:61], v[34:35], off offset:1536 sc1
	s_andn2_b64 vcc, exec, s[50:51]
	s_cbranch_vccnz .LBB0_162
	s_and_b64 vcc, exec, s[38:39]
	s_add_i32 s10, s31, s46
	s_cbranch_vccnz .LBB0_177
	v_mov_b32_e32 v34, v31
	v_mov_b32_e32 v35, v32
	v_mov_b32_e32 v36, v30
	v_mov_b32_e32 v37, v33
	v_pk_add_f32 v[34:35], v[34:35], v[36:37]
	v_mov_b32_e32 v36, v27
	v_mov_b32_e32 v37, v28
	v_mov_b32_e32 v38, v26
	v_mov_b32_e32 v39, v29
	v_pk_add_f32 v[36:37], v[36:37], v[38:39]
	v_add_f32_e32 v34, v34, v35
	v_pk_add_f32 v[36:37], v[36:37], v[36:37] op_sel:[0,1] op_sel_hi:[1,0]
	v_add_f32_e32 v34, 0, v34
	v_add_f32_e32 v38, v18, v19
	v_add_f32_e32 v40, v20, v21
	v_mov_b32_e32 v35, v22
	v_mov_b32_e32 v37, v23
	v_mov_b32_e32 v39, v24
	v_mov_b32_e32 v41, v25
	v_pk_add_f32 v[34:35], v[34:35], v[36:37]
	v_pk_add_f32 v[36:37], v[38:39], v[40:41]
	s_nop 0
	v_pk_add_f32 v[34:35], v[34:35], v[36:37]
	v_add_f32_e32 v34, v34, v35
	v_mov_b32_e32 v35, v34
	s_nop 1
	v_add_f32_dpp v35, v35, v35 quad_perm:[1,0,3,2] row_mask:0xf bank_mask:0xf
	s_nop 1
	v_add_f32_dpp v35, v35, v35 quad_perm:[2,3,0,1] row_mask:0xf bank_mask:0xf
	s_nop 1
	v_add_f32_dpp v35, v35, v35 row_half_mirror row_mask:0xf bank_mask:0xf
	s_nop 1
	v_add_f32_dpp v35, v35, v35 row_mirror row_mask:0xf bank_mask:0xf
	s_nop 1
	v_add_f32_dpp v35, v35, v35 row_bcast:15 row_mask:0xa bank_mask:0xf
	s_nop 1
	v_add_f32_dpp v35, v35, v35 row_bcast:31 row_mask:0xc bank_mask:0xf
	s_nop 1
	v_readlane_b32 vcc_lo, v35, 63
	s_nop 1
	v_mov_b32_e32 v35, vcc_lo
	v_fmamk_f32 v33, v35, 0xba800000, v33
	v_fmamk_f32 v31, v35, 0xba800000, v31
	v_fmamk_f32 v32, v35, 0xba800000, v32
	v_fmac_f32_e32 v30, 0xba800000, v35
	v_mul_f32_e32 v34, v31, v31
	v_mul_f32_e32 v42, v33, v33
	v_fmac_f32_e32 v34, v30, v30
	v_fmac_f32_e32 v42, v32, v32
	v_fmamk_f32 v29, v35, 0xba800000, v29
	v_fmamk_f32 v27, v35, 0xba800000, v27
	v_add_f32_e32 v34, v34, v42
	v_fmamk_f32 v28, v35, 0xba800000, v28
	v_fmac_f32_e32 v26, 0xba800000, v35
	v_mul_f32_e32 v42, v27, v27
	v_mul_f32_e32 v43, v29, v29
	v_fmac_f32_e32 v42, v26, v26
	v_fmac_f32_e32 v43, v28, v28
	v_add_f32_e32 v42, v42, v43
	v_fmamk_f32 v21, v35, 0xba800000, v21
	v_fmamk_f32 v19, v35, 0xba800000, v19
	v_add_f32_e32 v34, v34, v42
	v_fmamk_f32 v20, v35, 0xba800000, v20
	v_fmac_f32_e32 v18, 0xba800000, v35
	v_mul_f32_e32 v42, v19, v19
	v_mul_f32_e32 v43, v21, v21
	v_fmac_f32_e32 v42, v18, v18
	v_fmac_f32_e32 v43, v20, v20
	v_add_f32_e32 v42, v42, v43
	v_fmamk_f32 v25, v35, 0xba800000, v25
	v_fmamk_f32 v23, v35, 0xba800000, v23
	v_add_f32_e32 v34, v34, v42
	v_fmamk_f32 v24, v35, 0xba800000, v24
	v_fmac_f32_e32 v22, 0xba800000, v35
	v_mul_f32_e32 v42, v23, v23
	v_mul_f32_e32 v43, v25, v25
	v_fmac_f32_e32 v42, v22, v22
	v_fmac_f32_e32 v43, v24, v24
	v_add_f32_e32 v42, v42, v43
	v_add_f32_e32 v34, v34, v42
	s_nop 1
	v_add_f32_dpp v34, v34, v34 quad_perm:[1,0,3,2] row_mask:0xf bank_mask:0xf
	s_nop 1
	v_add_f32_dpp v34, v34, v34 quad_perm:[2,3,0,1] row_mask:0xf bank_mask:0xf
	s_nop 1
	v_add_f32_dpp v34, v34, v34 row_half_mirror row_mask:0xf bank_mask:0xf
	s_nop 1
	v_add_f32_dpp v34, v34, v34 row_mirror row_mask:0xf bank_mask:0xf
	s_nop 1
	v_add_f32_dpp v34, v34, v34 row_bcast:15 row_mask:0xa bank_mask:0xf
	s_nop 1
	v_add_f32_dpp v34, v34, v34 row_bcast:31 row_mask:0xc bank_mask:0xf
	s_nop 1
	v_readlane_b32 vcc_lo, v34, 63
	s_nop 1
	v_mov_b32_e32 v34, vcc_lo
	v_fmamk_f32 v34, v34, 0x3a800000, v213
	v_mul_f32_e32 v36, 0x4f800000, v34
	v_cmp_gt_f32_e32 vcc, s61, v34
	s_nop 1
	v_cndmask_b32_e32 v34, v34, v36, vcc
	v_sqrt_f32_e32 v36, v34
	s_nop 0
	v_add_u32_e32 v37, -1, v36
	v_fma_f32 v38, -v37, v36, v34
	v_cmp_ge_f32_e64 s[0:1], 0, v38
	v_add_u32_e32 v38, 1, v36
	s_nop 0
	v_cndmask_b32_e64 v37, v36, v37, s[0:1]
	v_fma_f32 v36, -v38, v36, v34
	v_cmp_lt_f32_e64 s[0:1], 0, v36
	s_nop 1
	v_cndmask_b32_e64 v36, v37, v38, s[0:1]
	v_mul_f32_e32 v37, 0x37800000, v36
	v_cndmask_b32_e32 v36, v36, v37, vcc
	v_cmp_class_f32_e32 vcc, v34, v214
	s_nop 1
	v_cndmask_b32_e32 v34, v36, v34, vcc
	v_div_scale_f32 v36, s[0:1], v34, v34, 1.0
	v_rcp_f32_e32 v37, v36
	s_nop 0
	v_fma_f32 v38, -v36, v37, 1.0
	v_fmac_f32_e32 v37, v38, v37
	v_div_scale_f32 v38, vcc, 1.0, v34, 1.0
	v_mul_f32_e32 v39, v38, v37
	v_fma_f32 v40, -v36, v39, v38
	v_fmac_f32_e32 v39, v40, v37
	v_fma_f32 v36, -v36, v39, v38
	v_div_fmas_f32 v36, v36, v37, v39
	v_div_fixup_f32 v34, v36, v34, 1.0
	s_and_saveexec_b64 s[0:1], s[36:37]
	s_cbranch_execz .LBB0_176
	s_ashr_i32 s11, s10, 31
	s_lshl_b64 s[50:51], s[10:11], 3
	v_readlane_b32 s11, v252, 20
	s_add_u32 s50, s11, s50
	v_readlane_b32 s11, v252, 21
	v_mul_f32_e32 v36, 0x3a800000, v35
	s_addc_u32 s51, s11, s51
	v_mov_b32_e32 v37, v34
	global_store_dwordx2 v1, v[36:37], s[50:51] sc1

.LBB0_177:
	s_min_i32 s0, s10, 0x8000
	s_ashr_i32 s0, s0, 12
	s_mulk_i32 s0, 0xc00
	s_ashr_i32 s1, s0, 31
	s_lshl_b64 s[0:1], s[0:1], 2
	s_add_u32 s0, s19, s0
	s_addc_u32 s1, s28, s1
	s_add_u32 s16, s0, 0x1000
	s_addc_u32 s17, s1, 0
	global_load_dwordx4 v[120:123], v0, s[0:1]
	global_load_dwordx4 v[124:127], v0, s[0:1] offset:1024
	global_load_dwordx4 v[128:131], v0, s[0:1] offset:2048
	global_load_dwordx4 v[132:135], v0, s[0:1] offset:3072
	global_load_dwordx4 v[136:139], v0, s[16:17]
	global_load_dwordx4 v[140:143], v0, s[16:17] offset:1024
	global_load_dwordx4 v[144:147], v0, s[16:17] offset:2048
	global_load_dwordx4 v[148:151], v0, s[16:17] offset:3072
	s_ashr_i32 s11, s10, 31
	s_lshl_b64 s[10:11], s[10:11], 11
	v_lshl_add_u64 v[42:43], v[72:73], 0, s[10:11]
	s_waitcnt vmcnt(0)
	v_pk_add_f32 v[138:139], v[138:139], 1.0 op_sel_hi:[1,0]
	v_pk_add_f32 v[136:137], v[136:137], 1.0 op_sel_hi:[1,0]
	v_pk_fma_f32 v[32:33], v[32:33], v[138:139], v[122:123]
	v_pk_fma_f32 v[30:31], v[30:31], v[136:137], v[120:121]
	s_nop 0
	v_cvt_pk_bf16_f32 v30, v30, v31
	v_cvt_pk_bf16_f32 v31, v32, v33
	global_store_dwordx2 v[42:43], v[30:31], off sc1
	v_pk_add_f32 v[142:143], v[142:143], 1.0 op_sel_hi:[1,0]
	v_pk_add_f32 v[140:141], v[140:141], 1.0 op_sel_hi:[1,0]
	v_pk_fma_f32 v[28:29], v[28:29], v[142:143], v[126:127]
	v_pk_fma_f32 v[26:27], v[26:27], v[140:141], v[124:125]
	s_nop 0
	v_cvt_pk_bf16_f32 v26, v26, v27
	v_cvt_pk_bf16_f32 v27, v28, v29
	global_store_dwordx2 v[42:43], v[26:27], off offset:512 sc1
	v_pk_add_f32 v[146:147], v[146:147], 1.0 op_sel_hi:[1,0]
	v_pk_add_f32 v[144:145], v[144:145], 1.0 op_sel_hi:[1,0]
	v_pk_fma_f32 v[20:21], v[20:21], v[146:147], v[130:131]
	v_pk_fma_f32 v[18:19], v[18:19], v[144:145], v[128:129]
	s_nop 0
	v_cvt_pk_bf16_f32 v18, v18, v19
	v_cvt_pk_bf16_f32 v19, v20, v21
	global_store_dwordx2 v[42:43], v[18:19], off offset:1024 sc1
	v_pk_add_f32 v[150:151], v[150:151], 1.0 op_sel_hi:[1,0]
	v_pk_add_f32 v[148:149], v[148:149], 1.0 op_sel_hi:[1,0]
	v_pk_fma_f32 v[24:25], v[24:25], v[150:151], v[134:135]
	v_pk_fma_f32 v[22:23], v[22:23], v[148:149], v[132:133]
	s_nop 0
	v_cvt_pk_bf16_f32 v22, v22, v23
	v_cvt_pk_bf16_f32 v23, v24, v25
	global_store_dwordx2 v[42:43], v[22:23], off offset:1536 sc1
	s_andn2_b64 vcc, exec, s[8:9]
	s_cbranch_vccnz .LBB0_162
	s_mul_i32 s0, s12, 3
	s_and_b64 vcc, exec, s[38:39]
	s_add_i32 s8, s0, s46
	s_cbranch_vccnz .LBB0_161
	v_mov_b32_e32 v18, v15
	v_mov_b32_e32 v19, v16
	v_mov_b32_e32 v20, v14
	v_mov_b32_e32 v21, v17
	v_pk_add_f32 v[18:19], v[18:19], v[20:21]
	v_mov_b32_e32 v20, v11
	v_mov_b32_e32 v21, v12
	v_mov_b32_e32 v22, v10
	v_mov_b32_e32 v23, v13
	v_pk_add_f32 v[20:21], v[20:21], v[22:23]
	v_add_f32_e32 v18, v18, v19
	v_pk_add_f32 v[20:21], v[20:21], v[20:21] op_sel:[0,1] op_sel_hi:[1,0]
	v_add_f32_e32 v18, 0, v18
	v_add_f32_e32 v22, v2, v3
	v_add_f32_e32 v24, v4, v5
	v_mov_b32_e32 v19, v6
	v_mov_b32_e32 v21, v7
	v_mov_b32_e32 v23, v8
	v_mov_b32_e32 v25, v9
	v_pk_add_f32 v[18:19], v[18:19], v[20:21]
	v_pk_add_f32 v[20:21], v[22:23], v[24:25]
	s_nop 0
	v_pk_add_f32 v[18:19], v[18:19], v[20:21]
	v_add_f32_e32 v18, v18, v19
	v_mov_b32_e32 v19, v18
	s_nop 1
	v_add_f32_dpp v19, v19, v19 quad_perm:[1,0,3,2] row_mask:0xf bank_mask:0xf
	s_nop 1
	v_add_f32_dpp v19, v19, v19 quad_perm:[2,3,0,1] row_mask:0xf bank_mask:0xf
	s_nop 1
	v_add_f32_dpp v19, v19, v19 row_half_mirror row_mask:0xf bank_mask:0xf
	s_nop 1
	v_add_f32_dpp v19, v19, v19 row_mirror row_mask:0xf bank_mask:0xf
	s_nop 1
	v_add_f32_dpp v19, v19, v19 row_bcast:15 row_mask:0xa bank_mask:0xf
	s_nop 1
	v_add_f32_dpp v19, v19, v19 row_bcast:31 row_mask:0xc bank_mask:0xf
	s_nop 1
	v_readlane_b32 vcc_lo, v19, 63
	s_nop 1
	v_mov_b32_e32 v19, vcc_lo
	v_fmamk_f32 v17, v19, 0xba800000, v17
	v_fmamk_f32 v15, v19, 0xba800000, v15
	v_fmamk_f32 v16, v19, 0xba800000, v16
	v_fmac_f32_e32 v14, 0xba800000, v19
	v_mul_f32_e32 v18, v15, v15
	v_mul_f32_e32 v26, v17, v17
	v_fmac_f32_e32 v18, v14, v14
	v_fmac_f32_e32 v26, v16, v16
	v_fmamk_f32 v13, v19, 0xba800000, v13
	v_fmamk_f32 v11, v19, 0xba800000, v11
	v_add_f32_e32 v18, v18, v26
	v_fmamk_f32 v12, v19, 0xba800000, v12
	v_fmac_f32_e32 v10, 0xba800000, v19
	v_mul_f32_e32 v26, v11, v11
	v_mul_f32_e32 v27, v13, v13
	v_fmac_f32_e32 v26, v10, v10
	v_fmac_f32_e32 v27, v12, v12
	v_add_f32_e32 v26, v26, v27
	v_fmamk_f32 v5, v19, 0xba800000, v5
	v_fmamk_f32 v3, v19, 0xba800000, v3
	v_add_f32_e32 v18, v18, v26
	v_fmamk_f32 v4, v19, 0xba800000, v4
	v_fmac_f32_e32 v2, 0xba800000, v19
	v_mul_f32_e32 v26, v3, v3
	v_mul_f32_e32 v27, v5, v5
	v_fmac_f32_e32 v26, v2, v2
	v_fmac_f32_e32 v27, v4, v4
	v_add_f32_e32 v26, v26, v27
	v_fmamk_f32 v9, v19, 0xba800000, v9
	v_fmamk_f32 v7, v19, 0xba800000, v7
	v_add_f32_e32 v18, v18, v26
	v_fmamk_f32 v8, v19, 0xba800000, v8
	v_fmac_f32_e32 v6, 0xba800000, v19
	v_mul_f32_e32 v26, v7, v7
	v_mul_f32_e32 v27, v9, v9
	v_fmac_f32_e32 v26, v6, v6
	v_fmac_f32_e32 v27, v8, v8
	v_add_f32_e32 v26, v26, v27
	v_add_f32_e32 v18, v18, v26
	s_nop 1
	v_add_f32_dpp v18, v18, v18 quad_perm:[1,0,3,2] row_mask:0xf bank_mask:0xf
	s_nop 1
	v_add_f32_dpp v18, v18, v18 quad_perm:[2,3,0,1] row_mask:0xf bank_mask:0xf
	s_nop 1
	v_add_f32_dpp v18, v18, v18 row_half_mirror row_mask:0xf bank_mask:0xf
	s_nop 1
	v_add_f32_dpp v18, v18, v18 row_mirror row_mask:0xf bank_mask:0xf
	s_nop 1
	v_add_f32_dpp v18, v18, v18 row_bcast:15 row_mask:0xa bank_mask:0xf
	s_nop 1
	v_add_f32_dpp v18, v18, v18 row_bcast:31 row_mask:0xc bank_mask:0xf
	s_nop 1
	v_readlane_b32 vcc_lo, v18, 63
	s_nop 1
	v_mov_b32_e32 v18, vcc_lo
	v_fmamk_f32 v18, v18, 0x3a800000, v213
	v_mul_f32_e32 v20, 0x4f800000, v18
	v_cmp_gt_f32_e32 vcc, s61, v18
	s_nop 1
	v_cndmask_b32_e32 v18, v18, v20, vcc
	v_sqrt_f32_e32 v20, v18
	s_nop 0
	v_add_u32_e32 v21, -1, v20
	v_fma_f32 v22, -v21, v20, v18
	v_cmp_ge_f32_e64 s[0:1], 0, v22
	v_add_u32_e32 v22, 1, v20
	s_nop 0
	v_cndmask_b32_e64 v21, v20, v21, s[0:1]
	v_fma_f32 v20, -v22, v20, v18
	v_cmp_lt_f32_e64 s[0:1], 0, v20
	s_nop 1
	v_cndmask_b32_e64 v20, v21, v22, s[0:1]
	v_mul_f32_e32 v21, 0x37800000, v20
	v_cndmask_b32_e32 v20, v20, v21, vcc
	v_cmp_class_f32_e32 vcc, v18, v214
	s_nop 1
	v_cndmask_b32_e32 v18, v20, v18, vcc
	v_div_scale_f32 v20, s[0:1], v18, v18, 1.0
	v_rcp_f32_e32 v21, v20
	s_nop 0
	v_fma_f32 v22, -v20, v21, 1.0
	v_fmac_f32_e32 v21, v22, v21
	v_div_scale_f32 v22, vcc, 1.0, v18, 1.0
	v_mul_f32_e32 v23, v22, v21
	v_fma_f32 v24, -v20, v23, v22
	v_fmac_f32_e32 v23, v24, v21
	v_fma_f32 v20, -v20, v23, v22
	v_div_fmas_f32 v20, v20, v21, v23
	v_div_fixup_f32 v18, v20, v18, 1.0
	s_and_saveexec_b64 s[0:1], s[36:37]
	s_cbranch_execz .LBB0_160
	s_ashr_i32 s9, s8, 31
	s_lshl_b64 s[10:11], s[8:9], 3
	v_readlane_b32 s9, v252, 20
	s_add_u32 s10, s9, s10
	v_readlane_b32 s9, v252, 21
	v_mul_f32_e32 v20, 0x3a800000, v19
	s_addc_u32 s11, s9, s11
	v_mov_b32_e32 v21, v18
	global_store_dwordx2 v1, v[20:21], s[10:11] sc1
	s_branch .LBB0_160

.Lpf_1:
	s_andn2_b64 vcc, exec, s[8:9]
	s_mov_b64 s[8:9], -1
	global_store_dwordx4 v[172:173], v[122:125], off sc1
	s_cbranch_vccnz .LBB0_265
	v_mov_b64_e32 v[128:129], v[116:117]
	v_mov_b64_e32 v[124:125], v[120:121]
	s_and_b64 vcc, exec, s[40:41]
	v_mov_b64_e32 v[126:127], v[114:115]
	v_mov_b64_e32 v[122:123], v[118:119]
	s_cbranch_vccnz .LBB0_264
	v_and_b32_e32 v122, 64, v211
	v_xor_b32_e32 v0, 32, v211
	v_add_u32_e32 v122, 64, v122
	v_cmp_lt_i32_e32 vcc, v0, v122
	s_nop 1
	v_cndmask_b32_e32 v0, v211, v0, vcc
	v_lshlrev_b32_e32 v0, 2, v0
	ds_bpermute_b32 v122, v0, v118
	ds_bpermute_b32 v126, v0, v114
	ds_bpermute_b32 v123, v0, v119
	ds_bpermute_b32 v124, v0, v120
	ds_bpermute_b32 v125, v0, v121
	ds_bpermute_b32 v127, v0, v115
	ds_bpermute_b32 v128, v0, v116
	ds_bpermute_b32 v129, v0, v117
	s_waitcnt lgkmcnt(0)
	v_pk_mul_f32 v[122:123], v[178:179], v[122:123]
	v_pk_mul_f32 v[124:125], v[180:181], v[124:125]
	v_pk_mul_f32 v[126:127], v[176:177], v[126:127]
	v_pk_fma_f32 v[124:125], v[120:121], v[136:137], v[124:125]
	v_pk_mul_f32 v[128:129], v[174:175], v[128:129]
	v_pk_fma_f32 v[122:123], v[118:119], v[134:135], v[122:123]
	v_pk_fma_f32 v[128:129], v[116:117], v[132:133], v[128:129]
	v_pk_fma_f32 v[126:127], v[114:115], v[130:131], v[126:127]

.LBB0_267:
	v_pk_mul_f32 v[114:115], v[124:125], s[94:95] op_sel_hi:[1,0]
	v_pk_mul_f32 v[116:117], v[122:123], s[94:95] op_sel_hi:[1,0]
	v_pk_mul_f32 v[118:119], v[128:129], s[94:95] op_sel_hi:[1,0]
	v_pk_mul_f32 v[120:121], v[126:127], s[94:95] op_sel_hi:[1,0]
	v_cndmask_b32_e64 v0, v124, v114, s[42:43]
	v_cndmask_b32_e64 v115, v125, v115, s[42:43]
	v_cndmask_b32_e64 v114, v122, v116, s[42:43]
	v_cndmask_b32_e64 v116, v123, v117, s[42:43]
	v_cndmask_b32_e64 v117, v128, v118, s[42:43]
	v_cndmask_b32_e64 v118, v129, v119, s[42:43]
	v_cndmask_b32_e64 v119, v126, v120, s[42:43]
	s_lshl_b32 s8, s8, 1
	s_mov_b32 s9, s71
	v_cndmask_b32_e64 v120, v127, v121, s[42:43]
	v_cvt_pk_bf16_f32 v114, v114, v116
	v_cvt_pk_bf16_f32 v115, v0, v115
	v_cvt_pk_bf16_f32 v116, v119, v120
	v_cvt_pk_bf16_f32 v117, v117, v118
	v_lshl_add_u64 v[118:119], v[172:173], 0, s[8:9]
	global_store_dwordx4 v[118:119], v[114:117], off sc1
	s_and_b64 vcc, exec, s[44:45]
	s_mov_b64 s[8:9], -1
	v_or_b32_e32 v114, 16, v168
	v_ashrrev_i32_e32 v115, 31, v114
	s_cbranch_vccnz .LBB0_271
	v_lshl_add_u64 v[116:117], v[114:115], 0, s[70:71]
	v_lshlrev_b64 v[116:117], 7, v[116:117]
	v_lshl_add_u64 v[130:131], v[166:167], 0, v[116:117]
	s_cbranch_execz .LBB0_272

.Lpf_2:
	s_and_b64 vcc, exec, s[44:45]
	s_mov_b64 s[8:9], -1
	global_store_dwordx4 v[130:131], v[106:109], off sc1
	s_cbranch_vccnz .LBB0_283
	v_mov_b64_e32 v[112:113], v[100:101]
	v_mov_b64_e32 v[108:109], v[104:105]
	s_and_b64 vcc, exec, s[40:41]
	v_mov_b64_e32 v[110:111], v[98:99]
	v_mov_b64_e32 v[106:107], v[102:103]
	s_cbranch_vccnz .LBB0_282
	v_and_b32_e32 v106, 64, v211
	v_xor_b32_e32 v0, 32, v211
	v_add_u32_e32 v106, 64, v106
	v_cmp_lt_i32_e32 vcc, v0, v106
	s_nop 1
	v_cndmask_b32_e32 v0, v211, v0, vcc
	v_lshlrev_b32_e32 v0, 2, v0
	ds_bpermute_b32 v106, v0, v102
	ds_bpermute_b32 v110, v0, v98
	ds_bpermute_b32 v107, v0, v103
	ds_bpermute_b32 v108, v0, v104
	ds_bpermute_b32 v109, v0, v105
	ds_bpermute_b32 v111, v0, v99
	ds_bpermute_b32 v112, v0, v100
	ds_bpermute_b32 v113, v0, v101
	s_waitcnt lgkmcnt(0)
	v_pk_mul_f32 v[106:107], v[136:137], v[106:107]
	v_pk_mul_f32 v[108:109], v[138:139], v[108:109]
	v_pk_mul_f32 v[110:111], v[134:135], v[110:111]
	v_pk_fma_f32 v[108:109], v[104:105], v[120:121], v[108:109]
	v_pk_mul_f32 v[112:113], v[132:133], v[112:113]
	v_pk_fma_f32 v[106:107], v[102:103], v[118:119], v[106:107]
	v_pk_fma_f32 v[112:113], v[100:101], v[116:117], v[112:113]
	v_pk_fma_f32 v[110:111], v[98:99], v[114:115], v[110:111]

.LBB0_285:
	v_pk_mul_f32 v[98:99], v[108:109], s[94:95] op_sel_hi:[1,0]
	v_pk_mul_f32 v[100:101], v[106:107], s[94:95] op_sel_hi:[1,0]
	v_pk_mul_f32 v[102:103], v[112:113], s[94:95] op_sel_hi:[1,0]
	v_pk_mul_f32 v[104:105], v[110:111], s[94:95] op_sel_hi:[1,0]
	v_cndmask_b32_e64 v0, v108, v98, s[42:43]
	v_cndmask_b32_e64 v99, v109, v99, s[42:43]
	v_cndmask_b32_e64 v98, v106, v100, s[42:43]
	v_cndmask_b32_e64 v100, v107, v101, s[42:43]
	v_cndmask_b32_e64 v101, v112, v102, s[42:43]
	v_cndmask_b32_e64 v102, v113, v103, s[42:43]
	v_cndmask_b32_e64 v103, v110, v104, s[42:43]
	s_lshl_b32 s8, s8, 1
	s_mov_b32 s9, s71
	v_cndmask_b32_e64 v104, v111, v105, s[42:43]
	v_cvt_pk_bf16_f32 v98, v98, v100
	v_cvt_pk_bf16_f32 v99, v0, v99
	v_cvt_pk_bf16_f32 v100, v103, v104
	v_cvt_pk_bf16_f32 v101, v101, v102
	v_lshl_add_u64 v[102:103], v[130:131], 0, s[8:9]
	global_store_dwordx4 v[102:103], v[98:101], off sc1
	s_and_b64 vcc, exec, s[44:45]
	s_mov_b64 s[8:9], -1
	v_or_b32_e32 v98, 32, v168
	v_ashrrev_i32_e32 v99, 31, v98
	s_cbranch_vccnz .LBB0_289
	v_lshl_add_u64 v[100:101], v[98:99], 0, s[70:71]
	v_lshlrev_b64 v[100:101], 7, v[100:101]
	v_lshl_add_u64 v[114:115], v[166:167], 0, v[100:101]
	s_cbranch_execz .LBB0_290

.Lpf_3:
	s_and_b64 vcc, exec, s[44:45]
	s_mov_b64 s[8:9], -1
	global_store_dwordx4 v[114:115], v[90:93], off sc1
	s_cbranch_vccnz .LBB0_301
	v_mov_b64_e32 v[96:97], v[84:85]
	v_mov_b64_e32 v[92:93], v[88:89]
	s_and_b64 vcc, exec, s[40:41]
	v_mov_b64_e32 v[94:95], v[82:83]
	v_mov_b64_e32 v[90:91], v[86:87]
	s_cbranch_vccnz .LBB0_300
	v_and_b32_e32 v90, 64, v211
	v_xor_b32_e32 v0, 32, v211
	v_add_u32_e32 v90, 64, v90
	v_cmp_lt_i32_e32 vcc, v0, v90
	s_nop 1
	v_cndmask_b32_e32 v0, v211, v0, vcc
	v_lshlrev_b32_e32 v0, 2, v0
	ds_bpermute_b32 v90, v0, v86
	ds_bpermute_b32 v94, v0, v82
	ds_bpermute_b32 v91, v0, v87
	ds_bpermute_b32 v92, v0, v88
	ds_bpermute_b32 v93, v0, v89
	ds_bpermute_b32 v95, v0, v83
	ds_bpermute_b32 v96, v0, v84
	ds_bpermute_b32 v97, v0, v85
	s_waitcnt lgkmcnt(0)
	v_pk_mul_f32 v[90:91], v[120:121], v[90:91]
	v_pk_mul_f32 v[92:93], v[122:123], v[92:93]
	v_pk_mul_f32 v[94:95], v[118:119], v[94:95]
	v_pk_fma_f32 v[92:93], v[88:89], v[104:105], v[92:93]
	v_pk_mul_f32 v[96:97], v[116:117], v[96:97]
	v_pk_fma_f32 v[90:91], v[86:87], v[102:103], v[90:91]
	v_pk_fma_f32 v[96:97], v[84:85], v[100:101], v[96:97]
	v_pk_fma_f32 v[94:95], v[82:83], v[98:99], v[94:95]

.LBB0_303:
	v_pk_mul_f32 v[82:83], v[92:93], s[94:95] op_sel_hi:[1,0]
	v_pk_mul_f32 v[84:85], v[90:91], s[94:95] op_sel_hi:[1,0]
	v_pk_mul_f32 v[86:87], v[96:97], s[94:95] op_sel_hi:[1,0]
	v_pk_mul_f32 v[88:89], v[94:95], s[94:95] op_sel_hi:[1,0]
	v_cndmask_b32_e64 v0, v92, v82, s[42:43]
	v_cndmask_b32_e64 v83, v93, v83, s[42:43]
	v_cndmask_b32_e64 v82, v90, v84, s[42:43]
	v_cndmask_b32_e64 v84, v91, v85, s[42:43]
	v_cndmask_b32_e64 v85, v96, v86, s[42:43]
	v_cndmask_b32_e64 v86, v97, v87, s[42:43]
	v_cndmask_b32_e64 v87, v94, v88, s[42:43]
	s_lshl_b32 s8, s8, 1
	s_mov_b32 s9, s71
	v_cndmask_b32_e64 v88, v95, v89, s[42:43]
	v_cvt_pk_bf16_f32 v82, v82, v84
	v_cvt_pk_bf16_f32 v83, v0, v83
	v_cvt_pk_bf16_f32 v84, v87, v88
	v_cvt_pk_bf16_f32 v85, v85, v86
	v_lshl_add_u64 v[86:87], v[114:115], 0, s[8:9]
	global_store_dwordx4 v[86:87], v[82:85], off sc1
	s_and_b64 vcc, exec, s[44:45]
	s_mov_b64 s[8:9], -1
	v_or_b32_e32 v82, 48, v168
	v_ashrrev_i32_e32 v83, 31, v82
	s_cbranch_vccnz .LBB0_307
	v_lshl_add_u64 v[84:85], v[82:83], 0, s[70:71]
	v_lshlrev_b64 v[84:85], 7, v[84:85]
	v_lshl_add_u64 v[98:99], v[166:167], 0, v[84:85]
	s_cbranch_execz .LBB0_308

.Lpf_4:
	s_and_b64 vcc, exec, s[44:45]
	s_mov_b64 s[8:9], -1
	global_store_dwordx4 v[98:99], v[74:77], off sc1
	s_cbranch_vccnz .LBB0_319
	v_mov_b64_e32 v[80:81], v[68:69]
	v_mov_b64_e32 v[76:77], v[72:73]
	s_and_b64 vcc, exec, s[40:41]
	v_mov_b64_e32 v[78:79], v[66:67]
	v_mov_b64_e32 v[74:75], v[70:71]
	s_cbranch_vccnz .LBB0_318
	v_and_b32_e32 v74, 64, v211
	v_xor_b32_e32 v0, 32, v211
	v_add_u32_e32 v74, 64, v74
	v_cmp_lt_i32_e32 vcc, v0, v74
	s_nop 1
	v_cndmask_b32_e32 v0, v211, v0, vcc
	v_lshlrev_b32_e32 v0, 2, v0
	ds_bpermute_b32 v74, v0, v70
	ds_bpermute_b32 v78, v0, v66
	ds_bpermute_b32 v75, v0, v71
	ds_bpermute_b32 v76, v0, v72
	ds_bpermute_b32 v77, v0, v73
	ds_bpermute_b32 v79, v0, v67
	ds_bpermute_b32 v80, v0, v68
	ds_bpermute_b32 v81, v0, v69
	s_waitcnt lgkmcnt(0)
	v_pk_mul_f32 v[74:75], v[104:105], v[74:75]
	v_pk_mul_f32 v[76:77], v[106:107], v[76:77]
	v_pk_mul_f32 v[78:79], v[102:103], v[78:79]
	v_pk_fma_f32 v[76:77], v[72:73], v[88:89], v[76:77]
	v_pk_mul_f32 v[80:81], v[100:101], v[80:81]
	v_pk_fma_f32 v[74:75], v[70:71], v[86:87], v[74:75]
	v_pk_fma_f32 v[80:81], v[68:69], v[84:85], v[80:81]
	v_pk_fma_f32 v[78:79], v[66:67], v[82:83], v[78:79]

.LBB0_321:
	v_pk_mul_f32 v[66:67], v[76:77], s[94:95] op_sel_hi:[1,0]
	v_pk_mul_f32 v[68:69], v[74:75], s[94:95] op_sel_hi:[1,0]
	v_pk_mul_f32 v[70:71], v[80:81], s[94:95] op_sel_hi:[1,0]
	v_pk_mul_f32 v[72:73], v[78:79], s[94:95] op_sel_hi:[1,0]
	v_cndmask_b32_e64 v0, v76, v66, s[42:43]
	v_cndmask_b32_e64 v67, v77, v67, s[42:43]
	v_cndmask_b32_e64 v66, v74, v68, s[42:43]
	v_cndmask_b32_e64 v68, v75, v69, s[42:43]
	v_cndmask_b32_e64 v69, v80, v70, s[42:43]
	v_cndmask_b32_e64 v70, v81, v71, s[42:43]
	v_cndmask_b32_e64 v71, v78, v72, s[42:43]
	s_lshl_b32 s8, s8, 1
	s_mov_b32 s9, s71
	v_cndmask_b32_e64 v72, v79, v73, s[42:43]
	v_cvt_pk_bf16_f32 v66, v66, v68
	v_cvt_pk_bf16_f32 v67, v0, v67
	v_cvt_pk_bf16_f32 v68, v71, v72
	v_cvt_pk_bf16_f32 v69, v69, v70
	v_lshl_add_u64 v[70:71], v[98:99], 0, s[8:9]
	global_store_dwordx4 v[70:71], v[66:69], off sc1
	s_and_b64 vcc, exec, s[44:45]
	s_mov_b64 s[8:9], -1
	v_add_u32_e32 v66, 0x80, v168
	v_ashrrev_i32_e32 v67, 31, v66
	s_cbranch_vccnz .LBB0_325
	v_lshl_add_u64 v[68:69], v[66:67], 0, s[70:71]
	v_lshlrev_b64 v[68:69], 7, v[68:69]
	v_lshl_add_u64 v[82:83], v[166:167], 0, v[68:69]
	s_cbranch_execz .LBB0_326

.Lpf_5:
	s_and_b64 vcc, exec, s[44:45]
	s_mov_b64 s[8:9], -1
	global_store_dwordx4 v[82:83], v[58:61], off sc1
	s_cbranch_vccnz .LBB0_337
	v_mov_b64_e32 v[64:65], v[52:53]
	v_mov_b64_e32 v[60:61], v[56:57]
	s_and_b64 vcc, exec, s[40:41]
	v_mov_b64_e32 v[62:63], v[50:51]
	v_mov_b64_e32 v[58:59], v[54:55]
	s_cbranch_vccnz .LBB0_336
	v_and_b32_e32 v58, 64, v211
	v_xor_b32_e32 v0, 32, v211
	v_add_u32_e32 v58, 64, v58
	v_cmp_lt_i32_e32 vcc, v0, v58
	s_nop 1
	v_cndmask_b32_e32 v0, v211, v0, vcc
	v_lshlrev_b32_e32 v0, 2, v0
	ds_bpermute_b32 v58, v0, v54
	ds_bpermute_b32 v62, v0, v50
	ds_bpermute_b32 v59, v0, v55
	ds_bpermute_b32 v60, v0, v56
	ds_bpermute_b32 v61, v0, v57
	ds_bpermute_b32 v63, v0, v51
	ds_bpermute_b32 v64, v0, v52
	ds_bpermute_b32 v65, v0, v53
	s_waitcnt lgkmcnt(0)
	v_pk_mul_f32 v[58:59], v[88:89], v[58:59]
	v_pk_mul_f32 v[60:61], v[90:91], v[60:61]
	v_pk_mul_f32 v[62:63], v[86:87], v[62:63]
	v_pk_fma_f32 v[60:61], v[56:57], v[72:73], v[60:61]
	v_pk_mul_f32 v[64:65], v[84:85], v[64:65]
	v_pk_fma_f32 v[58:59], v[54:55], v[70:71], v[58:59]
	v_pk_fma_f32 v[64:65], v[52:53], v[68:69], v[64:65]
	v_pk_fma_f32 v[62:63], v[50:51], v[66:67], v[62:63]

.LBB0_339:
	v_pk_mul_f32 v[50:51], v[60:61], s[94:95] op_sel_hi:[1,0]
	v_pk_mul_f32 v[52:53], v[58:59], s[94:95] op_sel_hi:[1,0]
	v_pk_mul_f32 v[54:55], v[64:65], s[94:95] op_sel_hi:[1,0]
	v_pk_mul_f32 v[56:57], v[62:63], s[94:95] op_sel_hi:[1,0]
	v_cndmask_b32_e64 v0, v60, v50, s[42:43]
	v_cndmask_b32_e64 v51, v61, v51, s[42:43]
	v_cndmask_b32_e64 v50, v58, v52, s[42:43]
	v_cndmask_b32_e64 v52, v59, v53, s[42:43]
	v_cndmask_b32_e64 v53, v64, v54, s[42:43]
	v_cndmask_b32_e64 v54, v65, v55, s[42:43]
	v_cndmask_b32_e64 v55, v62, v56, s[42:43]
	s_lshl_b32 s8, s8, 1
	s_mov_b32 s9, s71
	v_cndmask_b32_e64 v56, v63, v57, s[42:43]
	v_cvt_pk_bf16_f32 v50, v50, v52
	v_cvt_pk_bf16_f32 v51, v0, v51
	v_cvt_pk_bf16_f32 v52, v55, v56
	v_cvt_pk_bf16_f32 v53, v53, v54
	v_lshl_add_u64 v[54:55], v[82:83], 0, s[8:9]
	global_store_dwordx4 v[54:55], v[50:53], off sc1
	s_and_b64 vcc, exec, s[44:45]
	s_mov_b64 s[8:9], -1
	v_add_u32_e32 v50, 0x90, v168
	v_ashrrev_i32_e32 v51, 31, v50
	s_cbranch_vccnz .LBB0_343
	v_lshl_add_u64 v[52:53], v[50:51], 0, s[70:71]
	v_lshlrev_b64 v[52:53], 7, v[52:53]
	v_lshl_add_u64 v[66:67], v[166:167], 0, v[52:53]
	s_cbranch_execz .LBB0_344

.Lpf_6:
	s_and_b64 vcc, exec, s[44:45]
	s_mov_b64 s[8:9], -1
	global_store_dwordx4 v[66:67], v[42:45], off sc1
	s_cbranch_vccnz .LBB0_355
	v_mov_b64_e32 v[48:49], v[36:37]
	v_mov_b64_e32 v[44:45], v[40:41]
	s_and_b64 vcc, exec, s[40:41]
	v_mov_b64_e32 v[46:47], v[34:35]
	v_mov_b64_e32 v[42:43], v[38:39]
	s_cbranch_vccnz .LBB0_354
	v_and_b32_e32 v42, 64, v211
	v_xor_b32_e32 v0, 32, v211
	v_add_u32_e32 v42, 64, v42
	v_cmp_lt_i32_e32 vcc, v0, v42
	s_nop 1
	v_cndmask_b32_e32 v0, v211, v0, vcc
	v_lshlrev_b32_e32 v0, 2, v0
	ds_bpermute_b32 v42, v0, v38
	ds_bpermute_b32 v46, v0, v34
	ds_bpermute_b32 v43, v0, v39
	ds_bpermute_b32 v44, v0, v40
	ds_bpermute_b32 v45, v0, v41
	ds_bpermute_b32 v47, v0, v35
	ds_bpermute_b32 v48, v0, v36
	ds_bpermute_b32 v49, v0, v37
	s_waitcnt lgkmcnt(0)
	v_pk_mul_f32 v[42:43], v[72:73], v[42:43]
	v_pk_mul_f32 v[44:45], v[74:75], v[44:45]
	v_pk_mul_f32 v[46:47], v[70:71], v[46:47]
	v_pk_fma_f32 v[44:45], v[40:41], v[56:57], v[44:45]
	v_pk_mul_f32 v[48:49], v[68:69], v[48:49]
	v_pk_fma_f32 v[42:43], v[38:39], v[54:55], v[42:43]
	v_pk_fma_f32 v[48:49], v[36:37], v[52:53], v[48:49]
	v_pk_fma_f32 v[46:47], v[34:35], v[50:51], v[46:47]

.LBB0_357:
	v_pk_mul_f32 v[34:35], v[44:45], s[94:95] op_sel_hi:[1,0]
	v_pk_mul_f32 v[36:37], v[42:43], s[94:95] op_sel_hi:[1,0]
	v_pk_mul_f32 v[38:39], v[48:49], s[94:95] op_sel_hi:[1,0]
	v_pk_mul_f32 v[40:41], v[46:47], s[94:95] op_sel_hi:[1,0]
	v_cndmask_b32_e64 v0, v44, v34, s[42:43]
	v_cndmask_b32_e64 v35, v45, v35, s[42:43]
	v_cndmask_b32_e64 v34, v42, v36, s[42:43]
	v_cndmask_b32_e64 v36, v43, v37, s[42:43]
	v_cndmask_b32_e64 v37, v48, v38, s[42:43]
	v_cndmask_b32_e64 v38, v49, v39, s[42:43]
	v_cndmask_b32_e64 v39, v46, v40, s[42:43]
	s_lshl_b32 s8, s8, 1
	s_mov_b32 s9, s71
	v_cndmask_b32_e64 v40, v47, v41, s[42:43]
	v_cvt_pk_bf16_f32 v34, v34, v36
	v_cvt_pk_bf16_f32 v35, v0, v35
	v_cvt_pk_bf16_f32 v36, v39, v40
	v_cvt_pk_bf16_f32 v37, v37, v38
	v_lshl_add_u64 v[38:39], v[66:67], 0, s[8:9]
	global_store_dwordx4 v[38:39], v[34:37], off sc1
	s_and_b64 vcc, exec, s[44:45]
	s_mov_b64 s[8:9], -1
	v_add_u32_e32 v34, 0xa0, v168
	v_ashrrev_i32_e32 v35, 31, v34
	s_cbranch_vccnz .LBB0_361
	v_lshl_add_u64 v[36:37], v[34:35], 0, s[70:71]
	v_lshlrev_b64 v[36:37], 7, v[36:37]
	v_lshl_add_u64 v[50:51], v[166:167], 0, v[36:37]
	s_cbranch_execz .LBB0_362

.Lpf_7:
	s_and_b64 vcc, exec, s[44:45]
	s_mov_b64 s[8:9], -1
	global_store_dwordx4 v[50:51], v[26:29], off sc1
	s_cbranch_vccnz .LBB0_373
	v_mov_b64_e32 v[32:33], v[20:21]
	v_mov_b64_e32 v[28:29], v[24:25]
	s_and_b64 vcc, exec, s[40:41]
	v_mov_b64_e32 v[30:31], v[18:19]
	v_mov_b64_e32 v[26:27], v[22:23]
	s_cbranch_vccnz .LBB0_372
	v_and_b32_e32 v26, 64, v211
	v_xor_b32_e32 v0, 32, v211
	v_add_u32_e32 v26, 64, v26
	v_cmp_lt_i32_e32 vcc, v0, v26
	s_nop 1
	v_cndmask_b32_e32 v0, v211, v0, vcc
	v_lshlrev_b32_e32 v0, 2, v0
	ds_bpermute_b32 v26, v0, v22
	ds_bpermute_b32 v30, v0, v18
	ds_bpermute_b32 v27, v0, v23
	ds_bpermute_b32 v28, v0, v24
	ds_bpermute_b32 v29, v0, v25
	ds_bpermute_b32 v31, v0, v19
	ds_bpermute_b32 v32, v0, v20
	ds_bpermute_b32 v33, v0, v21
	s_waitcnt lgkmcnt(0)
	v_pk_mul_f32 v[26:27], v[56:57], v[26:27]
	v_pk_mul_f32 v[28:29], v[58:59], v[28:29]
	v_pk_mul_f32 v[30:31], v[54:55], v[30:31]
	v_pk_fma_f32 v[28:29], v[24:25], v[40:41], v[28:29]
	v_pk_mul_f32 v[32:33], v[52:53], v[32:33]
	v_pk_fma_f32 v[26:27], v[22:23], v[38:39], v[26:27]
	v_pk_fma_f32 v[32:33], v[20:21], v[36:37], v[32:33]
	v_pk_fma_f32 v[30:31], v[18:19], v[34:35], v[30:31]

.LBB0_375:
	v_pk_mul_f32 v[18:19], v[28:29], s[94:95] op_sel_hi:[1,0]
	v_pk_mul_f32 v[20:21], v[26:27], s[94:95] op_sel_hi:[1,0]
	v_pk_mul_f32 v[22:23], v[32:33], s[94:95] op_sel_hi:[1,0]
	v_pk_mul_f32 v[24:25], v[30:31], s[94:95] op_sel_hi:[1,0]
	v_cndmask_b32_e64 v0, v28, v18, s[42:43]
	v_cndmask_b32_e64 v19, v29, v19, s[42:43]
	v_cndmask_b32_e64 v18, v26, v20, s[42:43]
	v_cndmask_b32_e64 v20, v27, v21, s[42:43]
	v_cndmask_b32_e64 v21, v32, v22, s[42:43]
	v_cndmask_b32_e64 v22, v33, v23, s[42:43]
	v_cndmask_b32_e64 v23, v30, v24, s[42:43]
	s_lshl_b32 s8, s8, 1
	s_mov_b32 s9, s71
	v_cndmask_b32_e64 v24, v31, v25, s[42:43]
	v_cvt_pk_bf16_f32 v18, v18, v20
	v_cvt_pk_bf16_f32 v19, v0, v19
	v_cvt_pk_bf16_f32 v20, v23, v24
	v_cvt_pk_bf16_f32 v21, v21, v22
	v_lshl_add_u64 v[22:23], v[50:51], 0, s[8:9]
	global_store_dwordx4 v[22:23], v[18:21], off sc1
	s_and_b64 vcc, exec, s[44:45]
	s_mov_b64 s[8:9], -1
	v_add_u32_e32 v18, 0xb0, v168
	v_ashrrev_i32_e32 v19, 31, v18
	s_cbranch_vccnz .LBB0_379
	v_lshl_add_u64 v[20:21], v[18:19], 0, s[70:71]
	v_lshlrev_b64 v[20:21], 7, v[20:21]
	v_lshl_add_u64 v[34:35], v[166:167], 0, v[20:21]
	s_cbranch_execz .LBB0_380

.LBB0_387:
	v_pk_mul_f32 v[10:11], v[28:29], s[94:95] op_sel_hi:[1,0]
	v_pk_mul_f32 v[12:13], v[26:27], s[94:95] op_sel_hi:[1,0]
	v_pk_mul_f32 v[14:15], v[32:33], s[94:95] op_sel_hi:[1,0]
	v_pk_mul_f32 v[16:17], v[30:31], s[94:95] op_sel_hi:[1,0]
	v_cndmask_b32_e64 v0, v28, v10, s[42:43]
	v_cndmask_b32_e64 v11, v29, v11, s[42:43]
	v_cndmask_b32_e64 v10, v26, v12, s[42:43]
	v_cndmask_b32_e64 v12, v27, v13, s[42:43]
	v_cndmask_b32_e64 v13, v32, v14, s[42:43]
	v_cndmask_b32_e64 v14, v33, v15, s[42:43]
	v_cndmask_b32_e64 v15, v30, v16, s[42:43]
	v_cndmask_b32_e64 v16, v31, v17, s[42:43]
	v_cvt_pk_bf16_f32 v10, v10, v12
	v_cvt_pk_bf16_f32 v11, v0, v11
	v_cvt_pk_bf16_f32 v12, v15, v16
	v_cvt_pk_bf16_f32 v13, v13, v14
	s_and_b64 vcc, exec, s[44:45]
	s_mov_b64 s[8:9], -1
	global_store_dwordx4 v[34:35], v[10:13], off sc1
	s_cbranch_vccnz .LBB0_391
	v_mov_b64_e32 v[16:17], v[4:5]
	v_mov_b64_e32 v[12:13], v[8:9]
	s_and_b64 vcc, exec, s[40:41]
	v_mov_b64_e32 v[14:15], v[2:3]
	v_mov_b64_e32 v[10:11], v[6:7]
	s_cbranch_vccnz .LBB0_390
	v_and_b32_e32 v10, 64, v211
	v_xor_b32_e32 v0, 32, v211
	v_add_u32_e32 v10, 64, v10
	v_cmp_lt_i32_e32 vcc, v0, v10
	s_nop 1
	v_cndmask_b32_e32 v0, v211, v0, vcc
	v_lshlrev_b32_e32 v0, 2, v0
	ds_bpermute_b32 v10, v0, v6
	ds_bpermute_b32 v14, v0, v2
	ds_bpermute_b32 v11, v0, v7
	ds_bpermute_b32 v12, v0, v8
	ds_bpermute_b32 v13, v0, v9
	ds_bpermute_b32 v15, v0, v3
	ds_bpermute_b32 v16, v0, v4
	ds_bpermute_b32 v17, v0, v5
	s_waitcnt lgkmcnt(0)
	v_pk_mul_f32 v[10:11], v[40:41], v[10:11]
	v_pk_mul_f32 v[12:13], v[42:43], v[12:13]
	v_pk_mul_f32 v[14:15], v[38:39], v[14:15]
	v_pk_fma_f32 v[12:13], v[8:9], v[24:25], v[12:13]
	v_pk_mul_f32 v[16:17], v[36:37], v[16:17]
	v_pk_fma_f32 v[10:11], v[6:7], v[22:23], v[10:11]
	v_pk_fma_f32 v[16:17], v[4:5], v[20:21], v[16:17]
	v_pk_fma_f32 v[14:15], v[2:3], v[18:19], v[14:15]

.LBB0_393:
	v_pk_mul_f32 v[2:3], v[12:13], s[94:95] op_sel_hi:[1,0]
	v_pk_mul_f32 v[4:5], v[10:11], s[94:95] op_sel_hi:[1,0]
	v_pk_mul_f32 v[6:7], v[16:17], s[94:95] op_sel_hi:[1,0]
	v_pk_mul_f32 v[8:9], v[14:15], s[94:95] op_sel_hi:[1,0]
	v_cndmask_b32_e64 v0, v12, v2, s[42:43]
	v_cndmask_b32_e64 v3, v13, v3, s[42:43]
	v_cndmask_b32_e64 v2, v10, v4, s[42:43]
	v_cndmask_b32_e64 v4, v11, v5, s[42:43]
	v_cndmask_b32_e64 v5, v16, v6, s[42:43]
	v_cndmask_b32_e64 v6, v17, v7, s[42:43]
	v_cndmask_b32_e64 v7, v14, v8, s[42:43]
	s_lshl_b32 s70, s8, 1
	v_cndmask_b32_e64 v8, v15, v9, s[42:43]
	v_cvt_pk_bf16_f32 v2, v2, v4
	v_cvt_pk_bf16_f32 v3, v0, v3
	v_cvt_pk_bf16_f32 v4, v7, v8
	v_cvt_pk_bf16_f32 v5, v5, v6
	v_lshl_add_u64 v[6:7], v[34:35], 0, s[70:71]
	s_andn2_b64 vcc, exec, s[38:39]
	s_mov_b64 s[8:9], -1
	global_store_dwordx4 v[6:7], v[2:5], off sc1
	s_cbranch_vccnz .LBB0_242
	s_andn2_b64 vcc, exec, s[62:63]
	s_cbranch_vccnz .LBB0_241
	s_barrier
	s_branch .LBB0_241

.LBB0_468:
	v_readlane_b32 s4, v253, 54
	v_readlane_b32 s5, v253, 55
	s_andn2_b64 vcc, exec, s[4:5]
	s_waitcnt lgkmcnt(0)
	s_barrier
	s_cbranch_vccnz .LBB0_455
	ds_read2st64_b32 v[4:5], v2 offset1:1
	ds_read2st64_b32 v[6:7], v2 offset0:2 offset1:3
	ds_read2st64_b32 v[8:9], v2 offset0:4 offset1:5
	ds_read2st64_b32 v[10:11], v2 offset0:6 offset1:7
	ds_read2st64_b32 v[12:13], v2 offset0:8 offset1:9
	ds_read2st64_b32 v[92:93], v2 offset0:10 offset1:11
	ds_read2st64_b32 v[94:95], v2 offset0:12 offset1:13
	ds_read2st64_b32 v[98:99], v2 offset0:14 offset1:15
	ds_read2st64_b32 v[102:103], v2 offset0:16 offset1:17
	ds_read2st64_b32 v[114:115], v2 offset0:18 offset1:19
	ds_read2st64_b32 v[116:117], v2 offset0:20 offset1:21
	ds_read2st64_b32 v[118:119], v2 offset0:22 offset1:23
	ds_read2st64_b32 v[120:121], v2 offset0:24 offset1:25
	ds_read2st64_b32 v[122:123], v2 offset0:26 offset1:27
	ds_read2st64_b32 v[124:125], v2 offset0:28 offset1:29
	ds_read2st64_b32 v[126:127], v2 offset0:30 offset1:31
	ds_read2st64_b32 v[128:129], v2 offset0:32 offset1:33
	ds_read2st64_b32 v[130:131], v2 offset0:34 offset1:35
	ds_read2st64_b32 v[132:133], v2 offset0:36 offset1:37
	ds_read2st64_b32 v[134:135], v2 offset0:38 offset1:39
	ds_read2st64_b32 v[136:137], v2 offset0:40 offset1:41
	ds_read2st64_b32 v[138:139], v2 offset0:42 offset1:43
	ds_read2st64_b32 v[140:141], v2 offset0:44 offset1:45
	ds_read2st64_b32 v[142:143], v2 offset0:46 offset1:47
	ds_read2st64_b32 v[144:145], v2 offset0:56 offset1:57
	ds_read2st64_b32 v[146:147], v2 offset0:58 offset1:59
	ds_read2st64_b32 v[14:15], v2 offset0:60 offset1:61
	ds_read2st64_b32 v[80:81], v2 offset0:62 offset1:63
	ds_read2st64_b32 v[148:149], v2 offset0:48 offset1:49
	ds_read2st64_b32 v[150:151], v2 offset0:50 offset1:51
	ds_read2st64_b32 v[152:153], v2 offset0:52 offset1:53
	ds_read2st64_b32 v[154:155], v2 offset0:54 offset1:55
	s_waitcnt lgkmcnt(14)
	v_pk_fma_f32 v[106:107], v[64:65], v[0:1], v[4:5] op_sel_hi:[1,0,1] neg_lo:[0,0,1] neg_hi:[0,0,1]
	v_lshlrev_b32_e32 v174, 2, v193
	v_pk_fma_f32 v[104:105], v[66:67], v[0:1], v[6:7] op_sel_hi:[1,0,1] neg_lo:[0,0,1] neg_hi:[0,0,1]
	v_pk_mul_f32 v[158:159], v[106:107], v[106:107]
	s_waitcnt lgkmcnt(5)
	v_pk_fma_f32 v[88:89], v[28:29], v[0:1], v[14:15] op_sel_hi:[1,0,1] neg_lo:[0,0,1] neg_hi:[0,0,1]
	s_waitcnt lgkmcnt(4)
	v_pk_fma_f32 v[90:91], v[30:31], v[0:1], v[80:81] op_sel_hi:[1,0,1] neg_lo:[0,0,1] neg_hi:[0,0,1]
	v_pk_mul_f32 v[156:157], v[104:105], v[104:105]
	global_load_dwordx4 v[84:87], v174, s[0:1]
	global_load_dwordx4 v[80:83], v174, s[0:1] offset:32
	v_pk_fma_f32 v[96:97], v[70:71], v[0:1], v[10:11] op_sel_hi:[1,0,1] neg_lo:[0,0,1] neg_hi:[0,0,1]
	v_pk_fma_f32 v[108:109], v[68:69], v[0:1], v[8:9] op_sel_hi:[1,0,1] neg_lo:[0,0,1] neg_hi:[0,0,1]
	v_pk_fma_f32 v[92:93], v[74:75], v[0:1], v[92:93] op_sel_hi:[1,0,1] neg_lo:[0,0,1] neg_hi:[0,0,1]
	v_pk_fma_f32 v[100:101], v[72:73], v[0:1], v[12:13] op_sel_hi:[1,0,1] neg_lo:[0,0,1] neg_hi:[0,0,1]
	v_pk_fma_f32 v[74:75], v[78:79], v[0:1], v[98:99] op_sel_hi:[1,0,1] neg_lo:[0,0,1] neg_hi:[0,0,1]
	v_pk_fma_f32 v[94:95], v[76:77], v[0:1], v[94:95] op_sel_hi:[1,0,1] neg_lo:[0,0,1] neg_hi:[0,0,1]
	v_pk_fma_f32 v[72:73], v[50:51], v[0:1], v[114:115] op_sel_hi:[1,0,1] neg_lo:[0,0,1] neg_hi:[0,0,1]
	v_pk_fma_f32 v[76:77], v[48:49], v[0:1], v[102:103] op_sel_hi:[1,0,1] neg_lo:[0,0,1] neg_hi:[0,0,1]
	v_pk_fma_f32 v[54:55], v[54:55], v[0:1], v[118:119] op_sel_hi:[1,0,1] neg_lo:[0,0,1] neg_hi:[0,0,1]
	v_pk_fma_f32 v[52:53], v[52:53], v[0:1], v[116:117] op_sel_hi:[1,0,1] neg_lo:[0,0,1] neg_hi:[0,0,1]
	v_pk_fma_f32 v[58:59], v[58:59], v[0:1], v[122:123] op_sel_hi:[1,0,1] neg_lo:[0,0,1] neg_hi:[0,0,1]
	v_pk_fma_f32 v[78:79], v[56:57], v[0:1], v[120:121] op_sel_hi:[1,0,1] neg_lo:[0,0,1] neg_hi:[0,0,1]
	v_pk_fma_f32 v[48:49], v[62:63], v[0:1], v[126:127] op_sel_hi:[1,0,1] neg_lo:[0,0,1] neg_hi:[0,0,1]
	v_pk_fma_f32 v[50:51], v[60:61], v[0:1], v[124:125] op_sel_hi:[1,0,1] neg_lo:[0,0,1] neg_hi:[0,0,1]
	v_pk_fma_f32 v[34:35], v[34:35], v[0:1], v[130:131] op_sel_hi:[1,0,1] neg_lo:[0,0,1] neg_hi:[0,0,1]
	v_pk_fma_f32 v[32:33], v[32:33], v[0:1], v[128:129] op_sel_hi:[1,0,1] neg_lo:[0,0,1] neg_hi:[0,0,1]
	v_pk_fma_f32 v[38:39], v[38:39], v[0:1], v[134:135] op_sel_hi:[1,0,1] neg_lo:[0,0,1] neg_hi:[0,0,1]
	v_pk_fma_f32 v[56:57], v[36:37], v[0:1], v[132:133] op_sel_hi:[1,0,1] neg_lo:[0,0,1] neg_hi:[0,0,1]
	v_pk_fma_f32 v[36:37], v[42:43], v[0:1], v[138:139] op_sel_hi:[1,0,1] neg_lo:[0,0,1] neg_hi:[0,0,1]
	v_pk_fma_f32 v[42:43], v[40:41], v[0:1], v[136:137] op_sel_hi:[1,0,1] neg_lo:[0,0,1] neg_hi:[0,0,1]
	v_pk_fma_f32 v[40:41], v[46:47], v[0:1], v[142:143] op_sel_hi:[1,0,1] neg_lo:[0,0,1] neg_hi:[0,0,1]
	v_pk_fma_f32 v[46:47], v[44:45], v[0:1], v[140:141] op_sel_hi:[1,0,1] neg_lo:[0,0,1] neg_hi:[0,0,1]
	s_waitcnt lgkmcnt(2)
	v_pk_fma_f32 v[44:45], v[18:19], v[0:1], v[150:151] op_sel_hi:[1,0,1] neg_lo:[0,0,1] neg_hi:[0,0,1]
	v_pk_fma_f32 v[62:63], v[16:17], v[0:1], v[148:149] op_sel_hi:[1,0,1] neg_lo:[0,0,1] neg_hi:[0,0,1]
	s_waitcnt lgkmcnt(0)
	v_pk_fma_f32 v[60:61], v[22:23], v[0:1], v[154:155] op_sel_hi:[1,0,1] neg_lo:[0,0,1] neg_hi:[0,0,1]
	v_pk_fma_f32 v[98:99], v[20:21], v[0:1], v[152:153] op_sel_hi:[1,0,1] neg_lo:[0,0,1] neg_hi:[0,0,1]
	v_pk_fma_f32 v[26:27], v[26:27], v[0:1], v[146:147] op_sel_hi:[1,0,1] neg_lo:[0,0,1] neg_hi:[0,0,1]
	v_pk_fma_f32 v[102:103], v[24:25], v[0:1], v[144:145] op_sel_hi:[1,0,1] neg_lo:[0,0,1] neg_hi:[0,0,1]
	v_add_f32_e32 v0, v158, v159
	v_add_f32_e32 v0, v0, v156
	v_pk_mul_f32 v[162:163], v[108:109], v[108:109]
	v_add_f32_e32 v0, v0, v157
	v_add_f32_e32 v0, v0, v162
	v_pk_mul_f32 v[160:161], v[96:97], v[96:97]
	v_add_f32_e32 v0, v0, v163
	global_load_dwordx4 v[68:71], v174, s[0:1] offset:64
	global_load_dwordx4 v[64:67], v174, s[0:1] offset:96
	v_add_f32_e32 v0, v0, v160
	v_pk_mul_f32 v[166:167], v[100:101], v[100:101]
	v_add_f32_e32 v0, v0, v161
	v_add_f32_e32 v0, v0, v166
	v_pk_mul_f32 v[164:165], v[92:93], v[92:93]
	v_add_f32_e32 v0, v0, v167
	v_add_f32_e32 v0, v0, v164
	v_pk_mul_f32 v[170:171], v[94:95], v[94:95]
	v_add_f32_e32 v0, v0, v165
	v_add_f32_e32 v0, v0, v170
	v_pk_mul_f32 v[168:169], v[74:75], v[74:75]
	global_load_dwordx4 v[10:13], v174, s[0:1] offset:128
	global_load_dwordx4 v[6:9], v174, s[0:1] offset:160
	v_add_f32_e32 v0, v0, v171
	v_add_f32_e32 v0, v0, v168
	v_pk_mul_f32 v[172:173], v[76:77], v[76:77]
	v_add_f32_e32 v0, v0, v169
	v_add_f32_e32 v0, v0, v172
	v_pk_mul_f32 v[114:115], v[72:73], v[72:73]
	v_add_f32_e32 v0, v0, v173
	v_add_f32_e32 v0, v0, v114
	v_lshlrev_b32_e32 v2, 8, v191
	v_pk_mul_f32 v[116:117], v[52:53], v[52:53]
	v_add_f32_e32 v0, v0, v115
	v_add3_u32 v112, s24, v2, v192
	global_load_dwordx4 v[28:31], v174, s[0:1] offset:192
	global_load_dwordx4 v[2:5], v174, s[0:1] offset:224
	v_add_f32_e32 v0, v0, v116
	v_pk_mul_f32 v[118:119], v[54:55], v[54:55]
	v_add_f32_e32 v0, v0, v117
	v_add_f32_e32 v0, v0, v118
	v_pk_mul_f32 v[120:121], v[78:79], v[78:79]
	v_add_f32_e32 v0, v0, v119
	v_add_f32_e32 v0, v0, v120
	v_pk_mul_f32 v[122:123], v[58:59], v[58:59]
	v_add_f32_e32 v0, v0, v121
	v_add_f32_e32 v0, v0, v122
	v_pk_mul_f32 v[124:125], v[50:51], v[50:51]
	v_add_f32_e32 v0, v0, v123
	v_add_f32_e32 v0, v0, v124
	v_pk_mul_f32 v[126:127], v[48:49], v[48:49]
	v_add_f32_e32 v0, v0, v125
	v_add_f32_e32 v0, v0, v126
	v_pk_mul_f32 v[128:129], v[32:33], v[32:33]
	v_add_f32_e32 v0, v0, v127
	v_add_f32_e32 v0, v0, v128
	v_pk_mul_f32 v[130:131], v[34:35], v[34:35]
	v_add_f32_e32 v0, v0, v129
	v_add_f32_e32 v0, v0, v130
	v_pk_mul_f32 v[132:133], v[56:57], v[56:57]
	v_add_f32_e32 v0, v0, v131
	v_add_f32_e32 v0, v0, v132
	v_pk_mul_f32 v[134:135], v[38:39], v[38:39]
	v_add_f32_e32 v0, v0, v133
	v_add_f32_e32 v0, v0, v134
	v_pk_mul_f32 v[136:137], v[42:43], v[42:43]
	v_add_f32_e32 v0, v0, v135
	v_add_f32_e32 v0, v0, v136
	v_pk_mul_f32 v[138:139], v[36:37], v[36:37]
	v_add_f32_e32 v0, v0, v137
	v_add_f32_e32 v0, v0, v138
	v_pk_mul_f32 v[140:141], v[46:47], v[46:47]
	v_add_f32_e32 v0, v0, v139
	v_add_f32_e32 v0, v0, v140
	v_pk_mul_f32 v[142:143], v[40:41], v[40:41]
	v_add_f32_e32 v0, v0, v141
	v_add_f32_e32 v0, v0, v142
	v_pk_mul_f32 v[16:17], v[62:63], v[62:63]
	v_add_f32_e32 v0, v0, v143
	v_add_f32_e32 v0, v0, v16
	v_pk_mul_f32 v[18:19], v[44:45], v[44:45]
	v_add_f32_e32 v0, v0, v17
	v_add_f32_e32 v0, v0, v18
	v_pk_mul_f32 v[20:21], v[98:99], v[98:99]
	v_add_f32_e32 v0, v0, v19
	v_add_f32_e32 v0, v0, v20
	v_pk_mul_f32 v[22:23], v[60:61], v[60:61]
	v_add_f32_e32 v0, v0, v21
	v_add_f32_e32 v0, v0, v22
	v_pk_mul_f32 v[24:25], v[102:103], v[102:103]
	v_add_f32_e32 v0, v0, v23
	v_add_f32_e32 v0, v0, v24
	v_pk_mul_f32 v[146:147], v[26:27], v[26:27]
	v_add_f32_e32 v0, v0, v25
	v_add_f32_e32 v0, v0, v146
	v_pk_mul_f32 v[14:15], v[88:89], v[88:89]
	v_add_f32_e32 v0, v0, v147
	v_add_f32_e32 v0, v0, v14
	v_pk_mul_f32 v[110:111], v[90:91], v[90:91]
	v_add_f32_e32 v0, v0, v15
	v_add_f32_e32 v0, v0, v110
	v_add_f32_e32 v0, v0, v111
	v_and_b32_e32 v113, 0xf0, v190
	s_movk_i32 s2, 0x50
	ds_bpermute_b32 v110, v184, v0
	v_xad_u32 v180, v113, s2, v112
	s_movk_i32 s2, 0x60
	v_xad_u32 v181, v113, s2, v112
	s_movk_i32 s2, 0x70
	v_xad_u32 v182, v113, s2, v112
	s_movk_i32 s2, 0x80
	v_xad_u32 v183, v113, s2, v112
	s_movk_i32 s2, 0x90
	v_xad_u32 v111, v113, s2, v112
	s_movk_i32 s2, 0xa0
	s_waitcnt lgkmcnt(0)
	v_add_f32_e32 v0, v0, v110
	v_xad_u32 v114, v113, s2, v112
	v_fmamk_f32 v0, v0, 0x3c000000, v213
	s_mov_b32 s2, 0x800000
	v_mul_f32_e32 v110, 0x4b800000, v0
	v_cmp_gt_f32_e32 vcc, s2, v0
	global_load_dwordx4 v[22:25], v174, s[0:1] offset:256
	global_load_dwordx4 v[18:21], v174, s[0:1] offset:288
	v_cndmask_b32_e32 v0, v0, v110, vcc
	v_rsq_f32_e32 v0, v0
	global_load_dwordx4 v[14:17], v174, s[0:1] offset:320
	v_add_u32_e32 v175, v112, v113
	v_xad_u32 v176, v113, 16, v112
	v_mul_f32_e32 v117, 0x45800000, v0
	v_cndmask_b32_e32 v0, v0, v117, vcc
	v_mul_f32_e32 v0, v185, v0
	s_waitcnt vmcnt(10)
	v_pk_mul_f32 v[86:87], v[86:87], v[0:1] op_sel_hi:[1,0]
	v_pk_mul_f32 v[84:85], v[84:85], v[0:1] op_sel_hi:[1,0]
	v_pk_mul_f32 v[86:87], v[104:105], v[86:87]
	v_pk_mul_f32 v[84:85], v[106:107], v[84:85]
	s_waitcnt vmcnt(9)
	v_pk_mul_f32 v[80:81], v[80:81], v[0:1] op_sel_hi:[1,0]
	v_cvt_pk_bf16_f32 v84, v84, v85
	v_cvt_pk_bf16_f32 v85, v86, v87
	v_pk_mul_f32 v[80:81], v[108:109], v[80:81]
	ds_write_b64 v175, v[84:85]
	v_pk_mul_f32 v[84:85], v[82:83], v[0:1] op_sel_hi:[1,0]
	v_cvt_pk_bf16_f32 v86, v80, v81
	global_load_dwordx4 v[80:83], v174, s[0:1] offset:352
	v_pk_mul_f32 v[84:85], v[96:97], v[84:85]
	s_waitcnt vmcnt(9)
	v_pk_mul_f32 v[68:69], v[68:69], v[0:1] op_sel_hi:[1,0]
	v_cvt_pk_bf16_f32 v87, v84, v85
	ds_write_b64 v176, v[86:87]
	v_pk_mul_f32 v[84:85], v[70:71], v[0:1] op_sel_hi:[1,0]
	v_pk_mul_f32 v[86:87], v[100:101], v[68:69]
	global_load_dwordx4 v[68:71], v174, s[0:1] offset:384
	v_pk_mul_f32 v[84:85], v[92:93], v[84:85]
	v_xad_u32 v177, v113, 32, v112
	v_cvt_pk_bf16_f32 v86, v86, v87
	v_cvt_pk_bf16_f32 v87, v84, v85
	ds_write_b64 v177, v[86:87]
	s_waitcnt vmcnt(9)
	v_pk_mul_f32 v[84:85], v[66:67], v[0:1] op_sel_hi:[1,0]
	v_pk_mul_f32 v[86:87], v[64:65], v[0:1] op_sel_hi:[1,0]
	global_load_dwordx4 v[64:67], v174, s[0:1] offset:416
	v_pk_mul_f32 v[86:87], v[94:95], v[86:87]
	v_pk_mul_f32 v[74:75], v[74:75], v[84:85]
	v_xad_u32 v178, v113, 48, v112
	v_cvt_pk_bf16_f32 v86, v86, v87
	v_cvt_pk_bf16_f32 v87, v74, v75
	ds_write_b64 v178, v[86:87]
	s_waitcnt vmcnt(9)
	v_pk_mul_f32 v[12:13], v[12:13], v[0:1] op_sel_hi:[1,0]
	global_load_dwordx4 v[84:87], v174, s[0:1] offset:448
	v_pk_mul_f32 v[10:11], v[10:11], v[0:1] op_sel_hi:[1,0]
	v_pk_mul_f32 v[12:13], v[72:73], v[12:13]
	v_pk_mul_f32 v[10:11], v[76:77], v[10:11]
	v_xad_u32 v179, v113, 64, v112
	v_cvt_pk_bf16_f32 v10, v10, v11
	v_cvt_pk_bf16_f32 v11, v12, v13
	ds_write_b64 v179, v[10:11]
	s_waitcnt vmcnt(9)
	v_pk_mul_f32 v[12:13], v[8:9], v[0:1] op_sel_hi:[1,0]
	global_load_dwordx4 v[8:11], v174, s[0:1] offset:480
	v_pk_mul_f32 v[6:7], v[6:7], v[0:1] op_sel_hi:[1,0]
	v_pk_mul_f32 v[12:13], v[54:55], v[12:13]
	v_pk_mul_f32 v[6:7], v[52:53], v[6:7]
	s_waitcnt vmcnt(8)
	v_pk_mul_f32 v[4:5], v[0:1], v[4:5] op_sel_hi:[0,1]
	v_cvt_pk_bf16_f32 v6, v6, v7
	v_cvt_pk_bf16_f32 v7, v12, v13
	ds_write_b64 v180, v[6:7]
	v_pk_mul_f32 v[6:7], v[30:31], v[0:1] op_sel_hi:[1,0]
	v_pk_mul_f32 v[12:13], v[28:29], v[0:1] op_sel_hi:[1,0]
	v_pk_mul_f32 v[52:53], v[58:59], v[6:7]
	v_pk_mul_f32 v[12:13], v[78:79], v[12:13]
	v_and_b32_e32 v6, 0x78, v189
	v_cvt_pk_bf16_f32 v12, v12, v13
	v_or_b32_e32 v13, s8, v6
	v_or_b32_e32 v6, s7, v188
	v_ashrrev_i32_e32 v7, 31, v6
	v_lshlrev_b64 v[54:55], 11, v[6:7]
	v_lshlrev_b32_e32 v6, 1, v13
	v_or_b32_e32 v54, v54, v6
	v_lshl_add_u64 v[28:29], s[64:65], 0, v[54:55]
	global_load_dwordx4 v[28:31], v[28:29], off nt
	v_pk_mul_f32 v[2:3], v[0:1], v[2:3] op_sel_hi:[0,1]
	v_pk_mul_f32 v[2:3], v[50:51], v[2:3]
	v_pk_mul_f32 v[4:5], v[48:49], v[4:5]
	v_cvt_pk_bf16_f32 v13, v52, v53
	v_cvt_pk_bf16_f32 v2, v2, v3
	v_cvt_pk_bf16_f32 v3, v4, v5
	ds_write_b64 v181, v[12:13]
	ds_write_b64 v182, v[2:3]
	s_waitcnt vmcnt(8)
	v_pk_mul_f32 v[2:3], v[0:1], v[24:25] op_sel_hi:[0,1]
	v_pk_mul_f32 v[4:5], v[0:1], v[22:23] op_sel_hi:[0,1]
	v_pk_mul_f32 v[4:5], v[32:33], v[4:5]
	v_pk_mul_f32 v[2:3], v[34:35], v[2:3]
	v_cvt_pk_bf16_f32 v4, v4, v5
	v_cvt_pk_bf16_f32 v5, v2, v3
	ds_write_b64 v183, v[4:5]
	s_waitcnt vmcnt(7)
	v_pk_mul_f32 v[2:3], v[0:1], v[20:21] op_sel_hi:[0,1]
	v_pk_mul_f32 v[4:5], v[0:1], v[18:19] op_sel_hi:[0,1]
	v_pk_mul_f32 v[4:5], v[56:57], v[4:5]
	v_pk_mul_f32 v[2:3], v[38:39], v[2:3]
	v_cvt_pk_bf16_f32 v4, v4, v5
	v_cvt_pk_bf16_f32 v5, v2, v3
	ds_write_b64 v111, v[4:5]
	s_waitcnt vmcnt(6)
	v_pk_mul_f32 v[2:3], v[0:1], v[16:17] op_sel_hi:[0,1]
	v_pk_mul_f32 v[4:5], v[0:1], v[14:15] op_sel_hi:[0,1]
	v_pk_mul_f32 v[4:5], v[42:43], v[4:5]
	v_pk_mul_f32 v[2:3], v[36:37], v[2:3]
	v_cvt_pk_bf16_f32 v4, v4, v5
	v_cvt_pk_bf16_f32 v5, v2, v3
	ds_write_b64 v114, v[4:5]
	s_waitcnt vmcnt(5)
	v_pk_mul_f32 v[2:3], v[0:1], v[82:83] op_sel_hi:[0,1]
	v_pk_mul_f32 v[4:5], v[0:1], v[80:81] op_sel_hi:[0,1]
	s_movk_i32 s2, 0xb0
	v_pk_mul_f32 v[4:5], v[46:47], v[4:5]
	v_pk_mul_f32 v[2:3], v[40:41], v[2:3]
	v_xad_u32 v110, v113, s2, v112
	v_cvt_pk_bf16_f32 v4, v4, v5
	v_cvt_pk_bf16_f32 v5, v2, v3
	ds_write_b64 v110, v[4:5]
	s_waitcnt vmcnt(4)
	v_pk_mul_f32 v[2:3], v[0:1], v[70:71] op_sel_hi:[0,1]
	v_pk_mul_f32 v[4:5], v[0:1], v[68:69] op_sel_hi:[0,1]
	s_movk_i32 s2, 0xc0
	v_pk_mul_f32 v[4:5], v[62:63], v[4:5]
	v_pk_mul_f32 v[2:3], v[44:45], v[2:3]
	v_xad_u32 v115, v113, s2, v112
	v_cvt_pk_bf16_f32 v4, v4, v5
	v_cvt_pk_bf16_f32 v5, v2, v3
	ds_write_b64 v115, v[4:5]
	s_waitcnt vmcnt(3)
	v_pk_mul_f32 v[2:3], v[0:1], v[66:67] op_sel_hi:[0,1]
	v_pk_mul_f32 v[4:5], v[0:1], v[64:65] op_sel_hi:[0,1]
	s_movk_i32 s2, 0xd0
	v_pk_mul_f32 v[4:5], v[98:99], v[4:5]
	v_pk_mul_f32 v[2:3], v[60:61], v[2:3]
	v_xad_u32 v116, v113, s2, v112
	v_cvt_pk_bf16_f32 v4, v4, v5
	v_cvt_pk_bf16_f32 v5, v2, v3
	ds_write_b64 v116, v[4:5]
	s_waitcnt vmcnt(2)
	v_pk_mul_f32 v[2:3], v[0:1], v[86:87] op_sel_hi:[0,1]
	v_pk_mul_f32 v[4:5], v[0:1], v[84:85] op_sel_hi:[0,1]
	v_pk_mul_f32 v[4:5], v[102:103], v[4:5]
	v_pk_mul_f32 v[2:3], v[26:27], v[2:3]
	s_movk_i32 s2, 0xe0
	v_cvt_pk_bf16_f32 v4, v4, v5
	v_cvt_pk_bf16_f32 v5, v2, v3
	v_xad_u32 v2, v113, s2, v112
	ds_write_b64 v2, v[4:5]
	s_waitcnt vmcnt(1)
	v_pk_mul_f32 v[2:3], v[0:1], v[10:11] op_sel_hi:[0,1]
	v_pk_mul_f32 v[4:5], v[0:1], v[8:9] op_sel_hi:[0,1]
	v_pk_mul_f32 v[4:5], v[88:89], v[4:5]
	v_pk_mul_f32 v[2:3], v[90:91], v[2:3]
	v_cvt_pk_bf16_f32 v4, v4, v5
	v_cvt_pk_bf16_f32 v5, v2, v3
	s_movk_i32 s2, 0xf0
	v_xad_u32 v0, v113, s2, v112
	ds_write_b64 v0, v[4:5]
	v_or_b32_e32 v116, 4, v188
	v_or_b32_e32 v2, s7, v116
	v_ashrrev_i32_e32 v3, 31, v2
	v_lshlrev_b64 v[68:69], 11, v[2:3]
	v_or_b32_e32 v68, v68, v6
	v_lshl_add_u64 v[2:3], s[64:65], 0, v[68:69]
	global_load_dwordx4 v[32:35], v[2:3], off nt
	v_or_b32_e32 v116, 8, v188
	v_or_b32_e32 v2, s7, v116
	v_ashrrev_i32_e32 v3, 31, v2
	v_lshlrev_b64 v[70:71], 11, v[2:3]
	v_or_b32_e32 v70, v70, v6
	v_lshl_add_u64 v[2:3], s[64:65], 0, v[70:71]
	global_load_dwordx4 v[36:39], v[2:3], off nt
	v_or_b32_e32 v116, 12, v188
	v_or_b32_e32 v2, s7, v116
	v_ashrrev_i32_e32 v3, 31, v2
	v_lshlrev_b64 v[72:73], 11, v[2:3]
	v_or_b32_e32 v72, v72, v6
	v_lshl_add_u64 v[2:3], s[64:65], 0, v[72:73]
	global_load_dwordx4 v[40:43], v[2:3], off nt
	v_or_b32_e32 v116, 16, v188
	v_or_b32_e32 v2, s7, v116
	v_ashrrev_i32_e32 v3, 31, v2
	v_lshlrev_b64 v[74:75], 11, v[2:3]
	v_or_b32_e32 v74, v74, v6
	v_lshl_add_u64 v[2:3], s[64:65], 0, v[74:75]
	global_load_dwordx4 v[44:47], v[2:3], off nt
	v_or_b32_e32 v116, 20, v188
	v_or_b32_e32 v2, s7, v116
	v_ashrrev_i32_e32 v3, 31, v2
	v_lshlrev_b64 v[76:77], 11, v[2:3]
	v_or_b32_e32 v76, v76, v6
	v_lshl_add_u64 v[2:3], s[64:65], 0, v[76:77]
	global_load_dwordx4 v[48:51], v[2:3], off nt
	v_or_b32_e32 v116, 24, v188
	v_or_b32_e32 v2, s7, v116
	v_ashrrev_i32_e32 v3, 31, v2
	v_lshlrev_b64 v[78:79], 11, v[2:3]
	v_or_b32_e32 v78, v78, v6
	v_lshl_add_u64 v[2:3], s[64:65], 0, v[78:79]
	global_load_dwordx4 v[60:63], v[2:3], off nt
	v_or_b32_e32 v116, 28, v188
	v_or_b32_e32 v2, s7, v116
	v_ashrrev_i32_e32 v3, 31, v2
	v_lshlrev_b64 v[80:81], 11, v[2:3]
	v_or_b32_e32 v80, v80, v6
	v_lshl_add_u64 v[2:3], s[64:65], 0, v[80:81]
	global_load_dwordx4 v[64:67], v[2:3], off nt
	v_or_b32_e32 v116, 0, v188
	v_xor_b32_e32 v2, v116, v187
	v_lshlrev_b32_e32 v2, 4, v2
	v_and_b32_e32 v2, 0xf0, v2
	v_lshlrev_b32_e32 v3, 8, v116
	v_add3_u32 v3, s24, v3, v2
	ds_read_b128 v[84:87], v3
	v_or_b32_e32 v116, 4, v188
	v_xor_b32_e32 v2, v116, v187
	v_lshlrev_b32_e32 v2, 4, v2
	v_and_b32_e32 v2, 0xf0, v2
	v_lshlrev_b32_e32 v3, 8, v116
	v_add3_u32 v3, s24, v3, v2
	ds_read_b128 v[88:91], v3
	v_or_b32_e32 v116, 8, v188
	v_xor_b32_e32 v2, v116, v187
	v_lshlrev_b32_e32 v2, 4, v2
	v_and_b32_e32 v2, 0xf0, v2
	v_lshlrev_b32_e32 v3, 8, v116
	v_add3_u32 v3, s24, v3, v2
	ds_read_b128 v[92:95], v3
	v_or_b32_e32 v116, 12, v188
	v_xor_b32_e32 v2, v116, v187
	v_lshlrev_b32_e32 v2, 4, v2
	v_and_b32_e32 v2, 0xf0, v2
	v_lshlrev_b32_e32 v3, 8, v116
	v_add3_u32 v3, s24, v3, v2
	ds_read_b128 v[96:99], v3
	v_or_b32_e32 v116, 16, v188
	v_xor_b32_e32 v2, v116, v187
	v_lshlrev_b32_e32 v2, 4, v2
	v_and_b32_e32 v2, 0xf0, v2
	v_lshlrev_b32_e32 v3, 8, v116
	v_add3_u32 v3, s24, v3, v2
	ds_read_b128 v[100:103], v3
	v_or_b32_e32 v116, 20, v188
	v_xor_b32_e32 v2, v116, v187
	v_lshlrev_b32_e32 v2, 4, v2
	v_and_b32_e32 v2, 0xf0, v2
	v_lshlrev_b32_e32 v3, 8, v116
	v_add3_u32 v3, s24, v3, v2
	ds_read_b128 v[104:107], v3
	v_or_b32_e32 v116, 24, v188
	v_xor_b32_e32 v2, v116, v187
	v_lshlrev_b32_e32 v2, 4, v2
	v_and_b32_e32 v2, 0xf0, v2
	v_lshlrev_b32_e32 v3, 8, v116
	v_add3_u32 v3, s24, v3, v2
	ds_read_b128 v[108:111], v3
	v_or_b32_e32 v116, 28, v188
	v_xor_b32_e32 v2, v116, v187
	v_lshlrev_b32_e32 v2, 4, v2
	v_and_b32_e32 v2, 0xf0, v2
	v_lshlrev_b32_e32 v3, 8, v116
	v_add3_u32 v3, s24, v3, v2
	ds_read_b128 v[112:115], v3
	s_waitcnt vmcnt(7) lgkmcnt(7)
	v_lshlrev_b32_e32 v8, 16, v84
	v_and_b32_e32 v9, 0xffff0000, v84
	v_lshlrev_b32_e32 v10, 16, v28
	v_and_b32_e32 v11, 0xffff0000, v28
	v_lshlrev_b32_e32 v12, 16, v85
	v_and_b32_e32 v13, 0xffff0000, v85
	v_lshlrev_b32_e32 v14, 16, v29
	v_and_b32_e32 v15, 0xffff0000, v29
	v_lshlrev_b32_e32 v16, 16, v86
	v_and_b32_e32 v17, 0xffff0000, v86
	v_lshlrev_b32_e32 v18, 16, v30
	v_and_b32_e32 v19, 0xffff0000, v30
	v_lshlrev_b32_e32 v20, 16, v87
	v_and_b32_e32 v21, 0xffff0000, v87
	v_lshlrev_b32_e32 v22, 16, v31
	v_and_b32_e32 v23, 0xffff0000, v31
	v_pk_mul_f32 v[8:9], v[8:9], v[10:11]
	v_pk_mul_f32 v[12:13], v[12:13], v[14:15]
	v_pk_mul_f32 v[16:17], v[16:17], v[18:19]
	v_pk_mul_f32 v[20:21], v[20:21], v[22:23]
	v_cvt_pk_bf16_f32 v84, v8, v9
	v_cvt_pk_bf16_f32 v85, v12, v13
	v_cvt_pk_bf16_f32 v86, v16, v17
	v_cvt_pk_bf16_f32 v87, v20, v21
	v_lshl_add_u64 v[2:3], s[66:67], 0, v[54:55]
	global_store_dwordx4 v[2:3], v[84:87], off sc1
	s_waitcnt vmcnt(7) lgkmcnt(6)
	v_lshlrev_b32_e32 v8, 16, v88
	v_and_b32_e32 v9, 0xffff0000, v88
	v_lshlrev_b32_e32 v10, 16, v32
	v_and_b32_e32 v11, 0xffff0000, v32
	v_lshlrev_b32_e32 v12, 16, v89
	v_and_b32_e32 v13, 0xffff0000, v89
	v_lshlrev_b32_e32 v14, 16, v33
	v_and_b32_e32 v15, 0xffff0000, v33
	v_lshlrev_b32_e32 v16, 16, v90
	v_and_b32_e32 v17, 0xffff0000, v90
	v_lshlrev_b32_e32 v18, 16, v34
	v_and_b32_e32 v19, 0xffff0000, v34
	v_lshlrev_b32_e32 v20, 16, v91
	v_and_b32_e32 v21, 0xffff0000, v91
	v_lshlrev_b32_e32 v22, 16, v35
	v_and_b32_e32 v23, 0xffff0000, v35
	v_pk_mul_f32 v[8:9], v[8:9], v[10:11]
	v_pk_mul_f32 v[12:13], v[12:13], v[14:15]
	v_pk_mul_f32 v[16:17], v[16:17], v[18:19]
	v_pk_mul_f32 v[20:21], v[20:21], v[22:23]
	v_cvt_pk_bf16_f32 v88, v8, v9
	v_cvt_pk_bf16_f32 v89, v12, v13
	v_cvt_pk_bf16_f32 v90, v16, v17
	v_cvt_pk_bf16_f32 v91, v20, v21
	v_lshl_add_u64 v[2:3], s[66:67], 0, v[68:69]
	global_store_dwordx4 v[2:3], v[88:91], off sc1
	s_waitcnt vmcnt(7) lgkmcnt(5)
	v_lshlrev_b32_e32 v8, 16, v92
	v_and_b32_e32 v9, 0xffff0000, v92
	v_lshlrev_b32_e32 v10, 16, v36
	v_and_b32_e32 v11, 0xffff0000, v36
	v_lshlrev_b32_e32 v12, 16, v93
	v_and_b32_e32 v13, 0xffff0000, v93
	v_lshlrev_b32_e32 v14, 16, v37
	v_and_b32_e32 v15, 0xffff0000, v37
	v_lshlrev_b32_e32 v16, 16, v94
	v_and_b32_e32 v17, 0xffff0000, v94
	v_lshlrev_b32_e32 v18, 16, v38
	v_and_b32_e32 v19, 0xffff0000, v38
	v_lshlrev_b32_e32 v20, 16, v95
	v_and_b32_e32 v21, 0xffff0000, v95
	v_lshlrev_b32_e32 v22, 16, v39
	v_and_b32_e32 v23, 0xffff0000, v39
	v_pk_mul_f32 v[8:9], v[8:9], v[10:11]
	v_pk_mul_f32 v[12:13], v[12:13], v[14:15]
	v_pk_mul_f32 v[16:17], v[16:17], v[18:19]
	v_pk_mul_f32 v[20:21], v[20:21], v[22:23]
	v_cvt_pk_bf16_f32 v92, v8, v9
	v_cvt_pk_bf16_f32 v93, v12, v13
	v_cvt_pk_bf16_f32 v94, v16, v17
	v_cvt_pk_bf16_f32 v95, v20, v21
	v_lshl_add_u64 v[2:3], s[66:67], 0, v[70:71]
	global_store_dwordx4 v[2:3], v[92:95], off sc1
	s_waitcnt vmcnt(7) lgkmcnt(4)
	v_lshlrev_b32_e32 v8, 16, v96
	v_and_b32_e32 v9, 0xffff0000, v96
	v_lshlrev_b32_e32 v10, 16, v40
	v_and_b32_e32 v11, 0xffff0000, v40
	v_lshlrev_b32_e32 v12, 16, v97
	v_and_b32_e32 v13, 0xffff0000, v97
	v_lshlrev_b32_e32 v14, 16, v41
	v_and_b32_e32 v15, 0xffff0000, v41
	v_lshlrev_b32_e32 v16, 16, v98
	v_and_b32_e32 v17, 0xffff0000, v98
	v_lshlrev_b32_e32 v18, 16, v42
	v_and_b32_e32 v19, 0xffff0000, v42
	v_lshlrev_b32_e32 v20, 16, v99
	v_and_b32_e32 v21, 0xffff0000, v99
	v_lshlrev_b32_e32 v22, 16, v43
	v_and_b32_e32 v23, 0xffff0000, v43
	v_pk_mul_f32 v[8:9], v[8:9], v[10:11]
	v_pk_mul_f32 v[12:13], v[12:13], v[14:15]
	v_pk_mul_f32 v[16:17], v[16:17], v[18:19]
	v_pk_mul_f32 v[20:21], v[20:21], v[22:23]
	v_cvt_pk_bf16_f32 v96, v8, v9
	v_cvt_pk_bf16_f32 v97, v12, v13
	v_cvt_pk_bf16_f32 v98, v16, v17
	v_cvt_pk_bf16_f32 v99, v20, v21
	v_lshl_add_u64 v[2:3], s[66:67], 0, v[72:73]
	global_store_dwordx4 v[2:3], v[96:99], off sc1
	s_waitcnt vmcnt(7) lgkmcnt(3)
	v_lshlrev_b32_e32 v8, 16, v100
	v_and_b32_e32 v9, 0xffff0000, v100
	v_lshlrev_b32_e32 v10, 16, v44
	v_and_b32_e32 v11, 0xffff0000, v44
	v_lshlrev_b32_e32 v12, 16, v101
	v_and_b32_e32 v13, 0xffff0000, v101
	v_lshlrev_b32_e32 v14, 16, v45
	v_and_b32_e32 v15, 0xffff0000, v45
	v_lshlrev_b32_e32 v16, 16, v102
	v_and_b32_e32 v17, 0xffff0000, v102
	v_lshlrev_b32_e32 v18, 16, v46
	v_and_b32_e32 v19, 0xffff0000, v46
	v_lshlrev_b32_e32 v20, 16, v103
	v_and_b32_e32 v21, 0xffff0000, v103
	v_lshlrev_b32_e32 v22, 16, v47
	v_and_b32_e32 v23, 0xffff0000, v47
	v_pk_mul_f32 v[8:9], v[8:9], v[10:11]
	v_pk_mul_f32 v[12:13], v[12:13], v[14:15]
	v_pk_mul_f32 v[16:17], v[16:17], v[18:19]
	v_pk_mul_f32 v[20:21], v[20:21], v[22:23]
	v_cvt_pk_bf16_f32 v100, v8, v9
	v_cvt_pk_bf16_f32 v101, v12, v13
	v_cvt_pk_bf16_f32 v102, v16, v17
	v_cvt_pk_bf16_f32 v103, v20, v21
	v_lshl_add_u64 v[2:3], s[66:67], 0, v[74:75]
	global_store_dwordx4 v[2:3], v[100:103], off sc1
	s_waitcnt vmcnt(7) lgkmcnt(2)
	v_lshlrev_b32_e32 v8, 16, v104
	v_and_b32_e32 v9, 0xffff0000, v104
	v_lshlrev_b32_e32 v10, 16, v48
	v_and_b32_e32 v11, 0xffff0000, v48
	v_lshlrev_b32_e32 v12, 16, v105
	v_and_b32_e32 v13, 0xffff0000, v105
	v_lshlrev_b32_e32 v14, 16, v49
	v_and_b32_e32 v15, 0xffff0000, v49
	v_lshlrev_b32_e32 v16, 16, v106
	v_and_b32_e32 v17, 0xffff0000, v106
	v_lshlrev_b32_e32 v18, 16, v50
	v_and_b32_e32 v19, 0xffff0000, v50
	v_lshlrev_b32_e32 v20, 16, v107
	v_and_b32_e32 v21, 0xffff0000, v107
	v_lshlrev_b32_e32 v22, 16, v51
	v_and_b32_e32 v23, 0xffff0000, v51
	v_pk_mul_f32 v[8:9], v[8:9], v[10:11]
	v_pk_mul_f32 v[12:13], v[12:13], v[14:15]
	v_pk_mul_f32 v[16:17], v[16:17], v[18:19]
	v_pk_mul_f32 v[20:21], v[20:21], v[22:23]
	v_cvt_pk_bf16_f32 v104, v8, v9
	v_cvt_pk_bf16_f32 v105, v12, v13
	v_cvt_pk_bf16_f32 v106, v16, v17
	v_cvt_pk_bf16_f32 v107, v20, v21
	v_lshl_add_u64 v[2:3], s[66:67], 0, v[76:77]
	global_store_dwordx4 v[2:3], v[104:107], off sc1
	s_waitcnt vmcnt(7) lgkmcnt(1)
	v_lshlrev_b32_e32 v8, 16, v108
	v_and_b32_e32 v9, 0xffff0000, v108
	v_lshlrev_b32_e32 v10, 16, v60
	v_and_b32_e32 v11, 0xffff0000, v60
	v_lshlrev_b32_e32 v12, 16, v109
	v_and_b32_e32 v13, 0xffff0000, v109
	v_lshlrev_b32_e32 v14, 16, v61
	v_and_b32_e32 v15, 0xffff0000, v61
	v_lshlrev_b32_e32 v16, 16, v110
	v_and_b32_e32 v17, 0xffff0000, v110
	v_lshlrev_b32_e32 v18, 16, v62
	v_and_b32_e32 v19, 0xffff0000, v62
	v_lshlrev_b32_e32 v20, 16, v111
	v_and_b32_e32 v21, 0xffff0000, v111
	v_lshlrev_b32_e32 v22, 16, v63
	v_and_b32_e32 v23, 0xffff0000, v63
	v_pk_mul_f32 v[8:9], v[8:9], v[10:11]
	v_pk_mul_f32 v[12:13], v[12:13], v[14:15]
	v_pk_mul_f32 v[16:17], v[16:17], v[18:19]
	v_pk_mul_f32 v[20:21], v[20:21], v[22:23]
	v_cvt_pk_bf16_f32 v108, v8, v9
	v_cvt_pk_bf16_f32 v109, v12, v13
	v_cvt_pk_bf16_f32 v110, v16, v17
	v_cvt_pk_bf16_f32 v111, v20, v21
	v_lshl_add_u64 v[2:3], s[66:67], 0, v[78:79]
	global_store_dwordx4 v[2:3], v[108:111], off sc1
	s_waitcnt vmcnt(7) lgkmcnt(0)
	v_lshlrev_b32_e32 v8, 16, v112
	v_and_b32_e32 v9, 0xffff0000, v112
	v_lshlrev_b32_e32 v10, 16, v64
	v_and_b32_e32 v11, 0xffff0000, v64
	v_lshlrev_b32_e32 v12, 16, v113
	v_and_b32_e32 v13, 0xffff0000, v113
	v_lshlrev_b32_e32 v14, 16, v65
	v_and_b32_e32 v15, 0xffff0000, v65
	v_lshlrev_b32_e32 v16, 16, v114
	v_and_b32_e32 v17, 0xffff0000, v114
	v_lshlrev_b32_e32 v18, 16, v66
	v_and_b32_e32 v19, 0xffff0000, v66
	v_lshlrev_b32_e32 v20, 16, v115
	v_and_b32_e32 v21, 0xffff0000, v115
	v_lshlrev_b32_e32 v22, 16, v67
	v_and_b32_e32 v23, 0xffff0000, v67
	v_pk_mul_f32 v[8:9], v[8:9], v[10:11]
	v_pk_mul_f32 v[12:13], v[12:13], v[14:15]
	v_pk_mul_f32 v[16:17], v[16:17], v[18:19]
	v_pk_mul_f32 v[20:21], v[20:21], v[22:23]
	v_cvt_pk_bf16_f32 v112, v8, v9
	v_cvt_pk_bf16_f32 v113, v12, v13
	v_cvt_pk_bf16_f32 v114, v16, v17
	v_cvt_pk_bf16_f32 v115, v20, v21
	v_lshl_add_u64 v[2:3], s[66:67], 0, v[80:81]
	global_store_dwordx4 v[2:3], v[112:115], off sc1
	s_branch .LBB0_455

.LBB0_483:
	v_readlane_b32 s4, v253, 54
	v_readlane_b32 s5, v253, 55
	s_andn2_b64 vcc, exec, s[4:5]
	s_waitcnt lgkmcnt(0)
	s_barrier
	s_cbranch_vccnz .LBB0_472
	ds_read2st64_b32 v[4:5], v2 offset1:1
	ds_read2st64_b32 v[6:7], v2 offset0:2 offset1:3
	ds_read2st64_b32 v[8:9], v2 offset0:4 offset1:5
	ds_read2st64_b32 v[10:11], v2 offset0:6 offset1:7
	ds_read2st64_b32 v[12:13], v2 offset0:8 offset1:9
	ds_read2st64_b32 v[92:93], v2 offset0:10 offset1:11
	ds_read2st64_b32 v[94:95], v2 offset0:12 offset1:13
	ds_read2st64_b32 v[98:99], v2 offset0:14 offset1:15
	ds_read2st64_b32 v[102:103], v2 offset0:16 offset1:17
	ds_read2st64_b32 v[114:115], v2 offset0:18 offset1:19
	ds_read2st64_b32 v[116:117], v2 offset0:20 offset1:21
	ds_read2st64_b32 v[118:119], v2 offset0:22 offset1:23
	ds_read2st64_b32 v[120:121], v2 offset0:24 offset1:25
	ds_read2st64_b32 v[122:123], v2 offset0:26 offset1:27
	ds_read2st64_b32 v[124:125], v2 offset0:28 offset1:29
	ds_read2st64_b32 v[126:127], v2 offset0:30 offset1:31
	ds_read2st64_b32 v[128:129], v2 offset0:32 offset1:33
	ds_read2st64_b32 v[130:131], v2 offset0:34 offset1:35
	ds_read2st64_b32 v[132:133], v2 offset0:36 offset1:37
	ds_read2st64_b32 v[134:135], v2 offset0:38 offset1:39
	ds_read2st64_b32 v[136:137], v2 offset0:40 offset1:41
	ds_read2st64_b32 v[138:139], v2 offset0:42 offset1:43
	ds_read2st64_b32 v[140:141], v2 offset0:44 offset1:45
	ds_read2st64_b32 v[142:143], v2 offset0:46 offset1:47
	ds_read2st64_b32 v[144:145], v2 offset0:56 offset1:57
	ds_read2st64_b32 v[146:147], v2 offset0:58 offset1:59
	ds_read2st64_b32 v[14:15], v2 offset0:60 offset1:61
	ds_read2st64_b32 v[80:81], v2 offset0:62 offset1:63
	ds_read2st64_b32 v[148:149], v2 offset0:48 offset1:49
	ds_read2st64_b32 v[150:151], v2 offset0:50 offset1:51
	ds_read2st64_b32 v[152:153], v2 offset0:52 offset1:53
	ds_read2st64_b32 v[154:155], v2 offset0:54 offset1:55
	s_waitcnt lgkmcnt(14)
	v_pk_fma_f32 v[106:107], v[64:65], v[0:1], v[4:5] op_sel_hi:[1,0,1] neg_lo:[0,0,1] neg_hi:[0,0,1]
	v_lshlrev_b32_e32 v174, 2, v193
	v_pk_fma_f32 v[104:105], v[66:67], v[0:1], v[6:7] op_sel_hi:[1,0,1] neg_lo:[0,0,1] neg_hi:[0,0,1]
	v_pk_mul_f32 v[158:159], v[106:107], v[106:107]
	s_waitcnt lgkmcnt(5)
	v_pk_fma_f32 v[88:89], v[28:29], v[0:1], v[14:15] op_sel_hi:[1,0,1] neg_lo:[0,0,1] neg_hi:[0,0,1]
	s_waitcnt lgkmcnt(4)
	v_pk_fma_f32 v[90:91], v[30:31], v[0:1], v[80:81] op_sel_hi:[1,0,1] neg_lo:[0,0,1] neg_hi:[0,0,1]
	v_pk_mul_f32 v[156:157], v[104:105], v[104:105]
	global_load_dwordx4 v[84:87], v174, s[0:1]
	global_load_dwordx4 v[80:83], v174, s[0:1] offset:32
	v_pk_fma_f32 v[96:97], v[70:71], v[0:1], v[10:11] op_sel_hi:[1,0,1] neg_lo:[0,0,1] neg_hi:[0,0,1]
	v_pk_fma_f32 v[108:109], v[68:69], v[0:1], v[8:9] op_sel_hi:[1,0,1] neg_lo:[0,0,1] neg_hi:[0,0,1]
	v_pk_fma_f32 v[92:93], v[74:75], v[0:1], v[92:93] op_sel_hi:[1,0,1] neg_lo:[0,0,1] neg_hi:[0,0,1]
	v_pk_fma_f32 v[100:101], v[72:73], v[0:1], v[12:13] op_sel_hi:[1,0,1] neg_lo:[0,0,1] neg_hi:[0,0,1]
	v_pk_fma_f32 v[74:75], v[78:79], v[0:1], v[98:99] op_sel_hi:[1,0,1] neg_lo:[0,0,1] neg_hi:[0,0,1]
	v_pk_fma_f32 v[94:95], v[76:77], v[0:1], v[94:95] op_sel_hi:[1,0,1] neg_lo:[0,0,1] neg_hi:[0,0,1]
	v_pk_fma_f32 v[72:73], v[50:51], v[0:1], v[114:115] op_sel_hi:[1,0,1] neg_lo:[0,0,1] neg_hi:[0,0,1]
	v_pk_fma_f32 v[76:77], v[48:49], v[0:1], v[102:103] op_sel_hi:[1,0,1] neg_lo:[0,0,1] neg_hi:[0,0,1]
	v_pk_fma_f32 v[54:55], v[54:55], v[0:1], v[118:119] op_sel_hi:[1,0,1] neg_lo:[0,0,1] neg_hi:[0,0,1]
	v_pk_fma_f32 v[52:53], v[52:53], v[0:1], v[116:117] op_sel_hi:[1,0,1] neg_lo:[0,0,1] neg_hi:[0,0,1]
	v_pk_fma_f32 v[58:59], v[58:59], v[0:1], v[122:123] op_sel_hi:[1,0,1] neg_lo:[0,0,1] neg_hi:[0,0,1]
	v_pk_fma_f32 v[78:79], v[56:57], v[0:1], v[120:121] op_sel_hi:[1,0,1] neg_lo:[0,0,1] neg_hi:[0,0,1]
	v_pk_fma_f32 v[48:49], v[62:63], v[0:1], v[126:127] op_sel_hi:[1,0,1] neg_lo:[0,0,1] neg_hi:[0,0,1]
	v_pk_fma_f32 v[50:51], v[60:61], v[0:1], v[124:125] op_sel_hi:[1,0,1] neg_lo:[0,0,1] neg_hi:[0,0,1]
	v_pk_fma_f32 v[34:35], v[34:35], v[0:1], v[130:131] op_sel_hi:[1,0,1] neg_lo:[0,0,1] neg_hi:[0,0,1]
	v_pk_fma_f32 v[32:33], v[32:33], v[0:1], v[128:129] op_sel_hi:[1,0,1] neg_lo:[0,0,1] neg_hi:[0,0,1]
	v_pk_fma_f32 v[38:39], v[38:39], v[0:1], v[134:135] op_sel_hi:[1,0,1] neg_lo:[0,0,1] neg_hi:[0,0,1]
	v_pk_fma_f32 v[56:57], v[36:37], v[0:1], v[132:133] op_sel_hi:[1,0,1] neg_lo:[0,0,1] neg_hi:[0,0,1]
	v_pk_fma_f32 v[36:37], v[42:43], v[0:1], v[138:139] op_sel_hi:[1,0,1] neg_lo:[0,0,1] neg_hi:[0,0,1]
	v_pk_fma_f32 v[42:43], v[40:41], v[0:1], v[136:137] op_sel_hi:[1,0,1] neg_lo:[0,0,1] neg_hi:[0,0,1]
	v_pk_fma_f32 v[40:41], v[46:47], v[0:1], v[142:143] op_sel_hi:[1,0,1] neg_lo:[0,0,1] neg_hi:[0,0,1]
	v_pk_fma_f32 v[46:47], v[44:45], v[0:1], v[140:141] op_sel_hi:[1,0,1] neg_lo:[0,0,1] neg_hi:[0,0,1]
	s_waitcnt lgkmcnt(2)
	v_pk_fma_f32 v[44:45], v[18:19], v[0:1], v[150:151] op_sel_hi:[1,0,1] neg_lo:[0,0,1] neg_hi:[0,0,1]
	v_pk_fma_f32 v[62:63], v[16:17], v[0:1], v[148:149] op_sel_hi:[1,0,1] neg_lo:[0,0,1] neg_hi:[0,0,1]
	s_waitcnt lgkmcnt(0)
	v_pk_fma_f32 v[60:61], v[22:23], v[0:1], v[154:155] op_sel_hi:[1,0,1] neg_lo:[0,0,1] neg_hi:[0,0,1]
	v_pk_fma_f32 v[98:99], v[20:21], v[0:1], v[152:153] op_sel_hi:[1,0,1] neg_lo:[0,0,1] neg_hi:[0,0,1]
	v_pk_fma_f32 v[26:27], v[26:27], v[0:1], v[146:147] op_sel_hi:[1,0,1] neg_lo:[0,0,1] neg_hi:[0,0,1]
	v_pk_fma_f32 v[102:103], v[24:25], v[0:1], v[144:145] op_sel_hi:[1,0,1] neg_lo:[0,0,1] neg_hi:[0,0,1]
	v_add_f32_e32 v0, v158, v159
	v_add_f32_e32 v0, v0, v156
	v_pk_mul_f32 v[162:163], v[108:109], v[108:109]
	v_add_f32_e32 v0, v0, v157
	v_add_f32_e32 v0, v0, v162
	v_pk_mul_f32 v[160:161], v[96:97], v[96:97]
	v_add_f32_e32 v0, v0, v163
	global_load_dwordx4 v[68:71], v174, s[0:1] offset:64
	global_load_dwordx4 v[64:67], v174, s[0:1] offset:96
	v_add_f32_e32 v0, v0, v160
	v_pk_mul_f32 v[166:167], v[100:101], v[100:101]
	v_add_f32_e32 v0, v0, v161
	v_add_f32_e32 v0, v0, v166
	v_pk_mul_f32 v[164:165], v[92:93], v[92:93]
	v_add_f32_e32 v0, v0, v167
	v_add_f32_e32 v0, v0, v164
	v_pk_mul_f32 v[170:171], v[94:95], v[94:95]
	v_add_f32_e32 v0, v0, v165
	v_add_f32_e32 v0, v0, v170
	v_pk_mul_f32 v[168:169], v[74:75], v[74:75]
	global_load_dwordx4 v[10:13], v174, s[0:1] offset:128
	global_load_dwordx4 v[6:9], v174, s[0:1] offset:160
	v_add_f32_e32 v0, v0, v171
	v_add_f32_e32 v0, v0, v168
	v_pk_mul_f32 v[172:173], v[76:77], v[76:77]
	v_add_f32_e32 v0, v0, v169
	v_add_f32_e32 v0, v0, v172
	v_pk_mul_f32 v[114:115], v[72:73], v[72:73]
	v_add_f32_e32 v0, v0, v173
	v_add_f32_e32 v0, v0, v114
	v_lshlrev_b32_e32 v2, 8, v191
	v_pk_mul_f32 v[116:117], v[52:53], v[52:53]
	v_add_f32_e32 v0, v0, v115
	v_add3_u32 v112, s24, v2, v192
	global_load_dwordx4 v[28:31], v174, s[0:1] offset:192
	global_load_dwordx4 v[2:5], v174, s[0:1] offset:224
	v_add_f32_e32 v0, v0, v116
	v_pk_mul_f32 v[118:119], v[54:55], v[54:55]
	v_add_f32_e32 v0, v0, v117
	v_add_f32_e32 v0, v0, v118
	v_pk_mul_f32 v[120:121], v[78:79], v[78:79]
	v_add_f32_e32 v0, v0, v119
	v_add_f32_e32 v0, v0, v120
	v_pk_mul_f32 v[122:123], v[58:59], v[58:59]
	v_add_f32_e32 v0, v0, v121
	v_add_f32_e32 v0, v0, v122
	v_pk_mul_f32 v[124:125], v[50:51], v[50:51]
	v_add_f32_e32 v0, v0, v123
	v_add_f32_e32 v0, v0, v124
	v_pk_mul_f32 v[126:127], v[48:49], v[48:49]
	v_add_f32_e32 v0, v0, v125
	v_add_f32_e32 v0, v0, v126
	v_pk_mul_f32 v[128:129], v[32:33], v[32:33]
	v_add_f32_e32 v0, v0, v127
	v_add_f32_e32 v0, v0, v128
	v_pk_mul_f32 v[130:131], v[34:35], v[34:35]
	v_add_f32_e32 v0, v0, v129
	v_add_f32_e32 v0, v0, v130
	v_pk_mul_f32 v[132:133], v[56:57], v[56:57]
	v_add_f32_e32 v0, v0, v131
	v_add_f32_e32 v0, v0, v132
	v_pk_mul_f32 v[134:135], v[38:39], v[38:39]
	v_add_f32_e32 v0, v0, v133
	v_add_f32_e32 v0, v0, v134
	v_pk_mul_f32 v[136:137], v[42:43], v[42:43]
	v_add_f32_e32 v0, v0, v135
	v_add_f32_e32 v0, v0, v136
	v_pk_mul_f32 v[138:139], v[36:37], v[36:37]
	v_add_f32_e32 v0, v0, v137
	v_add_f32_e32 v0, v0, v138
	v_pk_mul_f32 v[140:141], v[46:47], v[46:47]
	v_add_f32_e32 v0, v0, v139
	v_add_f32_e32 v0, v0, v140
	v_pk_mul_f32 v[142:143], v[40:41], v[40:41]
	v_add_f32_e32 v0, v0, v141
	v_add_f32_e32 v0, v0, v142
	v_pk_mul_f32 v[16:17], v[62:63], v[62:63]
	v_add_f32_e32 v0, v0, v143
	v_add_f32_e32 v0, v0, v16
	v_pk_mul_f32 v[18:19], v[44:45], v[44:45]
	v_add_f32_e32 v0, v0, v17
	v_add_f32_e32 v0, v0, v18
	v_pk_mul_f32 v[20:21], v[98:99], v[98:99]
	v_add_f32_e32 v0, v0, v19
	v_add_f32_e32 v0, v0, v20
	v_pk_mul_f32 v[22:23], v[60:61], v[60:61]
	v_add_f32_e32 v0, v0, v21
	v_add_f32_e32 v0, v0, v22
	v_pk_mul_f32 v[24:25], v[102:103], v[102:103]
	v_add_f32_e32 v0, v0, v23
	v_add_f32_e32 v0, v0, v24
	v_pk_mul_f32 v[146:147], v[26:27], v[26:27]
	v_add_f32_e32 v0, v0, v25
	v_add_f32_e32 v0, v0, v146
	v_pk_mul_f32 v[14:15], v[88:89], v[88:89]
	v_add_f32_e32 v0, v0, v147
	v_add_f32_e32 v0, v0, v14
	v_pk_mul_f32 v[110:111], v[90:91], v[90:91]
	v_add_f32_e32 v0, v0, v15
	v_add_f32_e32 v0, v0, v110
	v_add_f32_e32 v0, v0, v111
	v_and_b32_e32 v113, 0xf0, v190
	s_movk_i32 s2, 0x50
	ds_bpermute_b32 v110, v184, v0
	v_xad_u32 v180, v113, s2, v112
	s_movk_i32 s2, 0x60
	v_xad_u32 v181, v113, s2, v112
	s_movk_i32 s2, 0x70
	v_xad_u32 v182, v113, s2, v112
	s_movk_i32 s2, 0x80
	v_xad_u32 v183, v113, s2, v112
	s_movk_i32 s2, 0x90
	v_xad_u32 v111, v113, s2, v112
	s_movk_i32 s2, 0xa0
	s_waitcnt lgkmcnt(0)
	v_add_f32_e32 v0, v0, v110
	v_xad_u32 v114, v113, s2, v112
	v_fmamk_f32 v0, v0, 0x3c000000, v213
	s_mov_b32 s2, 0x800000
	v_mul_f32_e32 v110, 0x4b800000, v0
	v_cmp_gt_f32_e32 vcc, s2, v0
	global_load_dwordx4 v[22:25], v174, s[0:1] offset:256
	global_load_dwordx4 v[18:21], v174, s[0:1] offset:288
	v_cndmask_b32_e32 v0, v0, v110, vcc
	v_rsq_f32_e32 v0, v0
	global_load_dwordx4 v[14:17], v174, s[0:1] offset:320
	v_add_u32_e32 v175, v112, v113
	v_xad_u32 v176, v113, 16, v112
	v_mul_f32_e32 v117, 0x45800000, v0
	v_cndmask_b32_e32 v0, v0, v117, vcc
	v_mul_f32_e32 v0, v185, v0
	s_waitcnt vmcnt(10)
	v_pk_mul_f32 v[86:87], v[86:87], v[0:1] op_sel_hi:[1,0]
	v_pk_mul_f32 v[84:85], v[84:85], v[0:1] op_sel_hi:[1,0]
	v_pk_mul_f32 v[86:87], v[104:105], v[86:87]
	v_pk_mul_f32 v[84:85], v[106:107], v[84:85]
	s_waitcnt vmcnt(9)
	v_pk_mul_f32 v[80:81], v[80:81], v[0:1] op_sel_hi:[1,0]
	v_cvt_pk_bf16_f32 v84, v84, v85
	v_cvt_pk_bf16_f32 v85, v86, v87
	v_pk_mul_f32 v[80:81], v[108:109], v[80:81]
	ds_write_b64 v175, v[84:85]
	v_pk_mul_f32 v[84:85], v[82:83], v[0:1] op_sel_hi:[1,0]
	v_cvt_pk_bf16_f32 v86, v80, v81
	global_load_dwordx4 v[80:83], v174, s[0:1] offset:352
	v_pk_mul_f32 v[84:85], v[96:97], v[84:85]
	s_waitcnt vmcnt(9)
	v_pk_mul_f32 v[68:69], v[68:69], v[0:1] op_sel_hi:[1,0]
	v_cvt_pk_bf16_f32 v87, v84, v85
	ds_write_b64 v176, v[86:87]
	v_pk_mul_f32 v[84:85], v[70:71], v[0:1] op_sel_hi:[1,0]
	v_pk_mul_f32 v[86:87], v[100:101], v[68:69]
	global_load_dwordx4 v[68:71], v174, s[0:1] offset:384
	v_pk_mul_f32 v[84:85], v[92:93], v[84:85]
	v_xad_u32 v177, v113, 32, v112
	v_cvt_pk_bf16_f32 v86, v86, v87
	v_cvt_pk_bf16_f32 v87, v84, v85
	ds_write_b64 v177, v[86:87]
	s_waitcnt vmcnt(9)
	v_pk_mul_f32 v[84:85], v[66:67], v[0:1] op_sel_hi:[1,0]
	v_pk_mul_f32 v[86:87], v[64:65], v[0:1] op_sel_hi:[1,0]
	global_load_dwordx4 v[64:67], v174, s[0:1] offset:416
	v_pk_mul_f32 v[86:87], v[94:95], v[86:87]
	v_pk_mul_f32 v[74:75], v[74:75], v[84:85]
	v_xad_u32 v178, v113, 48, v112
	v_cvt_pk_bf16_f32 v86, v86, v87
	v_cvt_pk_bf16_f32 v87, v74, v75
	ds_write_b64 v178, v[86:87]
	s_waitcnt vmcnt(9)
	v_pk_mul_f32 v[12:13], v[12:13], v[0:1] op_sel_hi:[1,0]
	global_load_dwordx4 v[84:87], v174, s[0:1] offset:448
	v_pk_mul_f32 v[10:11], v[10:11], v[0:1] op_sel_hi:[1,0]
	v_pk_mul_f32 v[12:13], v[72:73], v[12:13]
	v_pk_mul_f32 v[10:11], v[76:77], v[10:11]
	v_xad_u32 v179, v113, 64, v112
	v_cvt_pk_bf16_f32 v10, v10, v11
	v_cvt_pk_bf16_f32 v11, v12, v13
	ds_write_b64 v179, v[10:11]
	s_waitcnt vmcnt(9)
	v_pk_mul_f32 v[12:13], v[8:9], v[0:1] op_sel_hi:[1,0]
	global_load_dwordx4 v[8:11], v174, s[0:1] offset:480
	v_pk_mul_f32 v[6:7], v[6:7], v[0:1] op_sel_hi:[1,0]
	v_pk_mul_f32 v[12:13], v[54:55], v[12:13]
	v_pk_mul_f32 v[6:7], v[52:53], v[6:7]
	s_waitcnt vmcnt(8)
	v_pk_mul_f32 v[4:5], v[0:1], v[4:5] op_sel_hi:[0,1]
	v_cvt_pk_bf16_f32 v6, v6, v7
	v_cvt_pk_bf16_f32 v7, v12, v13
	ds_write_b64 v180, v[6:7]
	v_pk_mul_f32 v[6:7], v[30:31], v[0:1] op_sel_hi:[1,0]
	v_pk_mul_f32 v[12:13], v[28:29], v[0:1] op_sel_hi:[1,0]
	v_pk_mul_f32 v[52:53], v[58:59], v[6:7]
	v_pk_mul_f32 v[12:13], v[78:79], v[12:13]
	v_and_b32_e32 v6, 0x78, v189
	v_cvt_pk_bf16_f32 v12, v12, v13
	v_or_b32_e32 v13, s9, v6
	v_or_b32_e32 v6, s8, v188
	v_ashrrev_i32_e32 v7, 31, v6
	v_lshlrev_b64 v[54:55], 11, v[6:7]
	v_lshlrev_b32_e32 v6, 1, v13
	v_or_b32_e32 v54, v54, v6
	v_lshl_add_u64 v[28:29], s[64:65], 0, v[54:55]
	global_load_dwordx4 v[28:31], v[28:29], off nt
	v_pk_mul_f32 v[2:3], v[0:1], v[2:3] op_sel_hi:[0,1]
	v_pk_mul_f32 v[2:3], v[50:51], v[2:3]
	v_pk_mul_f32 v[4:5], v[48:49], v[4:5]
	v_cvt_pk_bf16_f32 v13, v52, v53
	v_cvt_pk_bf16_f32 v2, v2, v3
	v_cvt_pk_bf16_f32 v3, v4, v5
	ds_write_b64 v181, v[12:13]
	ds_write_b64 v182, v[2:3]
	s_waitcnt vmcnt(8)
	v_pk_mul_f32 v[2:3], v[0:1], v[24:25] op_sel_hi:[0,1]
	v_pk_mul_f32 v[4:5], v[0:1], v[22:23] op_sel_hi:[0,1]
	v_pk_mul_f32 v[4:5], v[32:33], v[4:5]
	v_pk_mul_f32 v[2:3], v[34:35], v[2:3]
	v_cvt_pk_bf16_f32 v4, v4, v5
	v_cvt_pk_bf16_f32 v5, v2, v3
	ds_write_b64 v183, v[4:5]
	s_waitcnt vmcnt(7)
	v_pk_mul_f32 v[2:3], v[0:1], v[20:21] op_sel_hi:[0,1]
	v_pk_mul_f32 v[4:5], v[0:1], v[18:19] op_sel_hi:[0,1]
	v_pk_mul_f32 v[4:5], v[56:57], v[4:5]
	v_pk_mul_f32 v[2:3], v[38:39], v[2:3]
	v_cvt_pk_bf16_f32 v4, v4, v5
	v_cvt_pk_bf16_f32 v5, v2, v3
	ds_write_b64 v111, v[4:5]
	s_waitcnt vmcnt(6)
	v_pk_mul_f32 v[2:3], v[0:1], v[16:17] op_sel_hi:[0,1]
	v_pk_mul_f32 v[4:5], v[0:1], v[14:15] op_sel_hi:[0,1]
	v_pk_mul_f32 v[4:5], v[42:43], v[4:5]
	v_pk_mul_f32 v[2:3], v[36:37], v[2:3]
	v_cvt_pk_bf16_f32 v4, v4, v5
	v_cvt_pk_bf16_f32 v5, v2, v3
	ds_write_b64 v114, v[4:5]
	s_waitcnt vmcnt(5)
	v_pk_mul_f32 v[2:3], v[0:1], v[82:83] op_sel_hi:[0,1]
	v_pk_mul_f32 v[4:5], v[0:1], v[80:81] op_sel_hi:[0,1]
	s_movk_i32 s2, 0xb0
	v_pk_mul_f32 v[4:5], v[46:47], v[4:5]
	v_pk_mul_f32 v[2:3], v[40:41], v[2:3]
	v_xad_u32 v110, v113, s2, v112
	v_cvt_pk_bf16_f32 v4, v4, v5
	v_cvt_pk_bf16_f32 v5, v2, v3
	ds_write_b64 v110, v[4:5]
	s_waitcnt vmcnt(4)
	v_pk_mul_f32 v[2:3], v[0:1], v[70:71] op_sel_hi:[0,1]
	v_pk_mul_f32 v[4:5], v[0:1], v[68:69] op_sel_hi:[0,1]
	s_movk_i32 s2, 0xc0
	v_pk_mul_f32 v[4:5], v[62:63], v[4:5]
	v_pk_mul_f32 v[2:3], v[44:45], v[2:3]
	v_xad_u32 v115, v113, s2, v112
	v_cvt_pk_bf16_f32 v4, v4, v5
	v_cvt_pk_bf16_f32 v5, v2, v3
	ds_write_b64 v115, v[4:5]
	s_waitcnt vmcnt(3)
	v_pk_mul_f32 v[2:3], v[0:1], v[66:67] op_sel_hi:[0,1]
	v_pk_mul_f32 v[4:5], v[0:1], v[64:65] op_sel_hi:[0,1]
	s_movk_i32 s2, 0xd0
	v_pk_mul_f32 v[4:5], v[98:99], v[4:5]
	v_pk_mul_f32 v[2:3], v[60:61], v[2:3]
	v_xad_u32 v116, v113, s2, v112
	v_cvt_pk_bf16_f32 v4, v4, v5
	v_cvt_pk_bf16_f32 v5, v2, v3
	ds_write_b64 v116, v[4:5]
	s_waitcnt vmcnt(2)
	v_pk_mul_f32 v[2:3], v[0:1], v[86:87] op_sel_hi:[0,1]
	v_pk_mul_f32 v[4:5], v[0:1], v[84:85] op_sel_hi:[0,1]
	v_pk_mul_f32 v[4:5], v[102:103], v[4:5]
	v_pk_mul_f32 v[2:3], v[26:27], v[2:3]
	s_movk_i32 s2, 0xe0
	v_cvt_pk_bf16_f32 v4, v4, v5
	v_cvt_pk_bf16_f32 v5, v2, v3
	v_xad_u32 v2, v113, s2, v112
	ds_write_b64 v2, v[4:5]
	s_waitcnt vmcnt(1)
	v_pk_mul_f32 v[2:3], v[0:1], v[10:11] op_sel_hi:[0,1]
	v_pk_mul_f32 v[4:5], v[0:1], v[8:9] op_sel_hi:[0,1]
	v_pk_mul_f32 v[4:5], v[88:89], v[4:5]
	v_pk_mul_f32 v[2:3], v[90:91], v[2:3]
	v_cvt_pk_bf16_f32 v4, v4, v5
	v_cvt_pk_bf16_f32 v5, v2, v3
	s_movk_i32 s2, 0xf0
	v_xor_b32_e32 v2, v188, v187
	v_xad_u32 v0, v113, s2, v112
	v_lshlrev_b32_e32 v2, 4, v2
	ds_write_b64 v0, v[4:5]
	v_lshlrev_b32_e32 v0, 8, v188
	v_and_b32_e32 v7, 0xf0, v2
	v_add3_u32 v0, s24, v0, v7
	ds_read_b128 v[2:5], v0
	s_waitcnt vmcnt(0)
	v_lshlrev_b32_e32 v10, 16, v28
	v_and_b32_e32 v11, 0xffff0000, v28
	v_or_b32_e32 v0, 4, v188
	v_or_b32_e32 v24, 28, v188
	s_waitcnt lgkmcnt(0)
	v_lshlrev_b32_e32 v8, 16, v2
	v_and_b32_e32 v9, 0xffff0000, v2
	v_pk_mul_f32 v[8:9], v[8:9], v[10:11]
	v_lshlrev_b32_e32 v10, 16, v29
	v_cvt_pk_bf16_f32 v2, v8, v9
	v_lshlrev_b32_e32 v8, 16, v3
	v_and_b32_e32 v9, 0xffff0000, v3
	v_and_b32_e32 v11, 0xffff0000, v29
	v_pk_mul_f32 v[8:9], v[8:9], v[10:11]
	v_lshlrev_b32_e32 v10, 16, v30
	v_cvt_pk_bf16_f32 v3, v8, v9
	v_lshlrev_b32_e32 v8, 16, v4
	v_and_b32_e32 v9, 0xffff0000, v4
	v_and_b32_e32 v11, 0xffff0000, v30
	v_pk_mul_f32 v[8:9], v[8:9], v[10:11]
	v_lshlrev_b32_e32 v10, 16, v31
	v_cvt_pk_bf16_f32 v4, v8, v9
	v_lshlrev_b32_e32 v8, 16, v5
	v_and_b32_e32 v9, 0xffff0000, v5
	v_and_b32_e32 v11, 0xffff0000, v31
	v_pk_mul_f32 v[8:9], v[8:9], v[10:11]
	s_nop 0
	v_cvt_pk_bf16_f32 v5, v8, v9
	v_lshl_add_u64 v[8:9], s[66:67], 0, v[54:55]
	global_store_dwordx4 v[8:9], v[2:5], off sc1
	v_bitop3_b32 v8, v188, v187, 4 bitop3:0x36
	v_lshlrev_b32_e32 v8, 4, v8
	v_or_b32_e32 v2, s8, v0
	v_ashrrev_i32_e32 v3, 31, v2
	v_lshlrev_b64 v[12:13], 11, v[2:3]
	v_or_b32_e32 v12, v12, v6
	v_lshl_add_u64 v[2:3], s[64:65], 0, v[12:13]
	global_load_dwordx4 v[2:5], v[2:3], off nt
	v_lshlrev_b32_e32 v0, 8, v0
	v_and_b32_e32 v8, 0xf0, v8
	v_add3_u32 v0, s24, v0, v8
	ds_read_b128 v[8:11], v0
	v_or_b32_e32 v0, 8, v188
	s_waitcnt lgkmcnt(0)
	v_lshlrev_b32_e32 v14, 16, v8
	v_and_b32_e32 v15, 0xffff0000, v8
	v_lshlrev_b32_e32 v8, 16, v9
	v_and_b32_e32 v9, 0xffff0000, v9
	s_waitcnt vmcnt(0)
	v_lshlrev_b32_e32 v16, 16, v2
	v_and_b32_e32 v17, 0xffff0000, v2
	v_pk_mul_f32 v[14:15], v[14:15], v[16:17]
	s_nop 0
	v_cvt_pk_bf16_f32 v2, v14, v15
	v_lshlrev_b32_e32 v14, 16, v3
	v_and_b32_e32 v15, 0xffff0000, v3
	v_pk_mul_f32 v[8:9], v[8:9], v[14:15]
	v_lshlrev_b32_e32 v14, 16, v4
	v_cvt_pk_bf16_f32 v3, v8, v9
	v_lshlrev_b32_e32 v8, 16, v10
	v_and_b32_e32 v9, 0xffff0000, v10
	v_and_b32_e32 v15, 0xffff0000, v4
	v_pk_mul_f32 v[8:9], v[8:9], v[14:15]
	v_lshlrev_b32_e32 v10, 16, v5
	v_cvt_pk_bf16_f32 v4, v8, v9
	v_lshlrev_b32_e32 v8, 16, v11
	v_and_b32_e32 v9, 0xffff0000, v11
	v_and_b32_e32 v11, 0xffff0000, v5
	v_pk_mul_f32 v[8:9], v[8:9], v[10:11]
	s_nop 0
	v_cvt_pk_bf16_f32 v5, v8, v9
	v_lshl_add_u64 v[8:9], s[66:67], 0, v[12:13]
	global_store_dwordx4 v[8:9], v[2:5], off sc1
	v_bitop3_b32 v8, v188, v187, 8 bitop3:0x36
	v_lshlrev_b32_e32 v8, 4, v8
	v_or_b32_e32 v2, s8, v0
	v_ashrrev_i32_e32 v3, 31, v2
	v_lshlrev_b64 v[12:13], 11, v[2:3]
	v_or_b32_e32 v12, v12, v6
	v_lshl_add_u64 v[2:3], s[64:65], 0, v[12:13]
	global_load_dwordx4 v[2:5], v[2:3], off nt
	v_lshlrev_b32_e32 v0, 8, v0
	v_and_b32_e32 v8, 0xf0, v8
	v_add3_u32 v0, s24, v0, v8
	ds_read_b128 v[8:11], v0
	v_or_b32_e32 v0, 12, v188
	s_waitcnt lgkmcnt(0)
	v_lshlrev_b32_e32 v14, 16, v8
	v_and_b32_e32 v15, 0xffff0000, v8
	v_lshlrev_b32_e32 v8, 16, v9
	v_and_b32_e32 v9, 0xffff0000, v9
	s_waitcnt vmcnt(0)
	v_lshlrev_b32_e32 v16, 16, v2
	v_and_b32_e32 v17, 0xffff0000, v2
	v_pk_mul_f32 v[14:15], v[14:15], v[16:17]
	s_nop 0
	v_cvt_pk_bf16_f32 v2, v14, v15
	v_lshlrev_b32_e32 v14, 16, v3
	v_and_b32_e32 v15, 0xffff0000, v3
	v_pk_mul_f32 v[8:9], v[8:9], v[14:15]
	v_lshlrev_b32_e32 v14, 16, v4
	v_cvt_pk_bf16_f32 v3, v8, v9
	v_lshlrev_b32_e32 v8, 16, v10
	v_and_b32_e32 v9, 0xffff0000, v10
	v_and_b32_e32 v15, 0xffff0000, v4
	v_pk_mul_f32 v[8:9], v[8:9], v[14:15]
	v_lshlrev_b32_e32 v10, 16, v5
	v_cvt_pk_bf16_f32 v4, v8, v9
	v_lshlrev_b32_e32 v8, 16, v11
	v_and_b32_e32 v9, 0xffff0000, v11
	v_and_b32_e32 v11, 0xffff0000, v5
	v_pk_mul_f32 v[8:9], v[8:9], v[10:11]
	s_nop 0
	v_cvt_pk_bf16_f32 v5, v8, v9
	v_lshl_add_u64 v[8:9], s[66:67], 0, v[12:13]
	global_store_dwordx4 v[8:9], v[2:5], off sc1
	v_bitop3_b32 v8, v188, v187, 12 bitop3:0x36
	v_lshlrev_b32_e32 v8, 4, v8
	v_or_b32_e32 v2, s8, v0
	v_ashrrev_i32_e32 v3, 31, v2
	v_lshlrev_b64 v[12:13], 11, v[2:3]
	v_or_b32_e32 v12, v12, v6
	v_lshl_add_u64 v[2:3], s[64:65], 0, v[12:13]
	global_load_dwordx4 v[2:5], v[2:3], off nt
	v_lshlrev_b32_e32 v0, 8, v0
	v_and_b32_e32 v8, 0xf0, v8
	v_add3_u32 v0, s24, v0, v8
	ds_read_b128 v[8:11], v0
	v_or_b32_e32 v0, 16, v188
	s_waitcnt lgkmcnt(0)
	v_lshlrev_b32_e32 v14, 16, v8
	v_and_b32_e32 v15, 0xffff0000, v8
	v_lshlrev_b32_e32 v8, 16, v9
	v_and_b32_e32 v9, 0xffff0000, v9
	s_waitcnt vmcnt(0)
	v_lshlrev_b32_e32 v16, 16, v2
	v_and_b32_e32 v17, 0xffff0000, v2
	v_pk_mul_f32 v[14:15], v[14:15], v[16:17]
	s_nop 0
	v_cvt_pk_bf16_f32 v2, v14, v15
	v_lshlrev_b32_e32 v14, 16, v3
	v_and_b32_e32 v15, 0xffff0000, v3
	v_pk_mul_f32 v[8:9], v[8:9], v[14:15]
	v_lshlrev_b32_e32 v14, 16, v4
	v_cvt_pk_bf16_f32 v3, v8, v9
	v_lshlrev_b32_e32 v8, 16, v10
	v_and_b32_e32 v9, 0xffff0000, v10
	v_and_b32_e32 v15, 0xffff0000, v4
	v_pk_mul_f32 v[8:9], v[8:9], v[14:15]
	v_lshlrev_b32_e32 v10, 16, v5
	v_cvt_pk_bf16_f32 v4, v8, v9
	v_lshlrev_b32_e32 v8, 16, v11
	v_and_b32_e32 v9, 0xffff0000, v11
	v_and_b32_e32 v11, 0xffff0000, v5
	v_pk_mul_f32 v[8:9], v[8:9], v[10:11]
	s_nop 0
	v_cvt_pk_bf16_f32 v5, v8, v9
	v_lshl_add_u64 v[8:9], s[66:67], 0, v[12:13]
	global_store_dwordx4 v[8:9], v[2:5], off sc1
	s_nop 1
	v_or_b32_e32 v2, s8, v0
	v_ashrrev_i32_e32 v3, 31, v2
	v_lshlrev_b64 v[12:13], 11, v[2:3]
	v_or_b32_e32 v12, v12, v6
	v_lshl_add_u64 v[2:3], s[64:65], 0, v[12:13]
	global_load_dwordx4 v[2:5], v[2:3], off nt
	v_lshlrev_b32_e32 v0, 8, v0
	v_add3_u32 v0, s24, v0, v7
	ds_read_b128 v[8:11], v0
	v_or_b32_e32 v0, 20, v188
	v_bitop3_b32 v7, v188, v187, 20 bitop3:0x36
	v_lshlrev_b32_e32 v7, 4, v7
	v_and_b32_e32 v7, 0xf0, v7
	s_waitcnt lgkmcnt(0)
	v_lshlrev_b32_e32 v14, 16, v8
	v_and_b32_e32 v15, 0xffff0000, v8
	v_lshlrev_b32_e32 v8, 16, v9
	v_and_b32_e32 v9, 0xffff0000, v9
	s_waitcnt vmcnt(0)
	v_lshlrev_b32_e32 v16, 16, v2
	v_and_b32_e32 v17, 0xffff0000, v2
	v_pk_mul_f32 v[14:15], v[14:15], v[16:17]
	s_nop 0
	v_cvt_pk_bf16_f32 v2, v14, v15
	v_lshlrev_b32_e32 v14, 16, v3
	v_and_b32_e32 v15, 0xffff0000, v3
	v_pk_mul_f32 v[8:9], v[8:9], v[14:15]
	v_lshlrev_b32_e32 v14, 16, v4
	v_cvt_pk_bf16_f32 v3, v8, v9
	v_lshlrev_b32_e32 v8, 16, v10
	v_and_b32_e32 v9, 0xffff0000, v10
	v_and_b32_e32 v15, 0xffff0000, v4
	v_pk_mul_f32 v[8:9], v[8:9], v[14:15]
	v_lshlrev_b32_e32 v10, 16, v5
	v_cvt_pk_bf16_f32 v4, v8, v9
	v_lshlrev_b32_e32 v8, 16, v11
	v_and_b32_e32 v9, 0xffff0000, v11
	v_and_b32_e32 v11, 0xffff0000, v5
	v_pk_mul_f32 v[8:9], v[8:9], v[10:11]
	s_nop 0
	v_cvt_pk_bf16_f32 v5, v8, v9
	v_lshl_add_u64 v[8:9], s[66:67], 0, v[12:13]
	global_store_dwordx4 v[8:9], v[2:5], off sc1
	s_nop 1
	v_or_b32_e32 v2, s8, v0
	v_ashrrev_i32_e32 v3, 31, v2
	v_lshlrev_b64 v[12:13], 11, v[2:3]
	v_or_b32_e32 v12, v12, v6
	v_lshl_add_u64 v[2:3], s[64:65], 0, v[12:13]
	global_load_dwordx4 v[2:5], v[2:3], off nt
	v_lshlrev_b32_e32 v0, 8, v0
	v_add3_u32 v0, s24, v0, v7
	ds_read_b128 v[8:11], v0
	v_or_b32_e32 v0, 24, v188
	v_bitop3_b32 v7, v188, v187, 24 bitop3:0x36
	v_lshlrev_b32_e32 v7, 4, v7
	v_and_b32_e32 v7, 0xf0, v7
	s_waitcnt lgkmcnt(0)
	v_lshlrev_b32_e32 v14, 16, v8
	v_and_b32_e32 v15, 0xffff0000, v8
	v_lshlrev_b32_e32 v8, 16, v9
	v_and_b32_e32 v9, 0xffff0000, v9
	s_waitcnt vmcnt(0)
	v_lshlrev_b32_e32 v16, 16, v2
	v_and_b32_e32 v17, 0xffff0000, v2
	v_pk_mul_f32 v[14:15], v[14:15], v[16:17]
	s_nop 0
	v_cvt_pk_bf16_f32 v2, v14, v15
	v_lshlrev_b32_e32 v14, 16, v3
	v_and_b32_e32 v15, 0xffff0000, v3
	v_pk_mul_f32 v[8:9], v[8:9], v[14:15]
	v_lshlrev_b32_e32 v14, 16, v4
	v_cvt_pk_bf16_f32 v3, v8, v9
	v_lshlrev_b32_e32 v8, 16, v10
	v_and_b32_e32 v9, 0xffff0000, v10
	v_and_b32_e32 v15, 0xffff0000, v4
	v_pk_mul_f32 v[8:9], v[8:9], v[14:15]
	v_lshlrev_b32_e32 v10, 16, v5
	v_cvt_pk_bf16_f32 v4, v8, v9
	v_lshlrev_b32_e32 v8, 16, v11
	v_and_b32_e32 v9, 0xffff0000, v11
	v_and_b32_e32 v11, 0xffff0000, v5
	v_pk_mul_f32 v[8:9], v[8:9], v[10:11]
	v_or_b32_e32 v14, s8, v24
	v_cvt_pk_bf16_f32 v5, v8, v9
	v_lshl_add_u64 v[8:9], s[66:67], 0, v[12:13]
	global_store_dwordx4 v[8:9], v[2:5], off sc1
	v_ashrrev_i32_e32 v15, 31, v14
	v_lshlrev_b64 v[14:15], 11, v[14:15]
	v_or_b32_e32 v2, s8, v0
	v_ashrrev_i32_e32 v3, 31, v2
	v_lshlrev_b64 v[12:13], 11, v[2:3]
	v_or_b32_e32 v12, v12, v6
	v_lshl_add_u64 v[2:3], s[64:65], 0, v[12:13]
	global_load_dwordx4 v[2:5], v[2:3], off nt
	v_lshlrev_b32_e32 v0, 8, v0
	v_add3_u32 v0, s24, v0, v7
	ds_read_b128 v[8:11], v0
	v_or_b32_e32 v14, v14, v6
	v_lshl_add_u64 v[6:7], s[66:67], 0, v[12:13]
	v_lshl_add_u64 v[12:13], s[64:65], 0, v[14:15]
	v_bitop3_b32 v0, v188, v187, 28 bitop3:0x36
	s_waitcnt lgkmcnt(0)
	v_lshlrev_b32_e32 v16, 16, v8
	v_and_b32_e32 v17, 0xffff0000, v8
	v_lshlrev_b32_e32 v8, 16, v9
	v_and_b32_e32 v9, 0xffff0000, v9
	v_lshlrev_b32_e32 v18, 16, v10
	v_and_b32_e32 v19, 0xffff0000, v10
	v_lshlrev_b32_e32 v10, 16, v11
	v_and_b32_e32 v11, 0xffff0000, v11
	v_lshlrev_b32_e32 v0, 4, v0
	v_and_b32_e32 v0, 0xf0, v0
	s_waitcnt vmcnt(0)
	v_lshlrev_b32_e32 v20, 16, v2
	v_and_b32_e32 v21, 0xffff0000, v2
	v_lshlrev_b32_e32 v2, 16, v3
	v_and_b32_e32 v3, 0xffff0000, v3
	v_lshlrev_b32_e32 v22, 16, v4
	v_and_b32_e32 v23, 0xffff0000, v4
	v_lshlrev_b32_e32 v4, 16, v5
	v_and_b32_e32 v5, 0xffff0000, v5
	v_pk_mul_f32 v[16:17], v[16:17], v[20:21]
	v_pk_mul_f32 v[8:9], v[8:9], v[2:3]
	v_pk_mul_f32 v[18:19], v[18:19], v[22:23]
	v_pk_mul_f32 v[10:11], v[10:11], v[4:5]
	v_cvt_pk_bf16_f32 v2, v16, v17
	v_cvt_pk_bf16_f32 v3, v8, v9
	v_cvt_pk_bf16_f32 v4, v18, v19
	v_cvt_pk_bf16_f32 v5, v10, v11
	global_store_dwordx4 v[6:7], v[2:5], off sc1
	global_load_dwordx4 v[2:5], v[12:13], off nt
	v_lshlrev_b32_e32 v6, 8, v24
	v_add3_u32 v0, s24, v6, v0
	ds_read_b128 v[6:9], v0
	s_waitcnt lgkmcnt(0)
	v_lshlrev_b32_e32 v10, 16, v6
	v_and_b32_e32 v11, 0xffff0000, v6
	v_lshlrev_b32_e32 v6, 16, v7
	v_and_b32_e32 v7, 0xffff0000, v7
	v_lshlrev_b32_e32 v12, 16, v8
	v_and_b32_e32 v13, 0xffff0000, v8
	v_lshlrev_b32_e32 v8, 16, v9
	v_and_b32_e32 v9, 0xffff0000, v9
	s_waitcnt vmcnt(0)
	v_lshlrev_b32_e32 v16, 16, v2
	v_and_b32_e32 v17, 0xffff0000, v2
	v_lshlrev_b32_e32 v2, 16, v3
	v_and_b32_e32 v3, 0xffff0000, v3
	v_lshlrev_b32_e32 v18, 16, v4
	v_and_b32_e32 v19, 0xffff0000, v4
	v_lshlrev_b32_e32 v4, 16, v5
	v_and_b32_e32 v5, 0xffff0000, v5
	v_pk_mul_f32 v[10:11], v[10:11], v[16:17]
	v_pk_mul_f32 v[6:7], v[6:7], v[2:3]
	v_pk_mul_f32 v[12:13], v[12:13], v[18:19]
	v_pk_mul_f32 v[8:9], v[8:9], v[4:5]
	v_cvt_pk_bf16_f32 v2, v10, v11
	v_cvt_pk_bf16_f32 v3, v6, v7
	v_cvt_pk_bf16_f32 v4, v12, v13
	v_cvt_pk_bf16_f32 v5, v8, v9
	v_lshl_add_u64 v[6:7], s[66:67], 0, v[14:15]
	global_store_dwordx4 v[6:7], v[2:5], off sc1
	s_branch .LBB0_472

.LBB0_490:
	v_div_scale_f32 v0, s[0:1], v160, v160, 1.0
	v_rcp_f32_e32 v2, v0
	v_readlane_b32 s0, v254, 4
	v_lshlrev_b32_e32 v7, 4, v230
	s_waitcnt vmcnt(0) lgkmcnt(0)
	s_barrier
	v_fma_f32 v3, -v0, v2, 1.0
	v_fmac_f32_e32 v2, v3, v2
	v_div_scale_f32 v3, vcc, 1.0, v160, 1.0
	v_mul_f32_e32 v4, v3, v2
	v_fma_f32 v5, -v0, v4, v3
	v_fmac_f32_e32 v4, v5, v2
	v_fma_f32 v0, -v0, v4, v3
	v_div_fmas_f32 v0, v0, v2, v4
	v_div_fixup_f32 v0, v0, v160, 1.0
	v_add3_u32 v6, s0, v235, v234
	v_pk_mul_f32 v[2:3], v[80:81], v[0:1] op_sel_hi:[1,0]
	v_pk_mul_f32 v[4:5], v[82:83], v[0:1] op_sel_hi:[1,0]
	v_cvt_pk_bf16_f32 v2, v2, v3
	v_cvt_pk_bf16_f32 v3, v4, v5
	v_add_u32_e32 v4, v6, v7
	ds_write_b64 v4, v[2:3] offset:32768
	v_pk_mul_f32 v[2:3], v[84:85], v[0:1] op_sel_hi:[1,0]
	v_pk_mul_f32 v[4:5], v[86:87], v[0:1] op_sel_hi:[1,0]
	v_cvt_pk_bf16_f32 v2, v2, v3
	v_cvt_pk_bf16_f32 v3, v4, v5
	v_xad_u32 v4, v7, 16, v6
	ds_write_b64 v4, v[2:3] offset:32768
	v_pk_mul_f32 v[2:3], v[88:89], v[0:1] op_sel_hi:[1,0]
	v_pk_mul_f32 v[4:5], v[90:91], v[0:1] op_sel_hi:[1,0]
	v_cvt_pk_bf16_f32 v2, v2, v3
	v_cvt_pk_bf16_f32 v3, v4, v5
	v_xad_u32 v4, v7, 32, v6
	ds_write_b64 v4, v[2:3] offset:32768
	v_pk_mul_f32 v[2:3], v[92:93], v[0:1] op_sel_hi:[1,0]
	v_pk_mul_f32 v[4:5], v[94:95], v[0:1] op_sel_hi:[1,0]
	v_cvt_pk_bf16_f32 v2, v2, v3
	v_cvt_pk_bf16_f32 v3, v4, v5
	v_xad_u32 v4, v7, 48, v6
	ds_write_b64 v4, v[2:3] offset:32768
	v_pk_mul_f32 v[2:3], v[96:97], v[0:1] op_sel_hi:[1,0]
	v_pk_mul_f32 v[4:5], v[98:99], v[0:1] op_sel_hi:[1,0]
	v_cvt_pk_bf16_f32 v2, v2, v3
	v_cvt_pk_bf16_f32 v3, v4, v5
	v_xad_u32 v4, v7, 64, v6
	ds_write_b64 v4, v[2:3] offset:32768
	v_pk_mul_f32 v[2:3], v[100:101], v[0:1] op_sel_hi:[1,0]
	v_pk_mul_f32 v[4:5], v[102:103], v[0:1] op_sel_hi:[1,0]
	s_movk_i32 s1, 0x50
	v_cvt_pk_bf16_f32 v2, v2, v3
	v_cvt_pk_bf16_f32 v3, v4, v5
	v_xad_u32 v4, v7, s1, v6
	ds_write_b64 v4, v[2:3] offset:32768
	v_pk_mul_f32 v[2:3], v[104:105], v[0:1] op_sel_hi:[1,0]
	v_pk_mul_f32 v[4:5], v[106:107], v[0:1] op_sel_hi:[1,0]
	s_movk_i32 s1, 0x60
	v_cvt_pk_bf16_f32 v2, v2, v3
	v_cvt_pk_bf16_f32 v3, v4, v5
	v_xad_u32 v4, v7, s1, v6
	ds_write_b64 v4, v[2:3] offset:32768
	v_pk_mul_f32 v[2:3], v[108:109], v[0:1] op_sel_hi:[1,0]
	v_pk_mul_f32 v[4:5], v[110:111], v[0:1] op_sel_hi:[1,0]
	s_movk_i32 s1, 0x70
	v_cvt_pk_bf16_f32 v2, v2, v3
	v_cvt_pk_bf16_f32 v3, v4, v5
	v_xad_u32 v0, v7, s1, v6
	ds_write_b64 v0, v[2:3] offset:32768
	v_lshrrev_b32_e32 v0, 3, v231
	v_xor_b32_e32 v2, v0, v230
	v_lshl_add_u32 v6, v2, 4, s0
	v_readlane_b32 s0, v254, 1
	s_or_b32 s0, s30, s0
	v_readlane_b32 s1, v254, 7
	s_add_i32 s1, s0, s1
	v_readlane_b32 s2, v254, 8
	s_add_i32 s2, s0, s2
	v_lshl_or_b32 v7, s19, 7, v7
	v_or_b32_e32 v14, 8, v0
	v_or_b32_e32 v8, s1, v0
	v_ashrrev_i32_e32 v9, 31, v8
	v_lshlrev_b64 v[36:37], 11, v[8:9]
	v_or_b32_e32 v36, v36, v7
	v_lshl_add_u64 v[8:9], s[64:65], 0, v[36:37]
	global_load_dwordx4 v[20:23], v[8:9], off nt
	v_or_b32_e32 v8, s1, v14
	v_ashrrev_i32_e32 v9, 31, v8
	v_lshlrev_b64 v[38:39], 11, v[8:9]
	v_or_b32_e32 v38, v38, v7
	v_lshl_add_u64 v[8:9], s[64:65], 0, v[38:39]
	global_load_dwordx4 v[24:27], v[8:9], off nt
	v_or_b32_e32 v8, s2, v0
	v_ashrrev_i32_e32 v9, 31, v8
	v_lshlrev_b64 v[40:41], 11, v[8:9]
	v_or_b32_e32 v40, v40, v7
	v_lshl_add_u64 v[8:9], s[64:65], 0, v[40:41]
	global_load_dwordx4 v[28:31], v[8:9], off nt
	v_or_b32_e32 v8, s2, v14
	v_ashrrev_i32_e32 v9, 31, v8
	v_lshlrev_b64 v[42:43], 11, v[8:9]
	v_or_b32_e32 v42, v42, v7
	v_lshl_add_u64 v[8:9], s[64:65], 0, v[42:43]
	global_load_dwordx4 v[32:35], v[8:9], off nt
	v_lshl_add_u32 v18, v0, 7, v6
	v_lshl_add_u32 v19, v14, 7, v6
	ds_read_b128 v[44:47], v18 offset:32768
	ds_read_b128 v[48:51], v19 offset:32768
	ds_read_b128 v[52:55], v18 offset:34816
	ds_read_b128 v[56:59], v19 offset:34816
	s_waitcnt vmcnt(3) lgkmcnt(3)
	v_lshlrev_b32_e32 v60, 16, v44
	v_and_b32_e32 v61, 0xffff0000, v44
	v_lshlrev_b32_e32 v62, 16, v20
	v_and_b32_e32 v63, 0xffff0000, v20
	v_lshlrev_b32_e32 v64, 16, v45
	v_and_b32_e32 v65, 0xffff0000, v45
	v_lshlrev_b32_e32 v66, 16, v21
	v_and_b32_e32 v67, 0xffff0000, v21
	v_lshlrev_b32_e32 v68, 16, v46
	v_and_b32_e32 v69, 0xffff0000, v46
	v_lshlrev_b32_e32 v70, 16, v22
	v_and_b32_e32 v71, 0xffff0000, v22
	v_lshlrev_b32_e32 v72, 16, v47
	v_and_b32_e32 v73, 0xffff0000, v47
	v_lshlrev_b32_e32 v74, 16, v23
	v_and_b32_e32 v75, 0xffff0000, v23
	v_pk_mul_f32 v[60:61], v[60:61], v[62:63]
	v_pk_mul_f32 v[64:65], v[64:65], v[66:67]
	v_pk_mul_f32 v[68:69], v[68:69], v[70:71]
	v_pk_mul_f32 v[72:73], v[72:73], v[74:75]
	v_cvt_pk_bf16_f32 v44, v60, v61
	v_cvt_pk_bf16_f32 v45, v64, v65
	v_cvt_pk_bf16_f32 v46, v68, v69
	v_cvt_pk_bf16_f32 v47, v72, v73
	v_lshl_add_u64 v[8:9], s[66:67], 0, v[36:37]
	global_store_dwordx4 v[8:9], v[44:47], off sc1
	s_waitcnt vmcnt(3) lgkmcnt(2)
	v_lshlrev_b32_e32 v60, 16, v48
	v_and_b32_e32 v61, 0xffff0000, v48
	v_lshlrev_b32_e32 v62, 16, v24
	v_and_b32_e32 v63, 0xffff0000, v24
	v_lshlrev_b32_e32 v64, 16, v49
	v_and_b32_e32 v65, 0xffff0000, v49
	v_lshlrev_b32_e32 v66, 16, v25
	v_and_b32_e32 v67, 0xffff0000, v25
	v_lshlrev_b32_e32 v68, 16, v50
	v_and_b32_e32 v69, 0xffff0000, v50
	v_lshlrev_b32_e32 v70, 16, v26
	v_and_b32_e32 v71, 0xffff0000, v26
	v_lshlrev_b32_e32 v72, 16, v51
	v_and_b32_e32 v73, 0xffff0000, v51
	v_lshlrev_b32_e32 v74, 16, v27
	v_and_b32_e32 v75, 0xffff0000, v27
	v_pk_mul_f32 v[60:61], v[60:61], v[62:63]
	v_pk_mul_f32 v[64:65], v[64:65], v[66:67]
	v_pk_mul_f32 v[68:69], v[68:69], v[70:71]
	v_pk_mul_f32 v[72:73], v[72:73], v[74:75]
	v_cvt_pk_bf16_f32 v48, v60, v61
	v_cvt_pk_bf16_f32 v49, v64, v65
	v_cvt_pk_bf16_f32 v50, v68, v69
	v_cvt_pk_bf16_f32 v51, v72, v73
	v_lshl_add_u64 v[8:9], s[66:67], 0, v[38:39]
	global_store_dwordx4 v[8:9], v[48:51], off sc1
	s_waitcnt vmcnt(3) lgkmcnt(1)
	v_lshlrev_b32_e32 v60, 16, v52
	v_and_b32_e32 v61, 0xffff0000, v52
	v_lshlrev_b32_e32 v62, 16, v28
	v_and_b32_e32 v63, 0xffff0000, v28
	v_lshlrev_b32_e32 v64, 16, v53
	v_and_b32_e32 v65, 0xffff0000, v53
	v_lshlrev_b32_e32 v66, 16, v29
	v_and_b32_e32 v67, 0xffff0000, v29
	v_lshlrev_b32_e32 v68, 16, v54
	v_and_b32_e32 v69, 0xffff0000, v54
	v_lshlrev_b32_e32 v70, 16, v30
	v_and_b32_e32 v71, 0xffff0000, v30
	v_lshlrev_b32_e32 v72, 16, v55
	v_and_b32_e32 v73, 0xffff0000, v55
	v_lshlrev_b32_e32 v74, 16, v31
	v_and_b32_e32 v75, 0xffff0000, v31
	v_pk_mul_f32 v[60:61], v[60:61], v[62:63]
	v_pk_mul_f32 v[64:65], v[64:65], v[66:67]
	v_pk_mul_f32 v[68:69], v[68:69], v[70:71]
	v_pk_mul_f32 v[72:73], v[72:73], v[74:75]
	v_cvt_pk_bf16_f32 v52, v60, v61
	v_cvt_pk_bf16_f32 v53, v64, v65
	v_cvt_pk_bf16_f32 v54, v68, v69
	v_cvt_pk_bf16_f32 v55, v72, v73
	v_lshl_add_u64 v[8:9], s[66:67], 0, v[40:41]
	global_store_dwordx4 v[8:9], v[52:55], off sc1
	s_waitcnt vmcnt(3) lgkmcnt(0)
	v_lshlrev_b32_e32 v60, 16, v56
	v_and_b32_e32 v61, 0xffff0000, v56
	v_lshlrev_b32_e32 v62, 16, v32
	v_and_b32_e32 v63, 0xffff0000, v32
	v_lshlrev_b32_e32 v64, 16, v57
	v_and_b32_e32 v65, 0xffff0000, v57
	v_lshlrev_b32_e32 v66, 16, v33
	v_and_b32_e32 v67, 0xffff0000, v33
	v_lshlrev_b32_e32 v68, 16, v58
	v_and_b32_e32 v69, 0xffff0000, v58
	v_lshlrev_b32_e32 v70, 16, v34
	v_and_b32_e32 v71, 0xffff0000, v34
	v_lshlrev_b32_e32 v72, 16, v59
	v_and_b32_e32 v73, 0xffff0000, v59
	v_lshlrev_b32_e32 v74, 16, v35
	v_and_b32_e32 v75, 0xffff0000, v35
	v_pk_mul_f32 v[60:61], v[60:61], v[62:63]
	v_pk_mul_f32 v[64:65], v[64:65], v[66:67]
	v_pk_mul_f32 v[68:69], v[68:69], v[70:71]
	v_pk_mul_f32 v[72:73], v[72:73], v[74:75]
	v_cvt_pk_bf16_f32 v56, v60, v61
	v_cvt_pk_bf16_f32 v57, v64, v65
	v_cvt_pk_bf16_f32 v58, v68, v69
	v_cvt_pk_bf16_f32 v59, v72, v73
	v_lshl_add_u64 v[8:9], s[66:67], 0, v[42:43]
	global_store_dwordx4 v[8:9], v[56:59], off sc1

.LBB0_556:
	s_nop 7
	v_div_scale_f32 v2, s[0:1], v50, v50, 1.0
	v_rcp_f32_e32 v3, v2
	v_readlane_b32 s0, v254, 4
	v_lshlrev_b32_e32 v8, 4, v130
	s_waitcnt vmcnt(0) lgkmcnt(0)
	s_barrier
	v_fma_f32 v4, -v2, v3, 1.0
	v_fmac_f32_e32 v3, v4, v3
	v_div_scale_f32 v4, vcc, 1.0, v50, 1.0
	v_mul_f32_e32 v5, v4, v3
	v_fma_f32 v6, -v2, v5, v4
	v_fmac_f32_e32 v5, v6, v3
	v_fma_f32 v2, -v2, v5, v4
	v_div_fmas_f32 v2, v2, v3, v5
	v_div_fixup_f32 v2, v2, v50, 1.0
	v_add3_u32 v0, s0, v0, v141
	v_pk_mul_f32 v[4:5], v[34:35], v[2:3] op_sel_hi:[1,0]
	v_pk_mul_f32 v[6:7], v[36:37], v[2:3] op_sel_hi:[1,0]
	v_cvt_pk_bf16_f32 v4, v4, v5
	v_cvt_pk_bf16_f32 v5, v6, v7
	v_add_u32_e32 v3, v0, v8
	ds_write_b64 v3, v[4:5] offset:32768
	v_pk_mul_f32 v[4:5], v[38:39], v[2:3] op_sel_hi:[1,0]
	v_pk_mul_f32 v[6:7], v[40:41], v[2:3] op_sel_hi:[1,0]
	v_cvt_pk_bf16_f32 v4, v4, v5
	v_cvt_pk_bf16_f32 v5, v6, v7
	v_xad_u32 v3, v8, 16, v0
	ds_write_b64 v3, v[4:5] offset:32768
	v_pk_mul_f32 v[4:5], v[42:43], v[2:3] op_sel_hi:[1,0]
	v_pk_mul_f32 v[6:7], v[44:45], v[2:3] op_sel_hi:[1,0]
	v_cvt_pk_bf16_f32 v4, v4, v5
	v_cvt_pk_bf16_f32 v5, v6, v7
	v_xad_u32 v3, v8, 32, v0
	ds_write_b64 v3, v[4:5] offset:32768
	v_pk_mul_f32 v[4:5], v[46:47], v[2:3] op_sel_hi:[1,0]
	v_pk_mul_f32 v[6:7], v[48:49], v[2:3] op_sel_hi:[1,0]
	v_cvt_pk_bf16_f32 v4, v4, v5
	v_cvt_pk_bf16_f32 v5, v6, v7
	v_xad_u32 v3, v8, 48, v0
	ds_write_b64 v3, v[4:5] offset:32768
	v_pk_mul_f32 v[4:5], v[18:19], v[2:3] op_sel_hi:[1,0]
	v_pk_mul_f32 v[6:7], v[20:21], v[2:3] op_sel_hi:[1,0]
	v_cvt_pk_bf16_f32 v4, v4, v5
	v_cvt_pk_bf16_f32 v5, v6, v7
	v_xad_u32 v3, v8, 64, v0
	ds_write_b64 v3, v[4:5] offset:32768
	v_pk_mul_f32 v[4:5], v[22:23], v[2:3] op_sel_hi:[1,0]
	v_pk_mul_f32 v[6:7], v[24:25], v[2:3] op_sel_hi:[1,0]
	s_movk_i32 s1, 0x50
	v_cvt_pk_bf16_f32 v4, v4, v5
	v_cvt_pk_bf16_f32 v5, v6, v7
	v_xad_u32 v3, v8, s1, v0
	ds_write_b64 v3, v[4:5] offset:32768
	v_pk_mul_f32 v[4:5], v[26:27], v[2:3] op_sel_hi:[1,0]
	v_pk_mul_f32 v[6:7], v[28:29], v[2:3] op_sel_hi:[1,0]
	s_movk_i32 s1, 0x60
	v_cvt_pk_bf16_f32 v4, v4, v5
	v_cvt_pk_bf16_f32 v5, v6, v7
	v_xad_u32 v3, v8, s1, v0
	ds_write_b64 v3, v[4:5] offset:32768
	v_pk_mul_f32 v[4:5], v[30:31], v[2:3] op_sel_hi:[1,0]
	v_pk_mul_f32 v[2:3], v[32:33], v[2:3] op_sel_hi:[1,0]
	s_movk_i32 s1, 0x70
	v_cvt_pk_bf16_f32 v4, v4, v5
	v_cvt_pk_bf16_f32 v5, v2, v3
	v_xad_u32 v0, v8, s1, v0
	ds_write_b64 v0, v[4:5] offset:32768
	v_lshrrev_b32_e32 v0, 3, v140
	v_lshl_or_b32 v13, s6, 1, v8
	v_xor_b32_e32 v2, v0, v130
	v_lshl_add_u32 v12, v2, 4, s0
	v_or_b32_e32 v14, 0, v0
	v_or_b32_e32 v6, s5, v14
	v_ashrrev_i32_e32 v7, 31, v6
	v_lshlrev_b64 v[36:37], 11, v[6:7]
	v_or_b32_e32 v36, v36, v13
	v_lshl_add_u64 v[6:7], s[64:65], 0, v[36:37]
	global_load_dwordx4 v[20:23], v[6:7], off nt
	v_or_b32_e32 v14, 8, v0
	v_or_b32_e32 v6, s5, v14
	v_ashrrev_i32_e32 v7, 31, v6
	v_lshlrev_b64 v[38:39], 11, v[6:7]
	v_or_b32_e32 v38, v38, v13
	v_lshl_add_u64 v[6:7], s[64:65], 0, v[38:39]
	global_load_dwordx4 v[24:27], v[6:7], off nt
	v_or_b32_e32 v14, 16, v0
	v_or_b32_e32 v6, s5, v14
	v_ashrrev_i32_e32 v7, 31, v6
	v_lshlrev_b64 v[40:41], 11, v[6:7]
	v_or_b32_e32 v40, v40, v13
	v_lshl_add_u64 v[6:7], s[64:65], 0, v[40:41]
	global_load_dwordx4 v[28:31], v[6:7], off nt
	v_or_b32_e32 v14, 24, v0
	v_or_b32_e32 v6, s5, v14
	v_ashrrev_i32_e32 v7, 31, v6
	v_lshlrev_b64 v[42:43], 11, v[6:7]
	v_or_b32_e32 v42, v42, v13
	v_lshl_add_u64 v[6:7], s[64:65], 0, v[42:43]
	global_load_dwordx4 v[32:35], v[6:7], off nt
	v_or_b32_e32 v14, 0, v0
	v_lshl_add_u32 v15, v14, 7, v12
	ds_read_b128 v[44:47], v15 offset:32768
	v_or_b32_e32 v14, 8, v0
	v_lshl_add_u32 v15, v14, 7, v12
	ds_read_b128 v[48:51], v15 offset:32768
	v_or_b32_e32 v14, 16, v0
	v_lshl_add_u32 v15, v14, 7, v12
	ds_read_b128 v[52:55], v15 offset:32768
	v_or_b32_e32 v14, 24, v0
	v_lshl_add_u32 v15, v14, 7, v12
	ds_read_b128 v[56:59], v15 offset:32768
	s_waitcnt vmcnt(3) lgkmcnt(3)
	v_lshlrev_b32_e32 v60, 16, v44
	v_and_b32_e32 v61, 0xffff0000, v44
	v_lshlrev_b32_e32 v62, 16, v20
	v_and_b32_e32 v63, 0xffff0000, v20
	v_lshlrev_b32_e32 v64, 16, v45
	v_and_b32_e32 v65, 0xffff0000, v45
	v_lshlrev_b32_e32 v66, 16, v21
	v_and_b32_e32 v67, 0xffff0000, v21
	v_lshlrev_b32_e32 v68, 16, v46
	v_and_b32_e32 v69, 0xffff0000, v46
	v_lshlrev_b32_e32 v70, 16, v22
	v_and_b32_e32 v71, 0xffff0000, v22
	v_lshlrev_b32_e32 v72, 16, v47
	v_and_b32_e32 v73, 0xffff0000, v47
	v_lshlrev_b32_e32 v74, 16, v23
	v_and_b32_e32 v75, 0xffff0000, v23
	v_pk_mul_f32 v[60:61], v[60:61], v[62:63]
	v_pk_mul_f32 v[64:65], v[64:65], v[66:67]
	v_pk_mul_f32 v[68:69], v[68:69], v[70:71]
	v_pk_mul_f32 v[72:73], v[72:73], v[74:75]
	v_cvt_pk_bf16_f32 v44, v60, v61
	v_cvt_pk_bf16_f32 v45, v64, v65
	v_cvt_pk_bf16_f32 v46, v68, v69
	v_cvt_pk_bf16_f32 v47, v72, v73
	v_lshl_add_u64 v[6:7], s[66:67], 0, v[36:37]
	global_store_dwordx4 v[6:7], v[44:47], off sc1
	s_waitcnt vmcnt(3) lgkmcnt(2)
	v_lshlrev_b32_e32 v60, 16, v48
	v_and_b32_e32 v61, 0xffff0000, v48
	v_lshlrev_b32_e32 v62, 16, v24
	v_and_b32_e32 v63, 0xffff0000, v24
	v_lshlrev_b32_e32 v64, 16, v49
	v_and_b32_e32 v65, 0xffff0000, v49
	v_lshlrev_b32_e32 v66, 16, v25
	v_and_b32_e32 v67, 0xffff0000, v25
	v_lshlrev_b32_e32 v68, 16, v50
	v_and_b32_e32 v69, 0xffff0000, v50
	v_lshlrev_b32_e32 v70, 16, v26
	v_and_b32_e32 v71, 0xffff0000, v26
	v_lshlrev_b32_e32 v72, 16, v51
	v_and_b32_e32 v73, 0xffff0000, v51
	v_lshlrev_b32_e32 v74, 16, v27
	v_and_b32_e32 v75, 0xffff0000, v27
	v_pk_mul_f32 v[60:61], v[60:61], v[62:63]
	v_pk_mul_f32 v[64:65], v[64:65], v[66:67]
	v_pk_mul_f32 v[68:69], v[68:69], v[70:71]
	v_pk_mul_f32 v[72:73], v[72:73], v[74:75]
	v_cvt_pk_bf16_f32 v48, v60, v61
	v_cvt_pk_bf16_f32 v49, v64, v65
	v_cvt_pk_bf16_f32 v50, v68, v69
	v_cvt_pk_bf16_f32 v51, v72, v73
	v_lshl_add_u64 v[6:7], s[66:67], 0, v[38:39]
	global_store_dwordx4 v[6:7], v[48:51], off sc1
	s_waitcnt vmcnt(3) lgkmcnt(1)
	v_lshlrev_b32_e32 v60, 16, v52
	v_and_b32_e32 v61, 0xffff0000, v52
	v_lshlrev_b32_e32 v62, 16, v28
	v_and_b32_e32 v63, 0xffff0000, v28
	v_lshlrev_b32_e32 v64, 16, v53
	v_and_b32_e32 v65, 0xffff0000, v53
	v_lshlrev_b32_e32 v66, 16, v29
	v_and_b32_e32 v67, 0xffff0000, v29
	v_lshlrev_b32_e32 v68, 16, v54
	v_and_b32_e32 v69, 0xffff0000, v54
	v_lshlrev_b32_e32 v70, 16, v30
	v_and_b32_e32 v71, 0xffff0000, v30
	v_lshlrev_b32_e32 v72, 16, v55
	v_and_b32_e32 v73, 0xffff0000, v55
	v_lshlrev_b32_e32 v74, 16, v31
	v_and_b32_e32 v75, 0xffff0000, v31
	v_pk_mul_f32 v[60:61], v[60:61], v[62:63]
	v_pk_mul_f32 v[64:65], v[64:65], v[66:67]
	v_pk_mul_f32 v[68:69], v[68:69], v[70:71]
	v_pk_mul_f32 v[72:73], v[72:73], v[74:75]
	v_cvt_pk_bf16_f32 v52, v60, v61
	v_cvt_pk_bf16_f32 v53, v64, v65
	v_cvt_pk_bf16_f32 v54, v68, v69
	v_cvt_pk_bf16_f32 v55, v72, v73
	v_lshl_add_u64 v[6:7], s[66:67], 0, v[40:41]
	global_store_dwordx4 v[6:7], v[52:55], off sc1
	s_waitcnt vmcnt(3) lgkmcnt(0)
	v_lshlrev_b32_e32 v60, 16, v56
	v_and_b32_e32 v61, 0xffff0000, v56
	v_lshlrev_b32_e32 v62, 16, v32
	v_and_b32_e32 v63, 0xffff0000, v32
	v_lshlrev_b32_e32 v64, 16, v57
	v_and_b32_e32 v65, 0xffff0000, v57
	v_lshlrev_b32_e32 v66, 16, v33
	v_and_b32_e32 v67, 0xffff0000, v33
	v_lshlrev_b32_e32 v68, 16, v58
	v_and_b32_e32 v69, 0xffff0000, v58
	v_lshlrev_b32_e32 v70, 16, v34
	v_and_b32_e32 v71, 0xffff0000, v34
	v_lshlrev_b32_e32 v72, 16, v59
	v_and_b32_e32 v73, 0xffff0000, v59
	v_lshlrev_b32_e32 v74, 16, v35
	v_and_b32_e32 v75, 0xffff0000, v35
	v_pk_mul_f32 v[60:61], v[60:61], v[62:63]
	v_pk_mul_f32 v[64:65], v[64:65], v[66:67]
	v_pk_mul_f32 v[68:69], v[68:69], v[70:71]
	v_pk_mul_f32 v[72:73], v[72:73], v[74:75]
	v_cvt_pk_bf16_f32 v56, v60, v61
	v_cvt_pk_bf16_f32 v57, v64, v65
	v_cvt_pk_bf16_f32 v58, v68, v69
	v_cvt_pk_bf16_f32 v59, v72, v73
	v_lshl_add_u64 v[6:7], s[66:67], 0, v[42:43]
	global_store_dwordx4 v[6:7], v[56:59], off sc1
	s_add_i32 s4, s4, s82
	s_cmpk_gt_i32 s4, 0x7f
	s_cbranch_scc1 .LBB0_552

.LBB0_643:
	v_ashrrev_i32_e32 v189, 31, v188
	v_lshlrev_b64 v[218:219], 10, v[188:189]
	v_lshl_add_u64 v[218:219], v[218:219], 0, v[184:185]
	s_and_b64 s[10:11], s[10:11], exec
	s_cselect_b32 s63, s83, s88
	s_cselect_b32 s62, s68, s89
	v_lshlrev_b64 v[222:223], 2, v[218:219]
	v_lshl_add_u64 v[224:225], s[62:63], 0, v[222:223]
	global_load_dwordx4 v[234:237], v[224:225], off
	global_load_dwordx4 v[238:241], v[224:225], off offset:64
	global_load_dwordx4 v[242:245], v[224:225], off offset:512
	global_load_dwordx4 v[246:249], v[224:225], off offset:576
	s_waitcnt vmcnt(3)
	v_pk_add_f32 v[132:133], v[132:133], 1.0 op_sel_hi:[1,0]
	v_pk_add_f32 v[130:131], v[130:131], 1.0 op_sel_hi:[1,0]
	s_cselect_b32 s11, s73, s79
	s_cselect_b32 s10, s33, s78
	v_lshl_add_u64 v[222:223], s[10:11], 0, v[222:223]
	s_and_b64 vcc, exec, s[38:39]
	v_sub_f32_e32 v235, v235, v208
	v_sub_f32_e32 v234, v234, v208
	v_sub_f32_e32 v237, v237, v208
	v_sub_f32_e32 v236, v236, v208
	v_pk_mul_f32 v[236:237], v[194:195], v[236:237] op_sel_hi:[0,1]
	v_pk_mul_f32 v[234:235], v[194:195], v[234:235] op_sel_hi:[0,1]
	v_pk_fma_f32 v[234:235], v[158:159], v[234:235], v[162:163]
	v_pk_fma_f32 v[236:237], v[156:157], v[236:237], v[160:161]
	v_pk_fma_f32 v[126:127], v[126:127], v[130:131], v[234:235]
	v_pk_fma_f32 v[128:129], v[128:129], v[132:133], v[236:237]
	global_store_dwordx4 v[222:223], v[126:129], off sc1
	s_nop 0
	s_nop 0
	v_pk_add_f32 v[126:127], v[136:137], 1.0 op_sel_hi:[1,0]
	v_pk_add_f32 v[128:129], v[134:135], 1.0 op_sel_hi:[1,0]
	s_waitcnt vmcnt(3)
	v_sub_f32_e32 v135, v239, v208
	v_sub_f32_e32 v134, v238, v208
	v_sub_f32_e32 v137, v241, v208
	v_sub_f32_e32 v136, v240, v208
	v_pk_mul_f32 v[136:137], v[194:195], v[136:137] op_sel_hi:[0,1]
	v_pk_mul_f32 v[134:135], v[194:195], v[134:135] op_sel_hi:[0,1]
	v_pk_fma_f32 v[134:135], v[152:153], v[134:135], v[154:155]
	v_pk_fma_f32 v[136:137], v[164:165], v[136:137], v[170:171]
	v_pk_fma_f32 v[122:123], v[122:123], v[128:129], v[134:135]
	v_pk_fma_f32 v[124:125], v[124:125], v[126:127], v[136:137]
	global_store_dwordx4 v[222:223], v[122:125], off offset:64 sc1
	s_nop 0
	s_waitcnt vmcnt(3)
	v_sub_f32_e32 v243, v243, v208
	v_sub_f32_e32 v242, v242, v208
	v_sub_f32_e32 v245, v245, v208
	v_sub_f32_e32 v244, v244, v208
	v_pk_mul_f32 v[244:245], v[194:195], v[244:245] op_sel_hi:[0,1]
	v_pk_mul_f32 v[242:243], v[194:195], v[242:243] op_sel_hi:[0,1]
	v_pk_add_f32 v[122:123], v[140:141], 1.0 op_sel_hi:[1,0]
	v_pk_add_f32 v[124:125], v[138:139], 1.0 op_sel_hi:[1,0]
	v_pk_fma_f32 v[242:243], v[174:175], v[242:243], v[178:179]
	v_pk_fma_f32 v[244:245], v[172:173], v[244:245], v[176:177]
	v_pk_fma_f32 v[118:119], v[118:119], v[124:125], v[242:243]
	v_pk_fma_f32 v[120:121], v[120:121], v[122:123], v[244:245]
	global_store_dwordx4 v[222:223], v[118:121], off offset:512 sc1
	s_nop 0
	s_waitcnt vmcnt(3)
	v_sub_f32_e32 v247, v247, v208
	v_sub_f32_e32 v246, v246, v208
	v_sub_f32_e32 v249, v249, v208
	v_sub_f32_e32 v248, v248, v208
	v_pk_mul_f32 v[248:249], v[194:195], v[248:249] op_sel_hi:[0,1]
	v_pk_mul_f32 v[246:247], v[194:195], v[246:247] op_sel_hi:[0,1]
	v_pk_add_f32 v[118:119], v[144:145], 1.0 op_sel_hi:[1,0]
	v_pk_add_f32 v[120:121], v[142:143], 1.0 op_sel_hi:[1,0]
	v_pk_fma_f32 v[246:247], v[166:167], v[246:247], v[168:169]
	v_pk_fma_f32 v[248:249], v[180:181], v[248:249], v[182:183]
	v_pk_fma_f32 v[114:115], v[114:115], v[120:121], v[246:247]
	v_pk_fma_f32 v[116:117], v[116:117], v[118:119], v[248:249]
	global_store_dwordx4 v[222:223], v[114:117], off offset:576 sc1
	s_cbranch_vccnz .LBB0_645
	s_nop 0
	v_or_b32_e32 v114, 16, v186
	v_ashrrev_i32_e32 v115, 31, v114
	v_lshl_add_u64 v[114:115], v[114:115], 3, s[6:7]
	global_load_dwordx2 v[190:191], v[114:115], off
	s_waitcnt vmcnt(0)
	v_mov_b32_e32 v192, v191
.LBB0_645:
	s_nop 0
	v_or_b32_e32 v114, 16, v188
	v_ashrrev_i32_e32 v115, 31, v114
	v_lshlrev_b64 v[114:115], 10, v[114:115]
	v_lshl_add_u64 v[114:115], v[114:115], 0, v[184:185]
	v_lshlrev_b64 v[134:135], 2, v[114:115]
	v_lshl_add_u64 v[136:137], s[62:63], 0, v[134:135]
	global_load_dwordx4 v[234:237], v[136:137], off
	global_load_dwordx4 v[238:241], v[136:137], off offset:64
	global_load_dwordx4 v[242:245], v[136:137], off offset:512
	global_load_dwordx4 v[246:249], v[136:137], off offset:576
	v_lshl_add_u64 v[134:135], s[10:11], 0, v[134:135]
	s_and_b64 vcc, exec, s[38:39]
	s_waitcnt vmcnt(3)
	v_sub_f32_e32 v235, v235, v190
	v_sub_f32_e32 v234, v234, v190
	v_sub_f32_e32 v237, v237, v190
	v_sub_f32_e32 v236, v236, v190
	v_pk_mul_f32 v[236:237], v[192:193], v[236:237] op_sel_hi:[0,1]
	v_pk_mul_f32 v[234:235], v[192:193], v[234:235] op_sel_hi:[0,1]
	v_pk_fma_f32 v[234:235], v[158:159], v[234:235], v[162:163]
	v_pk_fma_f32 v[236:237], v[156:157], v[236:237], v[160:161]
	v_pk_fma_f32 v[110:111], v[110:111], v[130:131], v[234:235]
	v_pk_fma_f32 v[112:113], v[112:113], v[132:133], v[236:237]
	global_store_dwordx4 v[134:135], v[110:113], off sc1
	s_nop 0
	s_waitcnt vmcnt(3)
	v_sub_f32_e32 v239, v239, v190
	v_sub_f32_e32 v238, v238, v190
	v_sub_f32_e32 v241, v241, v190
	v_sub_f32_e32 v240, v240, v190
	v_pk_mul_f32 v[240:241], v[192:193], v[240:241] op_sel_hi:[0,1]
	v_pk_mul_f32 v[238:239], v[192:193], v[238:239] op_sel_hi:[0,1]
	v_pk_fma_f32 v[238:239], v[152:153], v[238:239], v[154:155]
	v_pk_fma_f32 v[240:241], v[164:165], v[240:241], v[170:171]
	v_pk_fma_f32 v[106:107], v[106:107], v[128:129], v[238:239]
	v_pk_fma_f32 v[108:109], v[108:109], v[126:127], v[240:241]
	global_store_dwordx4 v[134:135], v[106:109], off offset:64 sc1
	s_nop 0
	s_waitcnt vmcnt(3)
	v_sub_f32_e32 v243, v243, v190
	v_sub_f32_e32 v242, v242, v190
	v_sub_f32_e32 v245, v245, v190
	v_sub_f32_e32 v244, v244, v190
	v_pk_mul_f32 v[244:245], v[192:193], v[244:245] op_sel_hi:[0,1]
	v_pk_mul_f32 v[242:243], v[192:193], v[242:243] op_sel_hi:[0,1]
	v_pk_fma_f32 v[242:243], v[174:175], v[242:243], v[178:179]
	v_pk_fma_f32 v[244:245], v[172:173], v[244:245], v[176:177]
	v_pk_fma_f32 v[102:103], v[102:103], v[124:125], v[242:243]
	v_pk_fma_f32 v[104:105], v[104:105], v[122:123], v[244:245]
	global_store_dwordx4 v[134:135], v[102:105], off offset:512 sc1
	s_nop 0
	s_waitcnt vmcnt(3)
	v_sub_f32_e32 v249, v249, v190
	v_sub_f32_e32 v247, v247, v190
	v_sub_f32_e32 v246, v246, v190
	v_sub_f32_e32 v248, v248, v190
	v_pk_mul_f32 v[248:249], v[192:193], v[248:249] op_sel_hi:[0,1]
	v_pk_mul_f32 v[246:247], v[192:193], v[246:247] op_sel_hi:[0,1]
	v_pk_fma_f32 v[246:247], v[166:167], v[246:247], v[168:169]
	v_pk_fma_f32 v[248:249], v[180:181], v[248:249], v[182:183]
	v_pk_fma_f32 v[98:99], v[98:99], v[120:121], v[246:247]
	v_pk_fma_f32 v[100:101], v[100:101], v[118:119], v[248:249]
	global_store_dwordx4 v[134:135], v[98:101], off offset:576 sc1
	v_mov_b32_e32 v102, 1.0
	v_mov_b32_e32 v104, 0
	v_mov_b32_e32 v98, 0
	v_mov_b32_e32 v100, 1.0
	s_cbranch_vccnz .LBB0_647
	v_or_b32_e32 v100, 32, v186
	v_ashrrev_i32_e32 v101, 31, v100
	v_lshl_add_u64 v[100:101], v[100:101], 3, s[6:7]
	global_load_dwordx2 v[104:105], v[100:101], off
	s_waitcnt vmcnt(0)
	v_mov_b32_e32 v100, v105
.LBB0_647:
	v_or_b32_e32 v106, 32, v188
	v_ashrrev_i32_e32 v107, 31, v106
	v_lshlrev_b64 v[106:107], 10, v[106:107]
	v_lshl_add_u64 v[106:107], v[106:107], 0, v[184:185]
	v_lshlrev_b64 v[110:111], 2, v[106:107]
	v_lshl_add_u64 v[112:113], s[62:63], 0, v[110:111]
	global_load_dwordx4 v[234:237], v[112:113], off
	global_load_dwordx4 v[238:241], v[112:113], off offset:64
	global_load_dwordx4 v[242:245], v[112:113], off offset:512
	global_load_dwordx4 v[246:249], v[112:113], off offset:576
	v_lshl_add_u64 v[110:111], s[10:11], 0, v[110:111]
	s_and_b64 vcc, exec, s[38:39]
	s_waitcnt vmcnt(3)
	v_sub_f32_e32 v235, v235, v104
	v_sub_f32_e32 v234, v234, v104
	v_sub_f32_e32 v237, v237, v104
	v_sub_f32_e32 v236, v236, v104
	v_pk_mul_f32 v[236:237], v[100:101], v[236:237] op_sel_hi:[0,1]
	v_pk_mul_f32 v[234:235], v[100:101], v[234:235] op_sel_hi:[0,1]
	v_pk_fma_f32 v[234:235], v[158:159], v[234:235], v[162:163]
	v_pk_fma_f32 v[236:237], v[156:157], v[236:237], v[160:161]
	v_pk_fma_f32 v[94:95], v[94:95], v[130:131], v[234:235]
	v_pk_fma_f32 v[96:97], v[96:97], v[132:133], v[236:237]
	global_store_dwordx4 v[110:111], v[94:97], off sc1
	s_nop 0
	s_waitcnt vmcnt(3)
	v_sub_f32_e32 v239, v239, v104
	v_sub_f32_e32 v238, v238, v104
	v_sub_f32_e32 v241, v241, v104
	v_sub_f32_e32 v240, v240, v104
	v_pk_mul_f32 v[240:241], v[100:101], v[240:241] op_sel_hi:[0,1]
	v_pk_mul_f32 v[238:239], v[100:101], v[238:239] op_sel_hi:[0,1]
	v_pk_fma_f32 v[238:239], v[152:153], v[238:239], v[154:155]
	v_pk_fma_f32 v[240:241], v[164:165], v[240:241], v[170:171]
	v_pk_fma_f32 v[90:91], v[90:91], v[128:129], v[238:239]
	v_pk_fma_f32 v[92:93], v[92:93], v[126:127], v[240:241]
	global_store_dwordx4 v[110:111], v[90:93], off offset:64 sc1
	s_nop 0
	s_waitcnt vmcnt(3)
	v_sub_f32_e32 v243, v243, v104
	v_sub_f32_e32 v242, v242, v104
	v_sub_f32_e32 v245, v245, v104
	v_sub_f32_e32 v244, v244, v104
	v_pk_mul_f32 v[244:245], v[100:101], v[244:245] op_sel_hi:[0,1]
	v_pk_mul_f32 v[242:243], v[100:101], v[242:243] op_sel_hi:[0,1]
	v_pk_fma_f32 v[242:243], v[174:175], v[242:243], v[178:179]
	v_pk_fma_f32 v[244:245], v[172:173], v[244:245], v[176:177]
	v_pk_fma_f32 v[86:87], v[86:87], v[124:125], v[242:243]
	v_pk_fma_f32 v[88:89], v[88:89], v[122:123], v[244:245]
	global_store_dwordx4 v[110:111], v[86:89], off offset:512 sc1
	s_nop 0
	s_waitcnt vmcnt(3)
	v_sub_f32_e32 v247, v247, v104
	v_sub_f32_e32 v246, v246, v104
	v_sub_f32_e32 v249, v249, v104
	v_sub_f32_e32 v248, v248, v104
	v_pk_mul_f32 v[248:249], v[100:101], v[248:249] op_sel_hi:[0,1]
	v_pk_mul_f32 v[246:247], v[100:101], v[246:247] op_sel_hi:[0,1]
	v_pk_fma_f32 v[246:247], v[166:167], v[246:247], v[168:169]
	v_pk_fma_f32 v[248:249], v[180:181], v[248:249], v[182:183]
	v_pk_fma_f32 v[82:83], v[82:83], v[120:121], v[246:247]
	v_pk_fma_f32 v[84:85], v[84:85], v[118:119], v[248:249]
	global_store_dwordx4 v[110:111], v[82:85], off offset:576 sc1
	s_cbranch_vccnz .LBB0_649
	s_nop 0
	v_or_b32_e32 v82, 48, v186
	v_ashrrev_i32_e32 v83, 31, v82
	v_lshl_add_u64 v[82:83], v[82:83], 3, s[6:7]
	global_load_dwordx2 v[98:99], v[82:83], off
	s_waitcnt vmcnt(0)
	v_mov_b32_e32 v102, v99
.LBB0_649:
	s_nop 0
	v_or_b32_e32 v82, 48, v188
	v_ashrrev_i32_e32 v83, 31, v82
	v_lshlrev_b64 v[82:83], 10, v[82:83]
	v_lshl_add_u64 v[82:83], v[82:83], 0, v[184:185]
	v_lshlrev_b64 v[86:87], 2, v[82:83]
	v_lshl_add_u64 v[88:89], s[62:63], 0, v[86:87]
	global_load_dwordx4 v[234:237], v[88:89], off
	global_load_dwordx4 v[238:241], v[88:89], off offset:64
	global_load_dwordx4 v[242:245], v[88:89], off offset:512
	global_load_dwordx4 v[246:249], v[88:89], off offset:576
	v_lshl_add_u64 v[86:87], s[10:11], 0, v[86:87]
	s_and_b64 vcc, exec, s[38:39]
	s_waitcnt vmcnt(3)
	v_sub_f32_e32 v235, v235, v98
	v_sub_f32_e32 v234, v234, v98
	v_sub_f32_e32 v237, v237, v98
	v_sub_f32_e32 v236, v236, v98
	v_pk_mul_f32 v[236:237], v[102:103], v[236:237] op_sel_hi:[0,1]
	v_pk_mul_f32 v[234:235], v[102:103], v[234:235] op_sel_hi:[0,1]
	v_pk_fma_f32 v[234:235], v[158:159], v[234:235], v[162:163]
	v_pk_fma_f32 v[236:237], v[156:157], v[236:237], v[160:161]
	v_pk_fma_f32 v[78:79], v[78:79], v[130:131], v[234:235]
	v_pk_fma_f32 v[80:81], v[80:81], v[132:133], v[236:237]
	global_store_dwordx4 v[86:87], v[78:81], off sc1
	s_nop 0
	s_waitcnt vmcnt(3)
	v_sub_f32_e32 v239, v239, v98
	v_sub_f32_e32 v238, v238, v98
	v_sub_f32_e32 v241, v241, v98
	v_sub_f32_e32 v240, v240, v98
	v_pk_mul_f32 v[240:241], v[102:103], v[240:241] op_sel_hi:[0,1]
	v_pk_mul_f32 v[238:239], v[102:103], v[238:239] op_sel_hi:[0,1]
	v_pk_fma_f32 v[238:239], v[152:153], v[238:239], v[154:155]
	v_pk_fma_f32 v[240:241], v[164:165], v[240:241], v[170:171]
	v_pk_fma_f32 v[74:75], v[74:75], v[128:129], v[238:239]
	v_pk_fma_f32 v[76:77], v[76:77], v[126:127], v[240:241]
	global_store_dwordx4 v[86:87], v[74:77], off offset:64 sc1
	s_nop 0
	s_waitcnt vmcnt(3)
	v_sub_f32_e32 v243, v243, v98
	v_sub_f32_e32 v242, v242, v98
	v_sub_f32_e32 v245, v245, v98
	v_sub_f32_e32 v244, v244, v98
	v_pk_mul_f32 v[244:245], v[102:103], v[244:245] op_sel_hi:[0,1]
	v_pk_mul_f32 v[242:243], v[102:103], v[242:243] op_sel_hi:[0,1]
	v_pk_fma_f32 v[242:243], v[174:175], v[242:243], v[178:179]
	v_pk_fma_f32 v[244:245], v[172:173], v[244:245], v[176:177]
	v_pk_fma_f32 v[70:71], v[70:71], v[124:125], v[242:243]
	v_pk_fma_f32 v[72:73], v[72:73], v[122:123], v[244:245]
	global_store_dwordx4 v[86:87], v[70:73], off offset:512 sc1
	s_nop 0
	s_waitcnt vmcnt(3)
	v_sub_f32_e32 v249, v249, v98
	v_sub_f32_e32 v247, v247, v98
	v_sub_f32_e32 v246, v246, v98
	v_sub_f32_e32 v248, v248, v98
	v_pk_mul_f32 v[248:249], v[102:103], v[248:249] op_sel_hi:[0,1]
	v_pk_mul_f32 v[246:247], v[102:103], v[246:247] op_sel_hi:[0,1]
	v_pk_fma_f32 v[246:247], v[166:167], v[246:247], v[168:169]
	v_pk_fma_f32 v[248:249], v[180:181], v[248:249], v[182:183]
	v_pk_fma_f32 v[66:67], v[66:67], v[120:121], v[246:247]
	v_pk_fma_f32 v[68:69], v[68:69], v[118:119], v[248:249]
	global_store_dwordx4 v[86:87], v[66:69], off offset:576 sc1
	v_mov_b32_e32 v70, 1.0
	v_mov_b32_e32 v74, 0
	v_mov_b32_e32 v66, 0
	v_mov_b32_e32 v72, 1.0
	s_cbranch_vccnz .LBB0_651
	v_lshl_add_u64 v[68:69], v[186:187], 3, s[6:7]
	global_load_dwordx2 v[74:75], v[68:69], off offset:1024
	s_waitcnt vmcnt(0)
	v_mov_b32_e32 v72, v75
.LBB0_651:
	v_lshlrev_b64 v[68:69], 10, v[188:189]
	v_lshl_add_u64 v[68:69], v[68:69], 0, v[184:185]
	v_lshl_add_u64 v[80:81], v[68:69], 2, v[200:201]
	v_lshl_add_u64 v[82:83], s[62:63], 0, v[80:81]
	global_load_dwordx4 v[234:237], v[82:83], off
	global_load_dwordx4 v[238:241], v[82:83], off offset:64
	global_load_dwordx4 v[242:245], v[82:83], off offset:512
	global_load_dwordx4 v[246:249], v[82:83], off offset:576
	v_lshl_add_u64 v[80:81], s[10:11], 0, v[80:81]
	s_and_b64 vcc, exec, s[38:39]
	s_waitcnt vmcnt(3)
	v_sub_f32_e32 v235, v235, v74
	v_sub_f32_e32 v234, v234, v74
	v_sub_f32_e32 v237, v237, v74
	v_sub_f32_e32 v236, v236, v74
	v_pk_mul_f32 v[236:237], v[72:73], v[236:237] op_sel_hi:[0,1]
	v_pk_mul_f32 v[234:235], v[72:73], v[234:235] op_sel_hi:[0,1]
	v_pk_fma_f32 v[234:235], v[158:159], v[234:235], v[162:163]
	v_pk_fma_f32 v[236:237], v[156:157], v[236:237], v[160:161]
	v_pk_fma_f32 v[62:63], v[62:63], v[130:131], v[234:235]
	v_pk_fma_f32 v[64:65], v[64:65], v[132:133], v[236:237]
	global_store_dwordx4 v[80:81], v[62:65], off sc1
	s_nop 0
	s_waitcnt vmcnt(3)
	v_sub_f32_e32 v239, v239, v74
	v_sub_f32_e32 v238, v238, v74
	v_sub_f32_e32 v241, v241, v74
	v_sub_f32_e32 v240, v240, v74
	v_pk_mul_f32 v[240:241], v[72:73], v[240:241] op_sel_hi:[0,1]
	v_pk_mul_f32 v[238:239], v[72:73], v[238:239] op_sel_hi:[0,1]
	v_pk_fma_f32 v[238:239], v[152:153], v[238:239], v[154:155]
	v_pk_fma_f32 v[240:241], v[164:165], v[240:241], v[170:171]
	v_pk_fma_f32 v[58:59], v[58:59], v[128:129], v[238:239]
	v_pk_fma_f32 v[60:61], v[60:61], v[126:127], v[240:241]
	global_store_dwordx4 v[80:81], v[58:61], off offset:64 sc1
	s_nop 0
	s_waitcnt vmcnt(3)
	v_sub_f32_e32 v243, v243, v74
	v_sub_f32_e32 v242, v242, v74
	v_sub_f32_e32 v245, v245, v74
	v_sub_f32_e32 v244, v244, v74
	v_pk_mul_f32 v[244:245], v[72:73], v[244:245] op_sel_hi:[0,1]
	v_pk_mul_f32 v[242:243], v[72:73], v[242:243] op_sel_hi:[0,1]
	v_pk_fma_f32 v[242:243], v[174:175], v[242:243], v[178:179]
	v_pk_fma_f32 v[244:245], v[172:173], v[244:245], v[176:177]
	v_pk_fma_f32 v[54:55], v[54:55], v[124:125], v[242:243]
	v_pk_fma_f32 v[56:57], v[56:57], v[122:123], v[244:245]
	global_store_dwordx4 v[80:81], v[54:57], off offset:512 sc1
	s_nop 0
	s_waitcnt vmcnt(3)
	v_sub_f32_e32 v247, v247, v74
	v_sub_f32_e32 v246, v246, v74
	v_sub_f32_e32 v249, v249, v74
	v_sub_f32_e32 v248, v248, v74
	v_pk_mul_f32 v[248:249], v[72:73], v[248:249] op_sel_hi:[0,1]
	v_pk_mul_f32 v[246:247], v[72:73], v[246:247] op_sel_hi:[0,1]
	v_pk_fma_f32 v[246:247], v[166:167], v[246:247], v[168:169]
	v_pk_fma_f32 v[248:249], v[180:181], v[248:249], v[182:183]
	v_pk_fma_f32 v[50:51], v[50:51], v[120:121], v[246:247]
	v_pk_fma_f32 v[52:53], v[52:53], v[118:119], v[248:249]
	global_store_dwordx4 v[80:81], v[50:53], off offset:576 sc1
	s_cbranch_vccnz .LBB0_653
	s_nop 0
	v_lshl_add_u64 v[50:51], v[186:187], 3, s[6:7]
	global_load_dwordx2 v[66:67], v[50:51], off offset:1152
	s_waitcnt vmcnt(0)
	v_mov_b32_e32 v70, v67
.LBB0_653:
	v_lshl_add_u64 v[54:55], v[68:69], 2, v[202:203]
	v_lshl_add_u64 v[56:57], s[62:63], 0, v[54:55]
	global_load_dwordx4 v[234:237], v[56:57], off
	global_load_dwordx4 v[238:241], v[56:57], off offset:64
	global_load_dwordx4 v[242:245], v[56:57], off offset:512
	global_load_dwordx4 v[246:249], v[56:57], off offset:576
	v_lshl_add_u64 v[54:55], s[10:11], 0, v[54:55]
	s_and_b64 vcc, exec, s[38:39]
	s_waitcnt vmcnt(3)
	v_sub_f32_e32 v235, v235, v66
	v_sub_f32_e32 v234, v234, v66
	v_sub_f32_e32 v237, v237, v66
	v_sub_f32_e32 v236, v236, v66
	v_pk_mul_f32 v[236:237], v[70:71], v[236:237] op_sel_hi:[0,1]
	v_pk_mul_f32 v[234:235], v[70:71], v[234:235] op_sel_hi:[0,1]
	v_pk_fma_f32 v[234:235], v[158:159], v[234:235], v[162:163]
	v_pk_fma_f32 v[236:237], v[156:157], v[236:237], v[160:161]
	v_pk_fma_f32 v[46:47], v[46:47], v[130:131], v[234:235]
	v_pk_fma_f32 v[48:49], v[48:49], v[132:133], v[236:237]
	global_store_dwordx4 v[54:55], v[46:49], off sc1
	s_nop 0
	s_waitcnt vmcnt(3)
	v_sub_f32_e32 v239, v239, v66
	v_sub_f32_e32 v238, v238, v66
	v_sub_f32_e32 v241, v241, v66
	v_sub_f32_e32 v240, v240, v66
	v_pk_mul_f32 v[240:241], v[70:71], v[240:241] op_sel_hi:[0,1]
	v_pk_mul_f32 v[238:239], v[70:71], v[238:239] op_sel_hi:[0,1]
	v_pk_fma_f32 v[238:239], v[152:153], v[238:239], v[154:155]
	v_pk_fma_f32 v[240:241], v[164:165], v[240:241], v[170:171]
	v_pk_fma_f32 v[42:43], v[42:43], v[128:129], v[238:239]
	v_pk_fma_f32 v[44:45], v[44:45], v[126:127], v[240:241]
	global_store_dwordx4 v[54:55], v[42:45], off offset:64 sc1
	s_nop 0
	s_waitcnt vmcnt(3)
	v_sub_f32_e32 v243, v243, v66
	v_sub_f32_e32 v242, v242, v66
	v_sub_f32_e32 v245, v245, v66
	v_sub_f32_e32 v244, v244, v66
	v_pk_mul_f32 v[244:245], v[70:71], v[244:245] op_sel_hi:[0,1]
	v_pk_mul_f32 v[242:243], v[70:71], v[242:243] op_sel_hi:[0,1]
	v_pk_fma_f32 v[242:243], v[174:175], v[242:243], v[178:179]
	v_pk_fma_f32 v[244:245], v[172:173], v[244:245], v[176:177]
	v_pk_fma_f32 v[38:39], v[38:39], v[124:125], v[242:243]
	v_pk_fma_f32 v[40:41], v[40:41], v[122:123], v[244:245]
	global_store_dwordx4 v[54:55], v[38:41], off offset:512 sc1
	s_nop 0
	s_waitcnt vmcnt(3)
	v_sub_f32_e32 v249, v249, v66
	v_sub_f32_e32 v247, v247, v66
	v_sub_f32_e32 v246, v246, v66
	v_sub_f32_e32 v248, v248, v66
	v_pk_mul_f32 v[248:249], v[70:71], v[248:249] op_sel_hi:[0,1]
	v_pk_mul_f32 v[246:247], v[70:71], v[246:247] op_sel_hi:[0,1]
	v_pk_fma_f32 v[246:247], v[166:167], v[246:247], v[168:169]
	v_pk_fma_f32 v[248:249], v[180:181], v[248:249], v[182:183]
	v_pk_fma_f32 v[34:35], v[34:35], v[120:121], v[246:247]
	v_pk_fma_f32 v[36:37], v[36:37], v[118:119], v[248:249]
	global_store_dwordx4 v[54:55], v[34:37], off offset:576 sc1
	v_mov_b32_e32 v38, 1.0
	v_mov_b32_e32 v42, 0
	v_mov_b32_e32 v34, 0
	v_mov_b32_e32 v40, 1.0
	s_cbranch_vccnz .LBB0_655
	v_lshl_add_u64 v[36:37], v[186:187], 3, s[6:7]
	global_load_dwordx2 v[42:43], v[36:37], off offset:1280
	s_waitcnt vmcnt(0)
	v_mov_b32_e32 v40, v43
.LBB0_655:
	v_lshlrev_b64 v[36:37], 10, v[188:189]
	v_lshl_add_u64 v[36:37], v[36:37], 0, v[184:185]
	v_lshl_add_u64 v[48:49], v[36:37], 2, v[204:205]
	v_lshl_add_u64 v[50:51], s[62:63], 0, v[48:49]
	global_load_dwordx4 v[234:237], v[50:51], off
	global_load_dwordx4 v[238:241], v[50:51], off offset:64
	global_load_dwordx4 v[242:245], v[50:51], off offset:512
	global_load_dwordx4 v[246:249], v[50:51], off offset:576
	v_lshl_add_u64 v[48:49], s[10:11], 0, v[48:49]
	s_and_b64 vcc, exec, s[38:39]
	s_waitcnt vmcnt(3)
	v_sub_f32_e32 v235, v235, v42
	v_sub_f32_e32 v234, v234, v42
	v_sub_f32_e32 v237, v237, v42
	v_sub_f32_e32 v236, v236, v42
	v_pk_mul_f32 v[236:237], v[40:41], v[236:237] op_sel_hi:[0,1]
	v_pk_mul_f32 v[234:235], v[40:41], v[234:235] op_sel_hi:[0,1]
	v_pk_fma_f32 v[234:235], v[158:159], v[234:235], v[162:163]
	v_pk_fma_f32 v[236:237], v[156:157], v[236:237], v[160:161]
	v_pk_fma_f32 v[30:31], v[30:31], v[130:131], v[234:235]
	v_pk_fma_f32 v[32:33], v[32:33], v[132:133], v[236:237]
	global_store_dwordx4 v[48:49], v[30:33], off sc1
	s_nop 0
	s_waitcnt vmcnt(3)
	v_sub_f32_e32 v239, v239, v42
	v_sub_f32_e32 v238, v238, v42
	v_sub_f32_e32 v241, v241, v42
	v_sub_f32_e32 v240, v240, v42
	v_pk_mul_f32 v[240:241], v[40:41], v[240:241] op_sel_hi:[0,1]
	v_pk_mul_f32 v[238:239], v[40:41], v[238:239] op_sel_hi:[0,1]
	v_pk_fma_f32 v[238:239], v[152:153], v[238:239], v[154:155]
	v_pk_fma_f32 v[240:241], v[164:165], v[240:241], v[170:171]
	v_pk_fma_f32 v[26:27], v[26:27], v[128:129], v[238:239]
	v_pk_fma_f32 v[28:29], v[28:29], v[126:127], v[240:241]
	global_store_dwordx4 v[48:49], v[26:29], off offset:64 sc1
	s_nop 0
	s_waitcnt vmcnt(3)
	v_sub_f32_e32 v243, v243, v42
	v_sub_f32_e32 v242, v242, v42
	v_sub_f32_e32 v245, v245, v42
	v_sub_f32_e32 v244, v244, v42
	v_pk_mul_f32 v[244:245], v[40:41], v[244:245] op_sel_hi:[0,1]
	v_pk_mul_f32 v[242:243], v[40:41], v[242:243] op_sel_hi:[0,1]
	v_pk_fma_f32 v[242:243], v[174:175], v[242:243], v[178:179]
	v_pk_fma_f32 v[244:245], v[172:173], v[244:245], v[176:177]
	v_pk_fma_f32 v[22:23], v[22:23], v[124:125], v[242:243]
	v_pk_fma_f32 v[24:25], v[24:25], v[122:123], v[244:245]
	global_store_dwordx4 v[48:49], v[22:25], off offset:512 sc1
	s_nop 0
	s_waitcnt vmcnt(3)
	v_sub_f32_e32 v247, v247, v42
	v_sub_f32_e32 v246, v246, v42
	v_sub_f32_e32 v249, v249, v42
	v_sub_f32_e32 v248, v248, v42
	v_pk_mul_f32 v[248:249], v[40:41], v[248:249] op_sel_hi:[0,1]
	v_pk_mul_f32 v[246:247], v[40:41], v[246:247] op_sel_hi:[0,1]
	v_pk_fma_f32 v[246:247], v[166:167], v[246:247], v[168:169]
	v_pk_fma_f32 v[248:249], v[180:181], v[248:249], v[182:183]
	v_pk_fma_f32 v[18:19], v[18:19], v[120:121], v[246:247]
	v_pk_fma_f32 v[20:21], v[20:21], v[118:119], v[248:249]
	global_store_dwordx4 v[48:49], v[18:21], off offset:576 sc1
	s_cbranch_vccnz .LBB0_657
	s_nop 0
	v_lshl_add_u64 v[18:19], v[186:187], 3, s[6:7]
	global_load_dwordx2 v[34:35], v[18:19], off offset:1408
	s_waitcnt vmcnt(0)
	v_mov_b32_e32 v38, v35
.LBB0_657:
	v_lshl_add_u64 v[22:23], v[36:37], 2, v[206:207]
	v_lshl_add_u64 v[24:25], s[62:63], 0, v[22:23]
	global_load_dwordx4 v[234:237], v[24:25], off
	global_load_dwordx4 v[238:241], v[24:25], off offset:64
	global_load_dwordx4 v[242:245], v[24:25], off offset:512
	global_load_dwordx4 v[246:249], v[24:25], off offset:576
	v_lshl_add_u64 v[22:23], s[10:11], 0, v[22:23]
	s_andn2_b64 vcc, exec, s[36:37]
	s_mov_b64 s[10:11], -1
	s_waitcnt vmcnt(3)
	v_sub_f32_e32 v235, v235, v34
	v_sub_f32_e32 v234, v234, v34
	v_sub_f32_e32 v237, v237, v34
	v_sub_f32_e32 v236, v236, v34
	v_pk_mul_f32 v[236:237], v[38:39], v[236:237] op_sel_hi:[0,1]
	v_pk_mul_f32 v[234:235], v[38:39], v[234:235] op_sel_hi:[0,1]
	v_pk_fma_f32 v[234:235], v[158:159], v[234:235], v[162:163]
	v_pk_fma_f32 v[236:237], v[156:157], v[236:237], v[160:161]
	v_pk_fma_f32 v[14:15], v[14:15], v[130:131], v[234:235]
	v_pk_fma_f32 v[16:17], v[16:17], v[132:133], v[236:237]
	global_store_dwordx4 v[22:23], v[14:17], off sc1
	s_nop 0
	s_waitcnt vmcnt(3)
	v_sub_f32_e32 v239, v239, v34
	v_sub_f32_e32 v238, v238, v34
	v_sub_f32_e32 v241, v241, v34
	v_sub_f32_e32 v240, v240, v34
	v_pk_mul_f32 v[240:241], v[38:39], v[240:241] op_sel_hi:[0,1]
	v_pk_mul_f32 v[238:239], v[38:39], v[238:239] op_sel_hi:[0,1]
	v_pk_fma_f32 v[238:239], v[152:153], v[238:239], v[154:155]
	v_pk_fma_f32 v[240:241], v[164:165], v[240:241], v[170:171]
	v_pk_fma_f32 v[10:11], v[10:11], v[128:129], v[238:239]
	v_pk_fma_f32 v[12:13], v[12:13], v[126:127], v[240:241]
	global_store_dwordx4 v[22:23], v[10:13], off offset:64 sc1
	s_nop 0
	s_waitcnt vmcnt(3)
	v_sub_f32_e32 v243, v243, v34
	v_sub_f32_e32 v242, v242, v34
	v_sub_f32_e32 v245, v245, v34
	v_sub_f32_e32 v244, v244, v34
	v_pk_mul_f32 v[244:245], v[38:39], v[244:245] op_sel_hi:[0,1]
	v_pk_mul_f32 v[242:243], v[38:39], v[242:243] op_sel_hi:[0,1]
	v_pk_fma_f32 v[242:243], v[174:175], v[242:243], v[178:179]
	v_pk_fma_f32 v[244:245], v[172:173], v[244:245], v[176:177]
	v_pk_fma_f32 v[6:7], v[6:7], v[124:125], v[242:243]
	v_pk_fma_f32 v[8:9], v[8:9], v[122:123], v[244:245]
	global_store_dwordx4 v[22:23], v[6:9], off offset:512 sc1
	s_nop 0
	s_waitcnt vmcnt(3)
	v_sub_f32_e32 v247, v247, v34
	v_sub_f32_e32 v246, v246, v34
	v_sub_f32_e32 v249, v249, v34
	v_sub_f32_e32 v248, v248, v34
	v_pk_mul_f32 v[248:249], v[38:39], v[248:249] op_sel_hi:[0,1]
	v_pk_mul_f32 v[246:247], v[38:39], v[246:247] op_sel_hi:[0,1]
	v_pk_fma_f32 v[246:247], v[166:167], v[246:247], v[168:169]
	v_pk_fma_f32 v[248:249], v[180:181], v[248:249], v[182:183]
	v_pk_fma_f32 v[2:3], v[2:3], v[120:121], v[246:247]
	v_pk_fma_f32 v[4:5], v[4:5], v[118:119], v[248:249]
	global_store_dwordx4 v[22:23], v[2:5], off offset:576 sc1
	s_cbranch_vccnz .LBB0_626
	s_andn2_b64 vcc, exec, s[4:5]
	s_cbranch_vccnz .LBB0_625
	s_barrier
	s_branch .LBB0_625
